# G4 in-proj epilogue: each pair of 8-byte row stores merged into one 16-byte store via v_permlane16_swap (half the store instructions, same bytes and addresses)
# speedup vs baseline: 1.0159x; 1.0064x over previous
; #define ROPE_FETCH(ai_, m_) do { const int s_ = (u.pm * BM + (ai_) * HALF + wr * 64 + (m_) * 16 + fr) & 2047, pos_ = (wc & 1) ? (s_ & 63) : (s_ >> 6); \
;             n01 = *(const f32x4*)(rope + pos_ * 16 + 4 * fq); n23 = *(const f32x4*)(rope + pos_ * 16 + 4 * fq + 2); } while (0)
;     __device__ __forceinline__ void operator()(const f32x4 (&acc)[2][2][4][2], const Unit& u, int wr, int wc, int fr, int fq) const {
;         const int pn = u.pn; const bool lat = u.pm < (T_LAT / BM);
;         const bool do_rope = lat && pn >= 2 && (pn <= 6 || pn == 9);
;         float one_ = 1.f, zero_ = 0.f; asm volatile("" : "+v"(one_), "+v"(zero_));
;         f32x4 n01 = (f32x4){one_, zero_, one_, zero_}, n23 = n01;
;     ...
;         if (do_rope) ROPE_FETCH(0, 0);
.LBB0_197:
	v_mbcnt_lo_u32_b32 v222, -1, 0
	v_mbcnt_hi_u32_b32 v222, -1, v222
	v_and_b32_e32 v222, 16, v222
	v_lshrrev_b32_e32 v222, 1, v222
	v_mul_u32_u24_e32 v222, 3, v222
	v_mov_b32_e32 v223, 0
	s_cmp_lt_i32 s3, 64
	s_cselect_b64 s[44:45], -1, 0
	s_cmp_gt_i32 s15, 1
	s_cselect_b64 s[18:19], -1, 0
	s_cmp_gt_i32 s15, 6
	s_cselect_b64 s[12:13], -1, 0
	s_cmp_lt_i32 s15, 7
	s_cselect_b64 s[22:23], -1, 0
	s_cmp_eq_u32 s15, 9
	s_cselect_b64 s[20:21], -1, 0
	s_or_b64 s[22:23], s[22:23], s[20:21]
	s_and_b64 s[18:19], s[18:19], s[22:23]
	s_and_b64 s[18:19], s[44:45], s[18:19]
	v_mov_b32_e32 v139, 0
	v_mov_b32_e32 v138, 1.0
	s_mov_b64 s[22:23], -1
	s_and_b64 vcc, exec, s[18:19]
	s_cbranch_vccnz .LBB0_199
	v_mov_b32_e32 v140, v138
	v_mov_b32_e32 v141, v139
	s_mov_b64 s[22:23], 0

;     __device__ __forceinline__ void operator()(const f32x4 (&acc)[2][2][4][2], const Unit& u, int wr, int wc, int fr, int fq) const {
;     ...
;                 const int r = u.pm * BM + ai * HALF + wr * 64 + m * 16 + fr;
;                 int b, s, keyidx;
;                 if (lat) { b = r >> 11; s = r & 2047; keyidx = CTXL + s; } else { const int rc = r - T_LAT; b = rc >> 8; s = 0; keyidx = rc & 255; }
; #pragma unroll
;                 for (int bj = 0; bj < 2; ++bj) {
;                     f32x4 v0 = acc[ai][bj][m][0], v1 = acc[ai][bj][m][1];
;                     const bool is_rope = (pn >= 2 && pn <= 6) || (pn == 9 && bj == 0);
;                     if (is_rope && lat) {
;                         const float cs[4] = {c01[0], c01[2], c23[0], c23[2]}, sn[4] = {c01[1], c01[3], c23[1], c23[3]};
; #pragma unroll
;                         for (int i = 0; i < 4; ++i) { const float x0 = v0[i], x1 = v1[i]; v0[i] = x0 * cs[i] - x1 * sn[i]; v1[i] = x1 * cs[i] + x0 * sn[i]; }
;                     }
;                     const int ctb = bj * HALF + wc * 32 + 4 * fq;
;                     if (pn <= 1) {
; #pragma unroll
;                         for (int i = 0; i < 4; ++i) { v0[i] = gelu_tanh_f(v0[i]); v1[i] = gelu_tanh_f(v1[i]); }
;                         bf16_t* p = UV + (size_t)r * 512 + pn * 256 + ctb;
;                         *(u32x2*)p = (u32x2){cvt_pk_bf16(v0[0], v0[1]), cvt_pk_bf16(v0[2], v0[3])}; *(u32x2*)(p + 16) = (u32x2){cvt_pk_bf16(v1[0], v1[1]), cvt_pk_bf16(v1[2], v1[3])};
;                     } else if (pn <= 4) {
;                         v0 = v0 * QSCALE; v1 = v1 * QSCALE;
;                         bf16_t* p = (pn <= 3) ? QB + (size_t)r * 512 + (pn - 2) * 256 + ctb : QC + (size_t)r * 256 + ctb;
;                         *(u32x2*)p = (u32x2){cvt_pk_bf16(v0[0], v0[1]), cvt_pk_bf16(v0[2], v0[3])}; *(u32x2*)(p + 16) = (u32x2){cvt_pk_bf16(v1[0], v1[1]), cvt_pk_bf16(v1[2], v1[3])};
;                     } else if (pn <= 6) {
;                         const int ck = (pn - 5) * 256 + ctb, head = ck >> 7, cw = ck & 127;
;                         bf16_t* p = KB + ((size_t)(b * 4 + head) * NKEY + keyidx) * 128 + cw;
;                         *(u32x2*)p = (u32x2){cvt_pk_bf16(v0[0], v0[1]), cvt_pk_bf16(v0[2], v0[3])}; *(u32x2*)(p + 16) = (u32x2){cvt_pk_bf16(v1[0], v1[1]), cvt_pk_bf16(v1[2], v1[3])};
;                     } else if (pn <= 8) {
.LBB0_205:
	v_readlane_b32 s3, v255, 10
	s_lshl_b32 s16, s15, 8
	s_add_i32 s26, s29, s3
	s_add_i32 s3, s16, 0xfffffb00
	s_lshr_b32 s25, s3, 7
	s_add_i32 s3, s26, 0xffffc000
	s_ashr_i32 s3, s3, 8
	s_ashr_i32 s14, s26, 11
	s_and_b64 s[20:21], s[44:45], exec
	s_cselect_b32 s3, s14, s3
	s_lshl_b32 s14, s3, 1
	v_readlane_b32 s20, v255, 13
	s_or_b32 s60, s14, s20
	s_lshl_b32 s14, s3, 2
	v_bitop3_b32 v0, s26, v194, v151 bitop3:0xc8
	s_add_i32 s3, s14, s25
	v_add_u32_e32 v0, 0x100, v0
	v_bitop3_b32 v168, s26, v195, v151 bitop3:0xc8
	s_cmp_gt_i32 s15, 1
	v_cndmask_b32_e64 v0, v168, v0, s[44:45]
	s_cselect_b64 s[48:49], -1, 0
	s_cmp_gt_u32 s15, 4
	v_mad_i64_i32 v[168:169], s[20:21], s60, v196, v[0:1]
	s_cselect_b64 s[96:97], -1, 0
	s_cmp_gt_u32 s15, 8
	v_or_b32_e32 v170, s26, v151
	s_cselect_b64 s[22:23], -1, 0
	s_add_i32 s20, s16, 0xfffff900
	v_ashrrev_i32_e32 v171, 31, v170
	s_cmp_eq_u32 s15, 4
	v_lshlrev_b64 v[178:179], 7, v[168:169]
	v_lshlrev_b64 v[174:175], 10, v[170:171]
	v_lshlrev_b64 v[176:177], 9, v[170:171]
	v_writelane_b32 v255, s20, 17
	s_cselect_b64 s[42:43], -1, 0
	s_mov_b64 s[50:51], -1
	s_and_b64 vcc, exec, s[48:49]
	s_cbranch_vccz .LBB0_219
	s_mov_b64 s[20:21], -1
	s_and_b64 vcc, exec, s[96:97]
	s_cbranch_vccz .LBB0_216
	s_and_b64 vcc, exec, s[12:13]
	s_cbranch_vccz .LBB0_213
	s_and_b64 vcc, exec, s[22:23]
	s_cbranch_vccz .LBB0_210
	v_lshl_add_u64 v[180:181], v[154:155], 0, v[178:179]
	v_cvt_pk_bf16_f32 v168, v134, v135
	v_cvt_pk_bf16_f32 v169, v136, v137
	v_mov_b64_e32 v[216:217], v[168:169]
	v_cvt_pk_bf16_f32 v182, v130, v131
	v_cvt_pk_bf16_f32 v183, v132, v133
	s_mov_b64 s[20:21], 0
.LBB0_210:
	s_andn2_b64 vcc, exec, s[20:21]
	s_cbranch_vccnz .LBB0_212
	v_readlane_b32 s15, v255, 17
	s_ashr_i32 s15, s15, 7
	s_add_i32 s15, s14, s15
	v_mad_i64_i32 v[168:169], s[20:21], s15, v196, v[0:1]
	v_lshlrev_b64 v[168:169], 8, v[168:169]
	v_lshl_add_u64 v[180:181], v[156:157], 0, v[168:169]
	v_cvt_pk_bf16_f32 v168, v134, v135
	v_cvt_pk_bf16_f32 v169, v136, v137
	v_mov_b64_e32 v[216:217], v[168:169]
	v_cvt_pk_bf16_f32 v182, v130, v131
	v_cvt_pk_bf16_f32 v183, v132, v133

; __device__ __forceinline__ unsigned cvt_pk_bf16(float lo, float hi) { unsigned r; asm volatile("v_cvt_pk_bf16_f32 %0, %1, %2" : "=v"(r) : "v"(lo), "v"(hi)); return r; }
;     __device__ __forceinline__ void operator()(const f32x4 (&acc)[2][2][4][2], const Unit& u, int wr, int wc, int fr, int fq) const {
;     ...
;                     } else if (pn <= 6) {
;                         const int ck = (pn - 5) * 256 + ctb, head = ck >> 7, cw = ck & 127;
;                         bf16_t* p = KB + ((size_t)(b * 4 + head) * NKEY + keyidx) * 128 + cw;
;                         *(u32x2*)p = (u32x2){cvt_pk_bf16(v0[0], v0[1]), cvt_pk_bf16(v0[2], v0[3])}; *(u32x2*)(p + 16) = (u32x2){cvt_pk_bf16(v1[0], v1[1]), cvt_pk_bf16(v1[2], v1[3])};
.LBB0_213:
	s_andn2_b64 vcc, exec, s[20:21]
	s_cbranch_vccnz .LBB0_215
	v_mad_i64_i32 v[168:169], s[20:21], s3, v196, v[0:1]
	v_lshlrev_b64 v[168:169], 8, v[168:169]
	v_lshl_add_u64 v[180:181], v[160:161], 0, v[168:169]
	v_cvt_pk_bf16_f32 v168, v134, v135
	v_cvt_pk_bf16_f32 v169, v136, v137
	v_mov_b64_e32 v[216:217], v[168:169]
	v_cvt_pk_bf16_f32 v182, v130, v131
	v_cvt_pk_bf16_f32 v183, v132, v133

; __device__ __forceinline__ unsigned cvt_pk_bf16(float lo, float hi) { unsigned r; asm volatile("v_cvt_pk_bf16_f32 %0, %1, %2" : "=v"(r) : "v"(lo), "v"(hi)); return r; }
;     __device__ __forceinline__ void operator()(const f32x4 (&acc)[2][2][4][2], const Unit& u, int wr, int wc, int fr, int fq) const {
;     ...
;                     } else if (pn <= 4) {
;                         v0 = v0 * QSCALE; v1 = v1 * QSCALE;
;                         bf16_t* p = (pn <= 3) ? QB + (size_t)r * 512 + (pn - 2) * 256 + ctb : QC + (size_t)r * 256 + ctb;
;                         *(u32x2*)p = (u32x2){cvt_pk_bf16(v0[0], v0[1]), cvt_pk_bf16(v0[2], v0[3])}; *(u32x2*)(p + 16) = (u32x2){cvt_pk_bf16(v1[0], v1[1]), cvt_pk_bf16(v1[2], v1[3])};
.LBB0_216:
	s_andn2_b64 vcc, exec, s[20:21]
	s_cbranch_vccnz .LBB0_218
	s_mov_b32 s20, 0x3e38aa3b
	v_pk_mul_f32 v[168:169], v[136:137], s[20:21] op_sel_hi:[1,0]
	v_pk_mul_f32 v[172:173], v[134:135], s[20:21] op_sel_hi:[1,0]
	v_pk_mul_f32 v[202:203], v[132:133], s[20:21] op_sel_hi:[1,0]
	v_pk_mul_f32 v[182:183], v[130:131], s[20:21] op_sel_hi:[1,0]
	v_lshl_add_u64 v[212:213], s[8:9], 0, v[174:175]
	s_movk_i32 s20, 0xfc00
	v_lshl_add_u64 v[212:213], s[16:17], 1, v[212:213]
	s_mov_b32 s21, -1
	v_lshl_add_u64 v[180:181], s[0:1], 0, v[176:177]
	v_lshl_add_u64 v[212:213], v[212:213], 0, s[20:21]
	v_cndmask_b32_e64 v181, v213, v181, s[42:43]
	v_cndmask_b32_e64 v180, v212, v180, s[42:43]
	v_lshlrev_b32_e32 v212, 1, v150
	v_mov_b32_e32 v213, v1
	v_lshl_add_u64 v[180:181], v[180:181], 0, v[212:213]
	v_cvt_pk_bf16_f32 v172, v172, v173
	v_cvt_pk_bf16_f32 v173, v168, v169
	v_mov_b64_e32 v[216:217], v[172:173]
	v_cvt_pk_bf16_f32 v182, v182, v183
	v_cvt_pk_bf16_f32 v183, v202, v203

;     __device__ __forceinline__ void operator()(const f32x4 (&acc)[2][2][4][2], const Unit& u, int wr, int wc, int fr, int fq) const {
;     ...
;                     f32x4 v0 = acc[ai][bj][m][0], v1 = acc[ai][bj][m][1];
;                     const bool is_rope = (pn >= 2 && pn <= 6) || (pn == 9 && bj == 0);
;                     if (is_rope && lat) {
;                         const float cs[4] = {c01[0], c01[2], c23[0], c23[2]}, sn[4] = {c01[1], c01[3], c23[1], c23[3]};
; #pragma unroll
;                         for (int i = 0; i < 4; ++i) { const float x0 = v0[i], x1 = v1[i]; v0[i] = x0 * cs[i] - x1 * sn[i]; v1[i] = x1 * cs[i] + x0 * sn[i]; }
;                     }
;                     const int ctb = bj * HALF + wc * 32 + 4 * fq;
;                     if (pn <= 1) {
; #pragma unroll
;                         for (int i = 0; i < 4; ++i) { v0[i] = gelu_tanh_f(v0[i]); v1[i] = gelu_tanh_f(v1[i]); }
;                         bf16_t* p = UV + (size_t)r * 512 + pn * 256 + ctb;
;                         *(u32x2*)p = (u32x2){cvt_pk_bf16(v0[0], v0[1]), cvt_pk_bf16(v0[2], v0[3])}; *(u32x2*)(p + 16) = (u32x2){cvt_pk_bf16(v1[0], v1[1]), cvt_pk_bf16(v1[2], v1[3])};
;                     } else if (pn <= 4) {
;                         v0 = v0 * QSCALE; v1 = v1 * QSCALE;
;                         bf16_t* p = (pn <= 3) ? QB + (size_t)r * 512 + (pn - 2) * 256 + ctb : QC + (size_t)r * 256 + ctb;
;                         *(u32x2*)p = (u32x2){cvt_pk_bf16(v0[0], v0[1]), cvt_pk_bf16(v0[2], v0[3])}; *(u32x2*)(p + 16) = (u32x2){cvt_pk_bf16(v1[0], v1[1]), cvt_pk_bf16(v1[2], v1[3])};
;                     } else if (pn <= 6) {
;                         const int ck = (pn - 5) * 256 + ctb, head = ck >> 7, cw = ck & 127;
;                         bf16_t* p = KB + ((size_t)(b * 4 + head) * NKEY + keyidx) * 128 + cw;
;                         *(u32x2*)p = (u32x2){cvt_pk_bf16(v0[0], v0[1]), cvt_pk_bf16(v0[2], v0[3])}; *(u32x2*)(p + 16) = (u32x2){cvt_pk_bf16(v1[0], v1[1]), cvt_pk_bf16(v1[2], v1[3])};
;                     } else if (pn <= 8) {
;                         const int cv = (pn - 7) * 256 + ctb, head = cv >> 7, e = cv & 127;
;                         bf16_t* p = VBt + ((size_t)(b * 4 + head) * NKEY + keyidx) * 128 + e;
.LBB0_219:
	s_ashr_i32 s21, s16, 31
	s_mov_b32 s20, s16
	v_lshl_add_u64 v[168:169], s[94:95], 0, v[174:175]
	s_andn2_b64 vcc, exec, s[50:51]
	v_lshl_add_u64 v[172:173], s[20:21], 1, v[168:169]
	v_lshlrev_b32_e32 v168, 1, v150
	s_cbranch_vccnz .LBB0_221
	v_mul_f32_e32 v169, 0x3d372713, v134
	v_mul_f32_e32 v169, v134, v169
	v_fma_f32 v169, v134, v169, v134
	v_mul_f32_e32 v169, 0xbfcc422a, v169
	v_mul_f32_e32 v169, 0x3fb8aa3b, v169
	v_exp_f32_e32 v169, v169
	s_nop 0
	v_add_f32_e32 v169, 1.0, v169
	v_rcp_f32_e32 v169, v169
	s_nop 0
	v_mul_f32_e32 v134, v134, v169
	v_mul_f32_e32 v169, 0x3d372713, v130
	v_mul_f32_e32 v169, v130, v169
	v_fma_f32 v169, v130, v169, v130
	v_mul_f32_e32 v169, 0xbfcc422a, v169
	v_mul_f32_e32 v169, 0x3fb8aa3b, v169
	v_exp_f32_e32 v169, v169
	s_nop 0
	v_add_f32_e32 v169, 1.0, v169
	v_rcp_f32_e32 v169, v169
	s_nop 0
	v_mul_f32_e32 v171, v130, v169
	v_mul_f32_e32 v130, 0x3d372713, v135
	v_mul_f32_e32 v130, v135, v130
	v_fma_f32 v130, v135, v130, v135
	v_mul_f32_e32 v130, 0xbfcc422a, v130
	v_mul_f32_e32 v130, 0x3fb8aa3b, v130
	v_exp_f32_e32 v130, v130
	v_mov_b32_e32 v169, v1
	v_lshl_add_u64 v[180:181], v[172:173], 0, v[168:169]
	v_add_f32_e32 v130, 1.0, v130
	v_rcp_f32_e32 v130, v130
	s_nop 0
	v_mul_f32_e32 v130, v135, v130
	v_mul_f32_e32 v135, 0x3d372713, v131
	v_mul_f32_e32 v135, v131, v135
	v_fma_f32 v135, v131, v135, v131
	v_mul_f32_e32 v135, 0xbfcc422a, v135
	v_mul_f32_e32 v135, 0x3fb8aa3b, v135
	v_exp_f32_e32 v135, v135
	v_cvt_pk_bf16_f32 v130, v134, v130
	s_nop 0
	v_add_f32_e32 v135, 1.0, v135
	v_rcp_f32_e32 v135, v135
	s_nop 0
	v_mul_f32_e32 v135, v131, v135
	v_mul_f32_e32 v131, 0x3d372713, v136
	v_mul_f32_e32 v131, v136, v131
	v_fma_f32 v131, v136, v131, v136
	v_mul_f32_e32 v131, 0xbfcc422a, v131
	v_mul_f32_e32 v131, 0x3fb8aa3b, v131
	v_exp_f32_e32 v131, v131
	s_nop 0
	v_add_f32_e32 v131, 1.0, v131
	v_rcp_f32_e32 v131, v131
	s_nop 0
	v_mul_f32_e32 v131, v136, v131
	v_mul_f32_e32 v136, 0x3d372713, v132
	v_mul_f32_e32 v136, v132, v136
	v_fma_f32 v136, v132, v136, v132
	v_mul_f32_e32 v136, 0xbfcc422a, v136
	v_mul_f32_e32 v136, 0x3fb8aa3b, v136
	v_exp_f32_e32 v136, v136
	s_nop 0
	v_add_f32_e32 v136, 1.0, v136
	v_rcp_f32_e32 v136, v136
	s_nop 0
	v_mul_f32_e32 v132, v132, v136
	v_mul_f32_e32 v136, 0x3d372713, v137
	v_mul_f32_e32 v136, v137, v136
	v_fma_f32 v136, v137, v136, v137
	v_mul_f32_e32 v136, 0xbfcc422a, v136
	v_mul_f32_e32 v136, 0x3fb8aa3b, v136
	v_exp_f32_e32 v136, v136
	s_nop 0
	v_add_f32_e32 v136, 1.0, v136
	v_rcp_f32_e32 v136, v136
	s_nop 0
	v_mul_f32_e32 v136, v137, v136
	v_mul_f32_e32 v137, 0x3d372713, v133
	v_mul_f32_e32 v137, v133, v137
	v_fma_f32 v137, v133, v137, v133
	v_mul_f32_e32 v137, 0xbfcc422a, v137
	v_mul_f32_e32 v137, 0x3fb8aa3b, v137
	v_exp_f32_e32 v137, v137
	v_cvt_pk_bf16_f32 v131, v131, v136
	v_mov_b64_e32 v[216:217], v[130:131]
	v_cvt_pk_bf16_f32 v182, v171, v135
	v_add_f32_e32 v137, 1.0, v137
	v_rcp_f32_e32 v137, v137
	s_nop 0
	v_mul_f32_e32 v133, v133, v137
	v_cvt_pk_bf16_f32 v183, v132, v133
.LBB0_221:
	s_and_b64 s[18:19], s[44:45], s[18:19]
	v_cndmask_b32_e64 v130, 0, 1, s[18:19]
	v_cmp_ne_u32_e64 s[50:51], 1, v130
	s_andn2_b64 vcc, exec, s[18:19]
	v_mov_b64_e32 v[218:219], v[182:183]
	s_nop 1
	v_permlane16_swap_b32_e32 v216, v218
	v_permlane16_swap_b32_e32 v217, v219
	v_lshl_add_u64 v[220:221], v[180:181], 0, v[222:223]
	flat_store_dwordx4 v[220:221], v[216:219]
	s_cbranch_vccnz .LBB0_223
	v_mul_f32_e32 v134, v120, v138
	v_mul_f32_e32 v136, v116, v139
	v_mul_f32_e32 v138, v116, v138
	v_mov_b32_e32 v116, v121
	v_mov_b32_e32 v130, v142
	v_mov_b32_e32 v131, v144
	v_mov_b32_e32 v144, v143
	v_mul_f32_e32 v142, v120, v139
	v_pk_mul_f32 v[180:181], v[116:117], v[140:141]
	v_mov_b32_e32 v120, v117
	v_pk_mul_f32 v[132:133], v[114:115], v[144:145]
	v_mov_b32_e32 v135, v180
	v_mov_b32_e32 v137, v181
	v_pk_mul_f32 v[116:117], v[120:121], v[140:141]
	v_pk_mul_f32 v[114:115], v[114:115], v[130:131]
	v_pk_fma_f32 v[130:131], v[118:119], v[130:131], v[132:133] neg_lo:[0,0,1] neg_hi:[0,0,1]
	v_pk_add_f32 v[132:133], v[134:135], v[136:137] neg_lo:[0,1] neg_hi:[0,1]
	v_mov_b32_e32 v143, v117
	v_mov_b32_e32 v139, v116
	v_pk_fma_f32 v[114:115], v[118:119], v[144:145], v[114:115]
	v_pk_add_f32 v[116:117], v[142:143], v[138:139]
	v_mov_b32_e32 v118, v130
	v_mov_b32_e32 v119, v131
	v_mov_b32_e32 v120, v132
	v_mov_b32_e32 v121, v133
.LBB0_223:
	v_cndmask_b32_e64 v130, 0, 1, s[48:49]
	v_cmp_ne_u32_e64 s[52:53], 1, v130
	v_cndmask_b32_e64 v130, 0, 1, s[96:97]
	s_mov_b64 s[18:19], -1
	s_andn2_b64 vcc, exec, s[48:49]
	v_cmp_ne_u32_e64 s[48:49], 1, v130
	s_cbranch_vccnz .LBB0_237
	s_and_b64 vcc, exec, s[48:49]
	s_cbranch_vccnz .LBB0_234
	s_andn2_b64 vcc, exec, s[12:13]
	s_cbranch_vccnz .LBB0_231
	s_andn2_b64 vcc, exec, s[22:23]
	s_cbranch_vccnz .LBB0_228
	v_lshl_add_u64 v[130:131], v[162:163], 0, v[178:179]
	v_cvt_pk_bf16_f32 v132, v118, v119
	v_cvt_pk_bf16_f32 v133, v120, v121
	s_mov_b64 s[18:19], 0
	v_mov_b64_e32 v[216:217], v[132:133]
	v_cvt_pk_bf16_f32 v132, v114, v115
	v_cvt_pk_bf16_f32 v133, v116, v117
.LBB0_228:
	s_andn2_b64 vcc, exec, s[18:19]
	s_cbranch_vccnz .LBB0_230
	s_add_i32 s15, s16, 0xfffff980
	s_ashr_i32 s15, s15, 7
	s_add_i32 s15, s14, s15
	v_mad_i64_i32 v[130:131], s[18:19], s15, v196, v[0:1]
	v_lshlrev_b64 v[130:131], 8, v[130:131]
	v_lshl_add_u64 v[130:131], v[156:157], 0, v[130:131]
	v_cvt_pk_bf16_f32 v132, v118, v119
	v_cvt_pk_bf16_f32 v133, v120, v121
	v_mov_b64_e32 v[216:217], v[132:133]
	v_cvt_pk_bf16_f32 v132, v114, v115
	v_cvt_pk_bf16_f32 v133, v116, v117

; __device__ __forceinline__ unsigned cvt_pk_bf16(float lo, float hi) { unsigned r; asm volatile("v_cvt_pk_bf16_f32 %0, %1, %2" : "=v"(r) : "v"(lo), "v"(hi)); return r; }
;     __device__ __forceinline__ void operator()(const f32x4 (&acc)[2][2][4][2], const Unit& u, int wr, int wc, int fr, int fq) const {
;     ...
;                     } else if (pn <= 8) {
;                         const int cv = (pn - 7) * 256 + ctb, head = cv >> 7, e = cv & 127;
;                         bf16_t* p = VBt + ((size_t)(b * 4 + head) * NKEY + keyidx) * 128 + e;
;                         *(u32x2*)p = (u32x2){cvt_pk_bf16(v0[0], v0[1]), cvt_pk_bf16(v0[2], v0[3])}; *(u32x2*)(p + 16) = (u32x2){cvt_pk_bf16(v1[0], v1[1]), cvt_pk_bf16(v1[2], v1[3])};
.LBB0_231:
	s_andn2_b64 vcc, exec, s[18:19]
	s_cbranch_vccnz .LBB0_233
	s_or_b32 s15, s3, 1
	v_mad_i64_i32 v[130:131], s[18:19], s15, v196, v[0:1]
	v_lshlrev_b64 v[130:131], 8, v[130:131]
	v_lshl_add_u64 v[130:131], v[160:161], 0, v[130:131]
	v_cvt_pk_bf16_f32 v132, v118, v119
	v_cvt_pk_bf16_f32 v133, v120, v121
	v_mov_b64_e32 v[216:217], v[132:133]
	v_cvt_pk_bf16_f32 v132, v114, v115
	v_cvt_pk_bf16_f32 v133, v116, v117

; __device__ __forceinline__ unsigned cvt_pk_bf16(float lo, float hi) { unsigned r; asm volatile("v_cvt_pk_bf16_f32 %0, %1, %2" : "=v"(r) : "v"(lo), "v"(hi)); return r; }
;     __device__ __forceinline__ void operator()(const f32x4 (&acc)[2][2][4][2], const Unit& u, int wr, int wc, int fr, int fq) const {
;     ...
;                     } else if (pn <= 4) {
;                         v0 = v0 * QSCALE; v1 = v1 * QSCALE;
;                         bf16_t* p = (pn <= 3) ? QB + (size_t)r * 512 + (pn - 2) * 256 + ctb : QC + (size_t)r * 256 + ctb;
;                         *(u32x2*)p = (u32x2){cvt_pk_bf16(v0[0], v0[1]), cvt_pk_bf16(v0[2], v0[3])}; *(u32x2*)(p + 16) = (u32x2){cvt_pk_bf16(v1[0], v1[1]), cvt_pk_bf16(v1[2], v1[3])};
.LBB0_234:
	s_andn2_b64 vcc, exec, s[18:19]
	s_cbranch_vccnz .LBB0_236
	s_mov_b32 s18, 0x3e38aa3b
	v_pk_mul_f32 v[132:133], v[120:121], s[18:19] op_sel_hi:[1,0]
	v_pk_mul_f32 v[134:135], v[118:119], s[18:19] op_sel_hi:[1,0]
	v_pk_mul_f32 v[136:137], v[116:117], s[18:19] op_sel_hi:[1,0]
	v_pk_mul_f32 v[138:139], v[114:115], s[18:19] op_sel_hi:[1,0]
	v_lshl_add_u64 v[140:141], s[8:9], 0, v[174:175]
	s_movk_i32 s18, 0xfc00
	v_lshl_add_u64 v[140:141], s[16:17], 1, v[140:141]
	s_mov_b32 s19, -1
	v_lshl_add_u64 v[130:131], s[0:1], 0, v[176:177]
	v_lshl_add_u64 v[140:141], v[140:141], 0, s[18:19]
	v_cndmask_b32_e64 v131, v141, v131, s[42:43]
	v_cndmask_b32_e64 v130, v140, v130, s[42:43]
	v_mov_b32_e32 v169, v1
	v_lshl_add_u64 v[140:141], v[130:131], 0, v[168:169]
	s_mov_b64 s[18:19], 0x100
	v_lshl_add_u64 v[130:131], v[140:141], 0, s[18:19]
	v_cvt_pk_bf16_f32 v134, v134, v135
	v_cvt_pk_bf16_f32 v135, v132, v133
	v_mov_b64_e32 v[216:217], v[134:135]
	v_cvt_pk_bf16_f32 v132, v138, v139
	v_cvt_pk_bf16_f32 v133, v136, v137

; __device__ __forceinline__ unsigned cvt_pk_bf16(float lo, float hi) { unsigned r; asm volatile("v_cvt_pk_bf16_f32 %0, %1, %2" : "=v"(r) : "v"(lo), "v"(hi)); return r; }
; __device__ __forceinline__ float gelu_tanh_f(float x) { const float y = 1.5957691216057308f * (x + 0.044715f * x * x * x); return x * __builtin_amdgcn_rcpf(1.f + __expf(-y)); }
; #define ROPE_FETCH(ai_, m_) do { const int s_ = (u.pm * BM + (ai_) * HALF + wr * 64 + (m_) * 16 + fr) & 2047, pos_ = (wc & 1) ? (s_ & 63) : (s_ >> 6); \
;             n01 = *(const f32x4*)(rope + pos_ * 16 + 4 * fq); n23 = *(const f32x4*)(rope + pos_ * 16 + 4 * fq + 2); } while (0)
;     __device__ __forceinline__ void operator()(const f32x4 (&acc)[2][2][4][2], const Unit& u, int wr, int wc, int fr, int fq) const {
;     ...
;         if (do_rope) ROPE_FETCH(0, 0);
; #pragma unroll
;         for (int ai = 0; ai < 2; ++ai)
; #pragma unroll
;             for (int m = 0; m < 4; ++m) {
;                 const f32x4 c01 = n01, c23 = n23;
;                 if (do_rope && (ai * 4 + m) < 7) ROPE_FETCH((ai * 4 + m + 1) >> 2, (ai * 4 + m + 1) & 3);
;     ...
;                     if (pn <= 1) {
; #pragma unroll
;                         for (int i = 0; i < 4; ++i) { v0[i] = gelu_tanh_f(v0[i]); v1[i] = gelu_tanh_f(v1[i]); }
;                         bf16_t* p = UV + (size_t)r * 512 + pn * 256 + ctb;
;                         *(u32x2*)p = (u32x2){cvt_pk_bf16(v0[0], v0[1]), cvt_pk_bf16(v0[2], v0[3])}; *(u32x2*)(p + 16) = (u32x2){cvt_pk_bf16(v1[0], v1[1]), cvt_pk_bf16(v1[2], v1[3])};
.LBB0_237:
	s_andn2_b64 vcc, exec, s[18:19]
	s_cbranch_vccnz .LBB0_239
	v_mul_f32_e32 v0, 0x3d372713, v118
	v_mul_f32_e32 v0, v118, v0
	v_fma_f32 v0, v118, v0, v118
	v_mul_f32_e32 v0, 0xbfcc422a, v0
	v_mul_f32_e32 v0, 0x3fb8aa3b, v0
	v_exp_f32_e32 v0, v0
	v_mov_b32_e32 v169, v1
	s_mov_b64 s[18:19], 0x100
	v_add_f32_e32 v0, 1.0, v0
	v_rcp_f32_e32 v0, v0
	s_nop 0
	v_mul_f32_e32 v0, v118, v0
	v_mul_f32_e32 v118, 0x3d372713, v114
	v_mul_f32_e32 v118, v114, v118
	v_fma_f32 v118, v114, v118, v114
	v_mul_f32_e32 v118, 0xbfcc422a, v118
	v_mul_f32_e32 v118, 0x3fb8aa3b, v118
	v_exp_f32_e32 v118, v118
	s_nop 0
	v_add_f32_e32 v118, 1.0, v118
	v_rcp_f32_e32 v118, v118
	s_nop 0
	v_mul_f32_e32 v118, v114, v118
	v_mul_f32_e32 v114, 0x3d372713, v119
	v_mul_f32_e32 v114, v119, v114
	v_fma_f32 v114, v119, v114, v119
	v_mul_f32_e32 v114, 0xbfcc422a, v114
	v_mul_f32_e32 v114, 0x3fb8aa3b, v114
	v_exp_f32_e32 v114, v114
	s_nop 0
	v_add_f32_e32 v114, 1.0, v114
	v_rcp_f32_e32 v114, v114
	s_nop 0
	v_mul_f32_e32 v119, v119, v114
	v_mul_f32_e32 v114, 0x3d372713, v115
	v_mul_f32_e32 v114, v115, v114
	v_fma_f32 v114, v115, v114, v115
	v_mul_f32_e32 v114, 0xbfcc422a, v114
	v_mul_f32_e32 v114, 0x3fb8aa3b, v114
	v_exp_f32_e32 v114, v114
	s_nop 0
	v_add_f32_e32 v114, 1.0, v114
	v_rcp_f32_e32 v114, v114
	s_nop 0
	v_mul_f32_e32 v132, v115, v114
	v_mul_f32_e32 v114, 0x3d372713, v120
	v_mul_f32_e32 v114, v120, v114
	v_fma_f32 v114, v120, v114, v120
	v_mul_f32_e32 v114, 0xbfcc422a, v114
	v_mul_f32_e32 v114, 0x3fb8aa3b, v114
	v_exp_f32_e32 v114, v114
	s_nop 0
	v_add_f32_e32 v114, 1.0, v114
	v_rcp_f32_e32 v114, v114
	s_nop 0
	v_mul_f32_e32 v120, v120, v114
	v_mul_f32_e32 v114, 0x3d372713, v116
	v_mul_f32_e32 v114, v116, v114
	v_fma_f32 v114, v116, v114, v116
	v_mul_f32_e32 v114, 0xbfcc422a, v114
	v_mul_f32_e32 v114, 0x3fb8aa3b, v114
	v_exp_f32_e32 v114, v114
	s_nop 0
	v_add_f32_e32 v114, 1.0, v114
	v_rcp_f32_e32 v114, v114
	s_nop 0
	v_mul_f32_e32 v133, v116, v114
	v_mul_f32_e32 v114, 0x3d372713, v121
	v_mul_f32_e32 v114, v121, v114
	v_fma_f32 v114, v121, v114, v121
	v_mul_f32_e32 v114, 0xbfcc422a, v114
	v_mul_f32_e32 v114, 0x3fb8aa3b, v114
	v_exp_f32_e32 v114, v114
	v_cvt_pk_bf16_f32 v116, v0, v119
	s_nop 0
	v_add_f32_e32 v114, 1.0, v114
	v_rcp_f32_e32 v114, v114
	s_nop 0
	v_mul_f32_e32 v121, v121, v114
	v_mul_f32_e32 v114, 0x3d372713, v117
	v_mul_f32_e32 v114, v117, v114
	v_fma_f32 v114, v117, v114, v117
	v_mul_f32_e32 v114, 0xbfcc422a, v114
	v_mul_f32_e32 v114, 0x3fb8aa3b, v114
	v_exp_f32_e32 v114, v114
	s_nop 0
	v_add_f32_e32 v114, 1.0, v114
	v_rcp_f32_e32 v114, v114
	s_nop 0
	v_mul_f32_e32 v134, v117, v114
	v_lshl_add_u64 v[114:115], v[172:173], 0, v[168:169]
	v_lshl_add_u64 v[130:131], v[114:115], 0, s[18:19]
	v_cvt_pk_bf16_f32 v117, v120, v121
	v_mov_b64_e32 v[216:217], v[116:117]
	v_cvt_pk_bf16_f32 v132, v118, v132
	v_cvt_pk_bf16_f32 v133, v133, v134
.LBB0_239:
	v_mov_b64_e32 v[218:219], v[132:133]
	s_nop 1
	v_permlane16_swap_b32_e32 v216, v218
	v_permlane16_swap_b32_e32 v217, v219
	v_lshl_add_u64 v[220:221], v[130:131], 0, v[222:223]
	flat_store_dwordx4 v[220:221], v[216:219]
	s_waitcnt vmcnt(0) lgkmcnt(0)
	v_mov_b64_e32 v[118:119], v[126:127]
	v_mov_b64_e32 v[114:115], v[122:123]
	s_and_b64 vcc, exec, s[54:55]
	v_mov_b64_e32 v[120:121], v[128:129]
	v_mov_b64_e32 v[116:117], v[124:125]
	s_cbranch_vccnz .LBB0_241
	s_lshr_b32 s15, s29, 6
	s_add_i32 s15, s15, s67
	s_and_b32 s15, s15, 31
	v_mov_b32_e32 v0, s15
	v_cndmask_b32_e64 v0, v209, v0, s[38:39]
	v_lshlrev_b32_e32 v0, 7, v0
	v_lshl_add_u64 v[118:119], v[152:153], 0, v[0:1]
	flat_load_dwordx4 v[114:117], v[118:119]
	s_nop 0
	flat_load_dwordx4 v[118:121], v[118:119] offset:16

;     __device__ __forceinline__ void operator()(const f32x4 (&acc)[2][2][4][2], const Unit& u, int wr, int wc, int fr, int fq) const {
;     ...
;                 const int r = u.pm * BM + ai * HALF + wr * 64 + m * 16 + fr;
;                 int b, s, keyidx;
;                 if (lat) { b = r >> 11; s = r & 2047; keyidx = CTXL + s; } else { const int rc = r - T_LAT; b = rc >> 8; s = 0; keyidx = rc & 255; }
; #pragma unroll
;                 for (int bj = 0; bj < 2; ++bj) {
;                     f32x4 v0 = acc[ai][bj][m][0], v1 = acc[ai][bj][m][1];
;                     const bool is_rope = (pn >= 2 && pn <= 6) || (pn == 9 && bj == 0);
;                     if (is_rope && lat) {
;                         const float cs[4] = {c01[0], c01[2], c23[0], c23[2]}, sn[4] = {c01[1], c01[3], c23[1], c23[3]};
; #pragma unroll
;                         for (int i = 0; i < 4; ++i) { const float x0 = v0[i], x1 = v1[i]; v0[i] = x0 * cs[i] - x1 * sn[i]; v1[i] = x1 * cs[i] + x0 * sn[i]; }
;                     }
;                     const int ctb = bj * HALF + wc * 32 + 4 * fq;
;                     if (pn <= 1) {
; #pragma unroll
;                         for (int i = 0; i < 4; ++i) { v0[i] = gelu_tanh_f(v0[i]); v1[i] = gelu_tanh_f(v1[i]); }
;                         bf16_t* p = UV + (size_t)r * 512 + pn * 256 + ctb;
;                         *(u32x2*)p = (u32x2){cvt_pk_bf16(v0[0], v0[1]), cvt_pk_bf16(v0[2], v0[3])}; *(u32x2*)(p + 16) = (u32x2){cvt_pk_bf16(v1[0], v1[1]), cvt_pk_bf16(v1[2], v1[3])};
;                     } else if (pn <= 4) {
;                         v0 = v0 * QSCALE; v1 = v1 * QSCALE;
;                         bf16_t* p = (pn <= 3) ? QB + (size_t)r * 512 + (pn - 2) * 256 + ctb : QC + (size_t)r * 256 + ctb;
;                         *(u32x2*)p = (u32x2){cvt_pk_bf16(v0[0], v0[1]), cvt_pk_bf16(v0[2], v0[3])}; *(u32x2*)(p + 16) = (u32x2){cvt_pk_bf16(v1[0], v1[1]), cvt_pk_bf16(v1[2], v1[3])};
;                     } else if (pn <= 6) {
;                         const int ck = (pn - 5) * 256 + ctb, head = ck >> 7, cw = ck & 127;
;                         bf16_t* p = KB + ((size_t)(b * 4 + head) * NKEY + keyidx) * 128 + cw;
;                         *(u32x2*)p = (u32x2){cvt_pk_bf16(v0[0], v0[1]), cvt_pk_bf16(v0[2], v0[3])}; *(u32x2*)(p + 16) = (u32x2){cvt_pk_bf16(v1[0], v1[1]), cvt_pk_bf16(v1[2], v1[3])};
;                     } else if (pn <= 8) {
.LBB0_243:
	s_movk_i32 s15, 0x7df
	v_bitop3_b32 v0, v170, s15, 16 bitop3:0xc8
	s_movk_i32 s15, 0xdf
	v_add_u32_e32 v0, 0x100, v0
	v_bitop3_b32 v131, v170, s15, 16 bitop3:0xc8
	s_mul_hi_i32 s19, s60, 0x900
	s_mul_i32 s18, s60, 0x900
	v_or_b32_e32 v130, 16, v170
	v_cndmask_b32_e64 v0, v131, v0, s[44:45]
	v_lshl_add_u64 v[132:133], s[18:19], 0, v[0:1]
	v_ashrrev_i32_e32 v131, 31, v130
	v_lshlrev_b64 v[136:137], 7, v[132:133]
	v_lshlrev_b64 v[132:133], 10, v[130:131]
	v_lshlrev_b64 v[134:135], 9, v[130:131]
	s_and_b64 vcc, exec, s[52:53]
	s_mov_b64 s[96:97], -1
	s_mov_b64 s[60:61], 0x100
	s_cbranch_vccnz .LBB0_273
	s_and_b64 vcc, exec, s[48:49]
	s_cbranch_vccnz .LBB0_254
	s_andn2_b64 vcc, exec, s[12:13]
	s_cbranch_vccnz .LBB0_251
	s_andn2_b64 vcc, exec, s[22:23]
	s_cbranch_vccnz .LBB0_248
	v_lshl_add_u64 v[138:139], v[154:155], 0, v[136:137]
	s_mov_b64 s[96:97], 0
	v_cvt_pk_bf16_f32 v130, v110, v111
	v_cvt_pk_bf16_f32 v131, v112, v113
	v_mov_b64_e32 v[216:217], v[130:131]
	v_cvt_pk_bf16_f32 v140, v106, v107
	v_cvt_pk_bf16_f32 v141, v108, v109
.LBB0_248:
	s_andn2_b64 vcc, exec, s[96:97]
	s_cbranch_vccnz .LBB0_250
	v_readlane_b32 s15, v255, 17
	s_ashr_i32 s15, s15, 7
	s_add_i32 s15, s14, s15
	v_mad_i64_i32 v[130:131], s[60:61], s15, v196, v[0:1]
	v_lshlrev_b64 v[130:131], 8, v[130:131]
	s_mov_b64 s[60:61], 0x100
	v_lshl_add_u64 v[138:139], v[156:157], 0, v[130:131]
	v_cvt_pk_bf16_f32 v130, v110, v111
	v_cvt_pk_bf16_f32 v131, v112, v113
	v_mov_b64_e32 v[216:217], v[130:131]
	v_cvt_pk_bf16_f32 v140, v106, v107
	v_cvt_pk_bf16_f32 v141, v108, v109

; __device__ __forceinline__ unsigned cvt_pk_bf16(float lo, float hi) { unsigned r; asm volatile("v_cvt_pk_bf16_f32 %0, %1, %2" : "=v"(r) : "v"(lo), "v"(hi)); return r; }
;     __device__ __forceinline__ void operator()(const f32x4 (&acc)[2][2][4][2], const Unit& u, int wr, int wc, int fr, int fq) const {
;     ...
;                     } else if (pn <= 8) {
;                         const int cv = (pn - 7) * 256 + ctb, head = cv >> 7, e = cv & 127;
;                         bf16_t* p = VBt + ((size_t)(b * 4 + head) * NKEY + keyidx) * 128 + e;
;                         *(u32x2*)p = (u32x2){cvt_pk_bf16(v0[0], v0[1]), cvt_pk_bf16(v0[2], v0[3])}; *(u32x2*)(p + 16) = (u32x2){cvt_pk_bf16(v1[0], v1[1]), cvt_pk_bf16(v1[2], v1[3])};
.LBB0_251:
	s_andn2_b64 vcc, exec, s[96:97]
	s_cbranch_vccnz .LBB0_253
	v_mad_i64_i32 v[130:131], s[60:61], s3, v196, v[0:1]
	v_lshlrev_b64 v[130:131], 8, v[130:131]
	s_mov_b64 s[60:61], 0x100
	v_lshl_add_u64 v[138:139], v[160:161], 0, v[130:131]
	v_cvt_pk_bf16_f32 v130, v110, v111
	v_cvt_pk_bf16_f32 v131, v112, v113
	v_mov_b64_e32 v[216:217], v[130:131]
	v_cvt_pk_bf16_f32 v140, v106, v107
	v_cvt_pk_bf16_f32 v141, v108, v109

; __device__ __forceinline__ unsigned cvt_pk_bf16(float lo, float hi) { unsigned r; asm volatile("v_cvt_pk_bf16_f32 %0, %1, %2" : "=v"(r) : "v"(lo), "v"(hi)); return r; }
;     __device__ __forceinline__ void operator()(const f32x4 (&acc)[2][2][4][2], const Unit& u, int wr, int wc, int fr, int fq) const {
;     ...
;                     } else if (pn <= 4) {
;                         v0 = v0 * QSCALE; v1 = v1 * QSCALE;
;                         bf16_t* p = (pn <= 3) ? QB + (size_t)r * 512 + (pn - 2) * 256 + ctb : QC + (size_t)r * 256 + ctb;
;                         *(u32x2*)p = (u32x2){cvt_pk_bf16(v0[0], v0[1]), cvt_pk_bf16(v0[2], v0[3])}; *(u32x2*)(p + 16) = (u32x2){cvt_pk_bf16(v1[0], v1[1]), cvt_pk_bf16(v1[2], v1[3])};
.LBB0_254:
	s_andn2_b64 vcc, exec, s[96:97]
	s_cbranch_vccnz .LBB0_256
	v_lshl_add_u64 v[172:173], s[8:9], 0, v[132:133]
	s_movk_i32 s96, 0xfc00
	v_lshl_add_u64 v[172:173], s[16:17], 1, v[172:173]
	s_mov_b32 s97, -1
	v_lshl_add_u64 v[138:139], s[0:1], 0, v[134:135]
	v_lshl_add_u64 v[172:173], v[172:173], 0, s[96:97]
	v_pk_mul_f32 v[140:141], v[110:111], s[74:75] op_sel_hi:[1,0]
	v_cndmask_b32_e64 v139, v173, v139, s[42:43]
	v_cndmask_b32_e64 v138, v172, v138, s[42:43]
	v_mov_b32_e32 v169, v1
	v_pk_mul_f32 v[130:131], v[112:113], s[74:75] op_sel_hi:[1,0]
	v_lshl_add_u64 v[138:139], v[138:139], 0, v[168:169]
	v_cvt_pk_bf16_f32 v140, v140, v141
	v_cvt_pk_bf16_f32 v141, v130, v131
	v_pk_mul_f32 v[142:143], v[108:109], s[74:75] op_sel_hi:[1,0]
	v_pk_mul_f32 v[144:145], v[106:107], s[74:75] op_sel_hi:[1,0]
	v_mov_b64_e32 v[216:217], v[140:141]
	v_cvt_pk_bf16_f32 v140, v144, v145
	v_cvt_pk_bf16_f32 v141, v142, v143

;     __device__ __forceinline__ void operator()(const f32x4 (&acc)[2][2][4][2], const Unit& u, int wr, int wc, int fr, int fq) const {
;     ...
;                 for (int bj = 0; bj < 2; ++bj) {
;                     f32x4 v0 = acc[ai][bj][m][0], v1 = acc[ai][bj][m][1];
;                     const bool is_rope = (pn >= 2 && pn <= 6) || (pn == 9 && bj == 0);
;                     if (is_rope && lat) {
;                         const float cs[4] = {c01[0], c01[2], c23[0], c23[2]}, sn[4] = {c01[1], c01[3], c23[1], c23[3]};
; #pragma unroll
;                         for (int i = 0; i < 4; ++i) { const float x0 = v0[i], x1 = v1[i]; v0[i] = x0 * cs[i] - x1 * sn[i]; v1[i] = x1 * cs[i] + x0 * sn[i]; }
;                     }
;                     const int ctb = bj * HALF + wc * 32 + 4 * fq;
;                     if (pn <= 1) {
; #pragma unroll
;                         for (int i = 0; i < 4; ++i) { v0[i] = gelu_tanh_f(v0[i]); v1[i] = gelu_tanh_f(v1[i]); }
;                         bf16_t* p = UV + (size_t)r * 512 + pn * 256 + ctb;
;                         *(u32x2*)p = (u32x2){cvt_pk_bf16(v0[0], v0[1]), cvt_pk_bf16(v0[2], v0[3])}; *(u32x2*)(p + 16) = (u32x2){cvt_pk_bf16(v1[0], v1[1]), cvt_pk_bf16(v1[2], v1[3])};
;                     } else if (pn <= 4) {
;                         v0 = v0 * QSCALE; v1 = v1 * QSCALE;
;                         bf16_t* p = (pn <= 3) ? QB + (size_t)r * 512 + (pn - 2) * 256 + ctb : QC + (size_t)r * 256 + ctb;
;                         *(u32x2*)p = (u32x2){cvt_pk_bf16(v0[0], v0[1]), cvt_pk_bf16(v0[2], v0[3])}; *(u32x2*)(p + 16) = (u32x2){cvt_pk_bf16(v1[0], v1[1]), cvt_pk_bf16(v1[2], v1[3])};
;                     } else if (pn <= 6) {
;                         const int ck = (pn - 5) * 256 + ctb, head = ck >> 7, cw = ck & 127;
;                         bf16_t* p = KB + ((size_t)(b * 4 + head) * NKEY + keyidx) * 128 + cw;
;                         *(u32x2*)p = (u32x2){cvt_pk_bf16(v0[0], v0[1]), cvt_pk_bf16(v0[2], v0[3])}; *(u32x2*)(p + 16) = (u32x2){cvt_pk_bf16(v1[0], v1[1]), cvt_pk_bf16(v1[2], v1[3])};
;                     } else if (pn <= 8) {
;                         const int cv = (pn - 7) * 256 + ctb, head = cv >> 7, e = cv & 127;
;                         bf16_t* p = VBt + ((size_t)(b * 4 + head) * NKEY + keyidx) * 128 + e;
.LBB0_257:
	s_and_b64 vcc, exec, s[50:51]
	v_mov_b64_e32 v[218:219], v[140:141]
	s_nop 1
	v_permlane16_swap_b32_e32 v216, v218
	v_permlane16_swap_b32_e32 v217, v219
	v_lshl_add_u64 v[220:221], v[138:139], 0, v[222:223]
	flat_store_dwordx4 v[220:221], v[216:219]
	s_cbranch_vccnz .LBB0_259

; __device__ __forceinline__ unsigned cvt_pk_bf16(float lo, float hi) { unsigned r; asm volatile("v_cvt_pk_bf16_f32 %0, %1, %2" : "=v"(r) : "v"(lo), "v"(hi)); return r; }
;     __device__ __forceinline__ void operator()(const f32x4 (&acc)[2][2][4][2], const Unit& u, int wr, int wc, int fr, int fq) const {
;     ...
;                     } else if (pn <= 6) {
;                         const int ck = (pn - 5) * 256 + ctb, head = ck >> 7, cw = ck & 127;
;                         bf16_t* p = KB + ((size_t)(b * 4 + head) * NKEY + keyidx) * 128 + cw;
;                         *(u32x2*)p = (u32x2){cvt_pk_bf16(v0[0], v0[1]), cvt_pk_bf16(v0[2], v0[3])}; *(u32x2*)(p + 16) = (u32x2){cvt_pk_bf16(v1[0], v1[1]), cvt_pk_bf16(v1[2], v1[3])};
;                     } else if (pn <= 8) {
;                         const int cv = (pn - 7) * 256 + ctb, head = cv >> 7, e = cv & 127;
;                         bf16_t* p = VBt + ((size_t)(b * 4 + head) * NKEY + keyidx) * 128 + e;
;                         *(u32x2*)p = (u32x2){cvt_pk_bf16(v0[0], v0[1]), cvt_pk_bf16(v0[2], v0[3])}; *(u32x2*)(p + 16) = (u32x2){cvt_pk_bf16(v1[0], v1[1]), cvt_pk_bf16(v1[2], v1[3])};
;                     } else {
;                         const int kv = wc >> 1, d = (wc & 1) * 32 + 4 * fq;
;                         if (bj == 0) {
;                             bf16_t* p = KC + ((size_t)(b * 2 + kv) * NKEY + keyidx) * 64 + d;
;                             *(u32x2*)p = (u32x2){cvt_pk_bf16(v0[0], v0[1]), cvt_pk_bf16(v0[2], v0[3])}; *(u32x2*)(p + 16) = (u32x2){cvt_pk_bf16(v1[0], v1[1]), cvt_pk_bf16(v1[2], v1[3])};
;                         } else {
;                             bf16_t* p = VCt + ((size_t)(b * 2 + kv) * NKEY + keyidx) * 64 + d;
;                             *(u32x2*)p = (u32x2){cvt_pk_bf16(v0[0], v0[1]), cvt_pk_bf16(v0[2], v0[3])}; *(u32x2*)(p + 16) = (u32x2){cvt_pk_bf16(v1[0], v1[1]), cvt_pk_bf16(v1[2], v1[3])};
;                         }
;                     }
.LBB0_259:
	s_and_b64 vcc, exec, s[52:53]
	s_mov_b64 s[96:97], -1
	s_cbranch_vccnz .LBB0_275
	s_and_b64 vcc, exec, s[48:49]
	s_cbranch_vccnz .LBB0_270
	s_andn2_b64 vcc, exec, s[12:13]
	s_cbranch_vccnz .LBB0_267
	s_andn2_b64 vcc, exec, s[22:23]
	s_cbranch_vccnz .LBB0_264
	v_lshl_add_u64 v[106:107], v[162:163], 0, v[136:137]
	v_cvt_pk_bf16_f32 v108, v102, v103
	v_cvt_pk_bf16_f32 v109, v104, v105
	s_mov_b64 s[96:97], 0
	v_mov_b64_e32 v[216:217], v[108:109]
	v_cvt_pk_bf16_f32 v108, v98, v99
	v_cvt_pk_bf16_f32 v109, v100, v101
.LBB0_264:
	s_andn2_b64 vcc, exec, s[96:97]
	s_cbranch_vccnz .LBB0_266
	s_add_i32 s15, s20, 0xfffff980
	s_ashr_i32 s15, s15, 7
	s_add_i32 s15, s14, s15
	v_mad_i64_i32 v[106:107], s[60:61], s15, v196, v[0:1]
	v_lshlrev_b64 v[106:107], 8, v[106:107]
	s_mov_b64 s[60:61], 0x100
	v_lshl_add_u64 v[106:107], v[156:157], 0, v[106:107]
	v_cvt_pk_bf16_f32 v108, v102, v103
	v_cvt_pk_bf16_f32 v109, v104, v105
	v_mov_b64_e32 v[216:217], v[108:109]
	v_cvt_pk_bf16_f32 v108, v98, v99
	v_cvt_pk_bf16_f32 v109, v100, v101

; __device__ __forceinline__ unsigned cvt_pk_bf16(float lo, float hi) { unsigned r; asm volatile("v_cvt_pk_bf16_f32 %0, %1, %2" : "=v"(r) : "v"(lo), "v"(hi)); return r; }
;     __device__ __forceinline__ void operator()(const f32x4 (&acc)[2][2][4][2], const Unit& u, int wr, int wc, int fr, int fq) const {
;     ...
;                     } else if (pn <= 8) {
;                         const int cv = (pn - 7) * 256 + ctb, head = cv >> 7, e = cv & 127;
;                         bf16_t* p = VBt + ((size_t)(b * 4 + head) * NKEY + keyidx) * 128 + e;
;                         *(u32x2*)p = (u32x2){cvt_pk_bf16(v0[0], v0[1]), cvt_pk_bf16(v0[2], v0[3])}; *(u32x2*)(p + 16) = (u32x2){cvt_pk_bf16(v1[0], v1[1]), cvt_pk_bf16(v1[2], v1[3])};
.LBB0_267:
	s_andn2_b64 vcc, exec, s[96:97]
	s_cbranch_vccnz .LBB0_269
	s_or_b32 s15, s3, 1
	v_mad_i64_i32 v[106:107], s[60:61], s15, v196, v[0:1]
	v_lshlrev_b64 v[106:107], 8, v[106:107]
	s_mov_b64 s[60:61], 0x100
	v_lshl_add_u64 v[106:107], v[160:161], 0, v[106:107]
	v_cvt_pk_bf16_f32 v108, v102, v103
	v_cvt_pk_bf16_f32 v109, v104, v105
	v_mov_b64_e32 v[216:217], v[108:109]
	v_cvt_pk_bf16_f32 v108, v98, v99
	v_cvt_pk_bf16_f32 v109, v100, v101

; __device__ __forceinline__ unsigned cvt_pk_bf16(float lo, float hi) { unsigned r; asm volatile("v_cvt_pk_bf16_f32 %0, %1, %2" : "=v"(r) : "v"(lo), "v"(hi)); return r; }
;     __device__ __forceinline__ void operator()(const f32x4 (&acc)[2][2][4][2], const Unit& u, int wr, int wc, int fr, int fq) const {
;     ...
;                     } else if (pn <= 4) {
;                         v0 = v0 * QSCALE; v1 = v1 * QSCALE;
;                         bf16_t* p = (pn <= 3) ? QB + (size_t)r * 512 + (pn - 2) * 256 + ctb : QC + (size_t)r * 256 + ctb;
;                         *(u32x2*)p = (u32x2){cvt_pk_bf16(v0[0], v0[1]), cvt_pk_bf16(v0[2], v0[3])}; *(u32x2*)(p + 16) = (u32x2){cvt_pk_bf16(v1[0], v1[1]), cvt_pk_bf16(v1[2], v1[3])};
.LBB0_270:
	s_andn2_b64 vcc, exec, s[96:97]
	s_cbranch_vccnz .LBB0_272
	v_lshl_add_u64 v[124:125], s[8:9], 0, v[132:133]
	s_movk_i32 s96, 0xfc00
	v_lshl_add_u64 v[124:125], s[16:17], 1, v[124:125]
	s_mov_b32 s97, -1
	v_lshl_add_u64 v[106:107], s[0:1], 0, v[134:135]
	v_lshl_add_u64 v[124:125], v[124:125], 0, s[96:97]
	v_cndmask_b32_e64 v107, v125, v107, s[42:43]
	v_cndmask_b32_e64 v106, v124, v106, s[42:43]
	v_mov_b32_e32 v169, v1
	v_lshl_add_u64 v[124:125], v[106:107], 0, v[168:169]
	v_pk_mul_f32 v[108:109], v[104:105], s[74:75] op_sel_hi:[1,0]
	v_pk_mul_f32 v[110:111], v[102:103], s[74:75] op_sel_hi:[1,0]
	v_lshl_add_u64 v[106:107], v[124:125], 0, s[60:61]
	v_pk_mul_f32 v[112:113], v[100:101], s[74:75] op_sel_hi:[1,0]
	v_pk_mul_f32 v[122:123], v[98:99], s[74:75] op_sel_hi:[1,0]
	v_cvt_pk_bf16_f32 v110, v110, v111
	v_cvt_pk_bf16_f32 v111, v108, v109
	v_mov_b64_e32 v[216:217], v[110:111]
	v_cvt_pk_bf16_f32 v108, v122, v123
	v_cvt_pk_bf16_f32 v109, v112, v113

; __device__ __forceinline__ unsigned cvt_pk_bf16(float lo, float hi) { unsigned r; asm volatile("v_cvt_pk_bf16_f32 %0, %1, %2" : "=v"(r) : "v"(lo), "v"(hi)); return r; }
; __device__ __forceinline__ float gelu_tanh_f(float x) { const float y = 1.5957691216057308f * (x + 0.044715f * x * x * x); return x * __builtin_amdgcn_rcpf(1.f + __expf(-y)); }
;     __device__ __forceinline__ void operator()(const f32x4 (&acc)[2][2][4][2], const Unit& u, int wr, int wc, int fr, int fq) const {
;     ...
;                     if (pn <= 1) {
; #pragma unroll
;                         for (int i = 0; i < 4; ++i) { v0[i] = gelu_tanh_f(v0[i]); v1[i] = gelu_tanh_f(v1[i]); }
;                         bf16_t* p = UV + (size_t)r * 512 + pn * 256 + ctb;
;                         *(u32x2*)p = (u32x2){cvt_pk_bf16(v0[0], v0[1]), cvt_pk_bf16(v0[2], v0[3])}; *(u32x2*)(p + 16) = (u32x2){cvt_pk_bf16(v1[0], v1[1]), cvt_pk_bf16(v1[2], v1[3])};
.LBB0_274:
	v_mul_f32_e32 v138, 0x3d372713, v110
	v_mul_f32_e32 v138, v110, v138
	v_fma_f32 v138, v110, v138, v110
	v_mul_f32_e32 v138, 0xbfcc422a, v138
	v_mul_f32_e32 v138, 0x3fb8aa3b, v138
	v_exp_f32_e32 v138, v138
	v_mov_b32_e32 v169, v1
	v_add_f32_e32 v138, 1.0, v138
	v_rcp_f32_e32 v138, v138
	s_nop 0
	v_mul_f32_e32 v110, v110, v138
	v_mul_f32_e32 v138, 0x3d372713, v106
	v_mul_f32_e32 v138, v106, v138
	v_fma_f32 v138, v106, v138, v106
	v_mul_f32_e32 v138, 0xbfcc422a, v138
	v_mul_f32_e32 v138, 0x3fb8aa3b, v138
	v_exp_f32_e32 v138, v138
	s_nop 0
	v_add_f32_e32 v138, 1.0, v138
	v_rcp_f32_e32 v138, v138
	s_nop 0
	v_mul_f32_e32 v140, v106, v138
	v_mul_f32_e32 v106, 0x3d372713, v111
	v_mul_f32_e32 v106, v111, v106
	v_fma_f32 v106, v111, v106, v111
	v_mul_f32_e32 v106, 0xbfcc422a, v106
	v_mul_f32_e32 v106, 0x3fb8aa3b, v106
	v_exp_f32_e32 v106, v106
	v_lshl_add_u64 v[138:139], v[130:131], 0, v[168:169]
	v_add_f32_e32 v106, 1.0, v106
	v_rcp_f32_e32 v106, v106
	s_nop 0
	v_mul_f32_e32 v106, v111, v106
	v_mul_f32_e32 v111, 0x3d372713, v107
	v_mul_f32_e32 v111, v107, v111
	v_fma_f32 v111, v107, v111, v107
	v_mul_f32_e32 v111, 0xbfcc422a, v111
	v_mul_f32_e32 v111, 0x3fb8aa3b, v111
	v_exp_f32_e32 v111, v111
	v_cvt_pk_bf16_f32 v106, v110, v106
	s_nop 0
	v_add_f32_e32 v111, 1.0, v111
	v_rcp_f32_e32 v111, v111
	s_nop 0
	v_mul_f32_e32 v111, v107, v111
	v_mul_f32_e32 v107, 0x3d372713, v112
	v_mul_f32_e32 v107, v112, v107
	v_fma_f32 v107, v112, v107, v112
	v_mul_f32_e32 v107, 0xbfcc422a, v107
	v_mul_f32_e32 v107, 0x3fb8aa3b, v107
	v_exp_f32_e32 v107, v107
	s_nop 0
	v_add_f32_e32 v107, 1.0, v107
	v_rcp_f32_e32 v107, v107
	s_nop 0
	v_mul_f32_e32 v107, v112, v107
	v_mul_f32_e32 v112, 0x3d372713, v108
	v_mul_f32_e32 v112, v108, v112
	v_fma_f32 v112, v108, v112, v108
	v_mul_f32_e32 v112, 0xbfcc422a, v112
	v_mul_f32_e32 v112, 0x3fb8aa3b, v112
	v_exp_f32_e32 v112, v112
	s_nop 0
	v_add_f32_e32 v112, 1.0, v112
	v_rcp_f32_e32 v112, v112
	s_nop 0
	v_mul_f32_e32 v108, v108, v112
	v_mul_f32_e32 v112, 0x3d372713, v113
	v_mul_f32_e32 v112, v113, v112
	v_fma_f32 v112, v113, v112, v113
	v_mul_f32_e32 v112, 0xbfcc422a, v112
	v_mul_f32_e32 v112, 0x3fb8aa3b, v112
	v_exp_f32_e32 v112, v112
	s_nop 0
	v_add_f32_e32 v112, 1.0, v112
	v_rcp_f32_e32 v112, v112
	s_nop 0
	v_mul_f32_e32 v112, v113, v112
	v_mul_f32_e32 v113, 0x3d372713, v109
	v_mul_f32_e32 v113, v109, v113
	v_fma_f32 v113, v109, v113, v109
	v_mul_f32_e32 v113, 0xbfcc422a, v113
	v_mul_f32_e32 v113, 0x3fb8aa3b, v113
	v_exp_f32_e32 v113, v113
	v_cvt_pk_bf16_f32 v107, v107, v112
	v_mov_b64_e32 v[216:217], v[106:107]
	v_cvt_pk_bf16_f32 v140, v140, v111
	v_add_f32_e32 v113, 1.0, v113
	v_rcp_f32_e32 v113, v113
	s_nop 0
	v_mul_f32_e32 v109, v109, v113
	v_cvt_pk_bf16_f32 v141, v108, v109
	s_and_b64 vcc, exec, s[50:51]
	v_mov_b64_e32 v[218:219], v[140:141]
	s_nop 1
	v_permlane16_swap_b32_e32 v216, v218
	v_permlane16_swap_b32_e32 v217, v219
	v_lshl_add_u64 v[220:221], v[138:139], 0, v[222:223]
	flat_store_dwordx4 v[220:221], v[216:219]
	s_cbranch_vccnz .LBB0_259
	s_branch .LBB0_258

; __device__ __forceinline__ unsigned cvt_pk_bf16(float lo, float hi) { unsigned r; asm volatile("v_cvt_pk_bf16_f32 %0, %1, %2" : "=v"(r) : "v"(lo), "v"(hi)); return r; }
; __device__ __forceinline__ float gelu_tanh_f(float x) { const float y = 1.5957691216057308f * (x + 0.044715f * x * x * x); return x * __builtin_amdgcn_rcpf(1.f + __expf(-y)); }
; #define ROPE_FETCH(ai_, m_) do { const int s_ = (u.pm * BM + (ai_) * HALF + wr * 64 + (m_) * 16 + fr) & 2047, pos_ = (wc & 1) ? (s_ & 63) : (s_ >> 6); \
;             n01 = *(const f32x4*)(rope + pos_ * 16 + 4 * fq); n23 = *(const f32x4*)(rope + pos_ * 16 + 4 * fq + 2); } while (0)
;     __device__ __forceinline__ void operator()(const f32x4 (&acc)[2][2][4][2], const Unit& u, int wr, int wc, int fr, int fq) const {
;     ...
;         if (do_rope) ROPE_FETCH(0, 0);
; #pragma unroll
;         for (int ai = 0; ai < 2; ++ai)
; #pragma unroll
;             for (int m = 0; m < 4; ++m) {
;                 const f32x4 c01 = n01, c23 = n23;
;                 if (do_rope && (ai * 4 + m) < 7) ROPE_FETCH((ai * 4 + m + 1) >> 2, (ai * 4 + m + 1) & 3);
;     ...
;                     if (pn <= 1) {
; #pragma unroll
;                         for (int i = 0; i < 4; ++i) { v0[i] = gelu_tanh_f(v0[i]); v1[i] = gelu_tanh_f(v1[i]); }
;                         bf16_t* p = UV + (size_t)r * 512 + pn * 256 + ctb;
;                         *(u32x2*)p = (u32x2){cvt_pk_bf16(v0[0], v0[1]), cvt_pk_bf16(v0[2], v0[3])}; *(u32x2*)(p + 16) = (u32x2){cvt_pk_bf16(v1[0], v1[1]), cvt_pk_bf16(v1[2], v1[3])};
.LBB0_276:
	v_mul_f32_e32 v0, 0x3d372713, v102
	v_mul_f32_e32 v0, v102, v0
	v_fma_f32 v0, v102, v0, v102
	v_mul_f32_e32 v0, 0xbfcc422a, v0
	v_mul_f32_e32 v0, 0x3fb8aa3b, v0
	v_exp_f32_e32 v0, v0
	v_mov_b32_e32 v169, v1
	v_add_f32_e32 v0, 1.0, v0
	v_rcp_f32_e32 v0, v0
	s_nop 0
	v_mul_f32_e32 v0, v102, v0
	v_mul_f32_e32 v102, 0x3d372713, v98
	v_mul_f32_e32 v102, v98, v102
	v_fma_f32 v102, v98, v102, v98
	v_mul_f32_e32 v102, 0xbfcc422a, v102
	v_mul_f32_e32 v102, 0x3fb8aa3b, v102
	v_exp_f32_e32 v102, v102
	s_nop 0
	v_add_f32_e32 v102, 1.0, v102
	v_rcp_f32_e32 v102, v102
	s_nop 0
	v_mul_f32_e32 v102, v98, v102
	v_mul_f32_e32 v98, 0x3d372713, v103
	v_mul_f32_e32 v98, v103, v98
	v_fma_f32 v98, v103, v98, v103
	v_mul_f32_e32 v98, 0xbfcc422a, v98
	v_mul_f32_e32 v98, 0x3fb8aa3b, v98
	v_exp_f32_e32 v98, v98
	s_nop 0
	v_add_f32_e32 v98, 1.0, v98
	v_rcp_f32_e32 v98, v98
	s_nop 0
	v_mul_f32_e32 v103, v103, v98
	v_mul_f32_e32 v98, 0x3d372713, v99
	v_mul_f32_e32 v98, v99, v98
	v_fma_f32 v98, v99, v98, v99
	v_mul_f32_e32 v98, 0xbfcc422a, v98
	v_mul_f32_e32 v98, 0x3fb8aa3b, v98
	v_exp_f32_e32 v98, v98
	s_nop 0
	v_add_f32_e32 v98, 1.0, v98
	v_rcp_f32_e32 v98, v98
	s_nop 0
	v_mul_f32_e32 v108, v99, v98
	v_mul_f32_e32 v98, 0x3d372713, v104
	v_mul_f32_e32 v98, v104, v98
	v_fma_f32 v98, v104, v98, v104
	v_mul_f32_e32 v98, 0xbfcc422a, v98
	v_mul_f32_e32 v98, 0x3fb8aa3b, v98
	v_exp_f32_e32 v98, v98
	s_nop 0
	v_add_f32_e32 v98, 1.0, v98
	v_rcp_f32_e32 v98, v98
	s_nop 0
	v_mul_f32_e32 v104, v104, v98
	v_mul_f32_e32 v98, 0x3d372713, v100
	v_mul_f32_e32 v98, v100, v98
	v_fma_f32 v98, v100, v98, v100
	v_mul_f32_e32 v98, 0xbfcc422a, v98
	v_mul_f32_e32 v98, 0x3fb8aa3b, v98
	v_exp_f32_e32 v98, v98
	s_nop 0
	v_add_f32_e32 v98, 1.0, v98
	v_rcp_f32_e32 v98, v98
	s_nop 0
	v_mul_f32_e32 v109, v100, v98
	v_mul_f32_e32 v98, 0x3d372713, v105
	v_mul_f32_e32 v98, v105, v98
	v_fma_f32 v98, v105, v98, v105
	v_mul_f32_e32 v98, 0xbfcc422a, v98
	v_mul_f32_e32 v98, 0x3fb8aa3b, v98
	v_exp_f32_e32 v98, v98
	v_cvt_pk_bf16_f32 v100, v0, v103
	s_nop 0
	v_add_f32_e32 v98, 1.0, v98
	v_rcp_f32_e32 v98, v98
	s_nop 0
	v_mul_f32_e32 v105, v105, v98
	v_mul_f32_e32 v98, 0x3d372713, v101
	v_mul_f32_e32 v98, v101, v98
	v_fma_f32 v98, v101, v98, v101
	v_mul_f32_e32 v98, 0xbfcc422a, v98
	v_mul_f32_e32 v98, 0x3fb8aa3b, v98
	v_exp_f32_e32 v98, v98
	s_nop 0
	v_add_f32_e32 v98, 1.0, v98
	v_rcp_f32_e32 v98, v98
	s_nop 0
	v_mul_f32_e32 v110, v101, v98
	v_lshl_add_u64 v[98:99], v[130:131], 0, v[168:169]
	v_lshl_add_u64 v[106:107], v[98:99], 0, s[60:61]
	v_cvt_pk_bf16_f32 v101, v104, v105
	v_mov_b64_e32 v[216:217], v[100:101]
	v_cvt_pk_bf16_f32 v108, v102, v108
	v_cvt_pk_bf16_f32 v109, v109, v110
.LBB0_277:
	v_mov_b64_e32 v[218:219], v[108:109]
	s_nop 1
	v_permlane16_swap_b32_e32 v216, v218
	v_permlane16_swap_b32_e32 v217, v219
	v_lshl_add_u64 v[220:221], v[106:107], 0, v[222:223]
	flat_store_dwordx4 v[220:221], v[216:219]
	s_waitcnt vmcnt(0) lgkmcnt(0)
	v_mov_b64_e32 v[102:103], v[118:119]
	v_mov_b64_e32 v[98:99], v[114:115]
	s_and_b64 vcc, exec, s[54:55]
	v_mov_b64_e32 v[104:105], v[120:121]
	v_mov_b64_e32 v[100:101], v[116:117]
	s_cbranch_vccnz .LBB0_279
	s_lshr_b32 s15, s29, 6
	s_add_i32 s15, s15, s67
	s_and_b32 s15, s15, 31
	v_mov_b32_e32 v0, s15
	v_cndmask_b32_e64 v0, v210, v0, s[38:39]
	v_lshlrev_b32_e32 v0, 7, v0
	v_lshl_add_u64 v[102:103], v[152:153], 0, v[0:1]
	flat_load_dwordx4 v[98:101], v[102:103]
	s_nop 0
	flat_load_dwordx4 v[102:105], v[102:103] offset:16

;     __device__ __forceinline__ void operator()(const f32x4 (&acc)[2][2][4][2], const Unit& u, int wr, int wc, int fr, int fq) const {
;     ...
;                 const int r = u.pm * BM + ai * HALF + wr * 64 + m * 16 + fr;
;                 int b, s, keyidx;
;                 if (lat) { b = r >> 11; s = r & 2047; keyidx = CTXL + s; } else { const int rc = r - T_LAT; b = rc >> 8; s = 0; keyidx = rc & 255; }
; #pragma unroll
;                 for (int bj = 0; bj < 2; ++bj) {
;                     f32x4 v0 = acc[ai][bj][m][0], v1 = acc[ai][bj][m][1];
;                     const bool is_rope = (pn >= 2 && pn <= 6) || (pn == 9 && bj == 0);
;                     if (is_rope && lat) {
;                         const float cs[4] = {c01[0], c01[2], c23[0], c23[2]}, sn[4] = {c01[1], c01[3], c23[1], c23[3]};
; #pragma unroll
;                         for (int i = 0; i < 4; ++i) { const float x0 = v0[i], x1 = v1[i]; v0[i] = x0 * cs[i] - x1 * sn[i]; v1[i] = x1 * cs[i] + x0 * sn[i]; }
;                     }
;                     const int ctb = bj * HALF + wc * 32 + 4 * fq;
;                     if (pn <= 1) {
; #pragma unroll
;                         for (int i = 0; i < 4; ++i) { v0[i] = gelu_tanh_f(v0[i]); v1[i] = gelu_tanh_f(v1[i]); }
;                         bf16_t* p = UV + (size_t)r * 512 + pn * 256 + ctb;
;                         *(u32x2*)p = (u32x2){cvt_pk_bf16(v0[0], v0[1]), cvt_pk_bf16(v0[2], v0[3])}; *(u32x2*)(p + 16) = (u32x2){cvt_pk_bf16(v1[0], v1[1]), cvt_pk_bf16(v1[2], v1[3])};
;                     } else if (pn <= 4) {
;                         v0 = v0 * QSCALE; v1 = v1 * QSCALE;
;                         bf16_t* p = (pn <= 3) ? QB + (size_t)r * 512 + (pn - 2) * 256 + ctb : QC + (size_t)r * 256 + ctb;
;                         *(u32x2*)p = (u32x2){cvt_pk_bf16(v0[0], v0[1]), cvt_pk_bf16(v0[2], v0[3])}; *(u32x2*)(p + 16) = (u32x2){cvt_pk_bf16(v1[0], v1[1]), cvt_pk_bf16(v1[2], v1[3])};
;                     } else if (pn <= 6) {
;                         const int ck = (pn - 5) * 256 + ctb, head = ck >> 7, cw = ck & 127;
;                         bf16_t* p = KB + ((size_t)(b * 4 + head) * NKEY + keyidx) * 128 + cw;
;                         *(u32x2*)p = (u32x2){cvt_pk_bf16(v0[0], v0[1]), cvt_pk_bf16(v0[2], v0[3])}; *(u32x2*)(p + 16) = (u32x2){cvt_pk_bf16(v1[0], v1[1]), cvt_pk_bf16(v1[2], v1[3])};
;                     } else if (pn <= 8) {
.LBB0_281:
	s_movk_i32 s15, 0x7ef
	v_bitop3_b32 v0, v170, s15, 32 bitop3:0xc8
	s_movk_i32 s15, 0xef
	v_add_u32_e32 v0, 0x100, v0
	v_bitop3_b32 v107, v170, s15, 32 bitop3:0xc8
	v_or_b32_e32 v106, 32, v170
	v_cndmask_b32_e64 v0, v107, v0, s[44:45]
	v_lshl_add_u64 v[108:109], s[18:19], 0, v[0:1]
	v_ashrrev_i32_e32 v107, 31, v106
	v_lshlrev_b64 v[112:113], 7, v[108:109]
	v_lshlrev_b64 v[108:109], 10, v[106:107]
	v_lshlrev_b64 v[110:111], 9, v[106:107]
	s_and_b64 vcc, exec, s[52:53]
	s_mov_b64 s[96:97], -1
	s_cbranch_vccnz .LBB0_311
	s_and_b64 vcc, exec, s[48:49]
	s_cbranch_vccnz .LBB0_292
	s_andn2_b64 vcc, exec, s[12:13]
	s_cbranch_vccnz .LBB0_289
	s_andn2_b64 vcc, exec, s[22:23]
	s_cbranch_vccnz .LBB0_286
	v_lshl_add_u64 v[122:123], v[154:155], 0, v[112:113]
	s_mov_b64 s[96:97], 0
	v_cvt_pk_bf16_f32 v106, v94, v95
	v_cvt_pk_bf16_f32 v107, v96, v97
	v_mov_b64_e32 v[216:217], v[106:107]
	v_cvt_pk_bf16_f32 v124, v90, v91
	v_cvt_pk_bf16_f32 v125, v92, v93
.LBB0_286:
	s_andn2_b64 vcc, exec, s[96:97]
	s_cbranch_vccnz .LBB0_288
	v_readlane_b32 s15, v255, 17
	s_ashr_i32 s15, s15, 7
	s_add_i32 s15, s14, s15
	v_mad_i64_i32 v[106:107], s[60:61], s15, v196, v[0:1]
	v_lshlrev_b64 v[106:107], 8, v[106:107]
	s_mov_b64 s[60:61], 0x100
	v_lshl_add_u64 v[122:123], v[156:157], 0, v[106:107]
	v_cvt_pk_bf16_f32 v106, v94, v95
	v_cvt_pk_bf16_f32 v107, v96, v97
	v_mov_b64_e32 v[216:217], v[106:107]
	v_cvt_pk_bf16_f32 v124, v90, v91
	v_cvt_pk_bf16_f32 v125, v92, v93

; __device__ __forceinline__ unsigned cvt_pk_bf16(float lo, float hi) { unsigned r; asm volatile("v_cvt_pk_bf16_f32 %0, %1, %2" : "=v"(r) : "v"(lo), "v"(hi)); return r; }
;     __device__ __forceinline__ void operator()(const f32x4 (&acc)[2][2][4][2], const Unit& u, int wr, int wc, int fr, int fq) const {
;     ...
;                     } else if (pn <= 8) {
;                         const int cv = (pn - 7) * 256 + ctb, head = cv >> 7, e = cv & 127;
;                         bf16_t* p = VBt + ((size_t)(b * 4 + head) * NKEY + keyidx) * 128 + e;
;                         *(u32x2*)p = (u32x2){cvt_pk_bf16(v0[0], v0[1]), cvt_pk_bf16(v0[2], v0[3])}; *(u32x2*)(p + 16) = (u32x2){cvt_pk_bf16(v1[0], v1[1]), cvt_pk_bf16(v1[2], v1[3])};
.LBB0_289:
	s_andn2_b64 vcc, exec, s[96:97]
	s_cbranch_vccnz .LBB0_291
	v_mad_i64_i32 v[106:107], s[60:61], s3, v196, v[0:1]
	v_lshlrev_b64 v[106:107], 8, v[106:107]
	s_mov_b64 s[60:61], 0x100
	v_lshl_add_u64 v[122:123], v[160:161], 0, v[106:107]
	v_cvt_pk_bf16_f32 v106, v94, v95
	v_cvt_pk_bf16_f32 v107, v96, v97
	v_mov_b64_e32 v[216:217], v[106:107]
	v_cvt_pk_bf16_f32 v124, v90, v91
	v_cvt_pk_bf16_f32 v125, v92, v93

; __device__ __forceinline__ unsigned cvt_pk_bf16(float lo, float hi) { unsigned r; asm volatile("v_cvt_pk_bf16_f32 %0, %1, %2" : "=v"(r) : "v"(lo), "v"(hi)); return r; }
;     __device__ __forceinline__ void operator()(const f32x4 (&acc)[2][2][4][2], const Unit& u, int wr, int wc, int fr, int fq) const {
;     ...
;                     } else if (pn <= 4) {
;                         v0 = v0 * QSCALE; v1 = v1 * QSCALE;
;                         bf16_t* p = (pn <= 3) ? QB + (size_t)r * 512 + (pn - 2) * 256 + ctb : QC + (size_t)r * 256 + ctb;
;                         *(u32x2*)p = (u32x2){cvt_pk_bf16(v0[0], v0[1]), cvt_pk_bf16(v0[2], v0[3])}; *(u32x2*)(p + 16) = (u32x2){cvt_pk_bf16(v1[0], v1[1]), cvt_pk_bf16(v1[2], v1[3])};
.LBB0_292:
	s_andn2_b64 vcc, exec, s[96:97]
	s_cbranch_vccnz .LBB0_294
	v_lshl_add_u64 v[130:131], s[8:9], 0, v[108:109]
	s_movk_i32 s96, 0xfc00
	v_lshl_add_u64 v[130:131], s[16:17], 1, v[130:131]
	s_mov_b32 s97, -1
	v_lshl_add_u64 v[122:123], s[0:1], 0, v[110:111]
	v_lshl_add_u64 v[130:131], v[130:131], 0, s[96:97]
	v_pk_mul_f32 v[124:125], v[94:95], s[74:75] op_sel_hi:[1,0]
	v_cndmask_b32_e64 v123, v131, v123, s[42:43]
	v_cndmask_b32_e64 v122, v130, v122, s[42:43]
	v_mov_b32_e32 v169, v1
	v_pk_mul_f32 v[106:107], v[96:97], s[74:75] op_sel_hi:[1,0]
	v_lshl_add_u64 v[122:123], v[122:123], 0, v[168:169]
	v_cvt_pk_bf16_f32 v124, v124, v125
	v_cvt_pk_bf16_f32 v125, v106, v107
	v_pk_mul_f32 v[126:127], v[92:93], s[74:75] op_sel_hi:[1,0]
	v_pk_mul_f32 v[128:129], v[90:91], s[74:75] op_sel_hi:[1,0]
	v_mov_b64_e32 v[216:217], v[124:125]
	v_cvt_pk_bf16_f32 v124, v128, v129
	v_cvt_pk_bf16_f32 v125, v126, v127

;     __device__ __forceinline__ void operator()(const f32x4 (&acc)[2][2][4][2], const Unit& u, int wr, int wc, int fr, int fq) const {
;     ...
;                 for (int bj = 0; bj < 2; ++bj) {
;                     f32x4 v0 = acc[ai][bj][m][0], v1 = acc[ai][bj][m][1];
;                     const bool is_rope = (pn >= 2 && pn <= 6) || (pn == 9 && bj == 0);
;                     if (is_rope && lat) {
;                         const float cs[4] = {c01[0], c01[2], c23[0], c23[2]}, sn[4] = {c01[1], c01[3], c23[1], c23[3]};
; #pragma unroll
;                         for (int i = 0; i < 4; ++i) { const float x0 = v0[i], x1 = v1[i]; v0[i] = x0 * cs[i] - x1 * sn[i]; v1[i] = x1 * cs[i] + x0 * sn[i]; }
;                     }
;                     const int ctb = bj * HALF + wc * 32 + 4 * fq;
;                     if (pn <= 1) {
; #pragma unroll
;                         for (int i = 0; i < 4; ++i) { v0[i] = gelu_tanh_f(v0[i]); v1[i] = gelu_tanh_f(v1[i]); }
;                         bf16_t* p = UV + (size_t)r * 512 + pn * 256 + ctb;
;                         *(u32x2*)p = (u32x2){cvt_pk_bf16(v0[0], v0[1]), cvt_pk_bf16(v0[2], v0[3])}; *(u32x2*)(p + 16) = (u32x2){cvt_pk_bf16(v1[0], v1[1]), cvt_pk_bf16(v1[2], v1[3])};
;                     } else if (pn <= 4) {
;                         v0 = v0 * QSCALE; v1 = v1 * QSCALE;
;                         bf16_t* p = (pn <= 3) ? QB + (size_t)r * 512 + (pn - 2) * 256 + ctb : QC + (size_t)r * 256 + ctb;
;                         *(u32x2*)p = (u32x2){cvt_pk_bf16(v0[0], v0[1]), cvt_pk_bf16(v0[2], v0[3])}; *(u32x2*)(p + 16) = (u32x2){cvt_pk_bf16(v1[0], v1[1]), cvt_pk_bf16(v1[2], v1[3])};
;                     } else if (pn <= 6) {
;                         const int ck = (pn - 5) * 256 + ctb, head = ck >> 7, cw = ck & 127;
;                         bf16_t* p = KB + ((size_t)(b * 4 + head) * NKEY + keyidx) * 128 + cw;
;                         *(u32x2*)p = (u32x2){cvt_pk_bf16(v0[0], v0[1]), cvt_pk_bf16(v0[2], v0[3])}; *(u32x2*)(p + 16) = (u32x2){cvt_pk_bf16(v1[0], v1[1]), cvt_pk_bf16(v1[2], v1[3])};
;                     } else if (pn <= 8) {
;                         const int cv = (pn - 7) * 256 + ctb, head = cv >> 7, e = cv & 127;
;                         bf16_t* p = VBt + ((size_t)(b * 4 + head) * NKEY + keyidx) * 128 + e;
.LBB0_295:
	s_and_b64 vcc, exec, s[50:51]
	v_mov_b64_e32 v[218:219], v[124:125]
	s_nop 1
	v_permlane16_swap_b32_e32 v216, v218
	v_permlane16_swap_b32_e32 v217, v219
	v_lshl_add_u64 v[220:221], v[122:123], 0, v[222:223]
	flat_store_dwordx4 v[220:221], v[216:219]
	s_cbranch_vccnz .LBB0_297

; __device__ __forceinline__ unsigned cvt_pk_bf16(float lo, float hi) { unsigned r; asm volatile("v_cvt_pk_bf16_f32 %0, %1, %2" : "=v"(r) : "v"(lo), "v"(hi)); return r; }
;     __device__ __forceinline__ void operator()(const f32x4 (&acc)[2][2][4][2], const Unit& u, int wr, int wc, int fr, int fq) const {
;     ...
;                     } else if (pn <= 6) {
;                         const int ck = (pn - 5) * 256 + ctb, head = ck >> 7, cw = ck & 127;
;                         bf16_t* p = KB + ((size_t)(b * 4 + head) * NKEY + keyidx) * 128 + cw;
;                         *(u32x2*)p = (u32x2){cvt_pk_bf16(v0[0], v0[1]), cvt_pk_bf16(v0[2], v0[3])}; *(u32x2*)(p + 16) = (u32x2){cvt_pk_bf16(v1[0], v1[1]), cvt_pk_bf16(v1[2], v1[3])};
;                     } else if (pn <= 8) {
;                         const int cv = (pn - 7) * 256 + ctb, head = cv >> 7, e = cv & 127;
;                         bf16_t* p = VBt + ((size_t)(b * 4 + head) * NKEY + keyidx) * 128 + e;
;                         *(u32x2*)p = (u32x2){cvt_pk_bf16(v0[0], v0[1]), cvt_pk_bf16(v0[2], v0[3])}; *(u32x2*)(p + 16) = (u32x2){cvt_pk_bf16(v1[0], v1[1]), cvt_pk_bf16(v1[2], v1[3])};
;                     } else {
;                         const int kv = wc >> 1, d = (wc & 1) * 32 + 4 * fq;
;                         if (bj == 0) {
;                             bf16_t* p = KC + ((size_t)(b * 2 + kv) * NKEY + keyidx) * 64 + d;
;                             *(u32x2*)p = (u32x2){cvt_pk_bf16(v0[0], v0[1]), cvt_pk_bf16(v0[2], v0[3])}; *(u32x2*)(p + 16) = (u32x2){cvt_pk_bf16(v1[0], v1[1]), cvt_pk_bf16(v1[2], v1[3])};
;                         } else {
;                             bf16_t* p = VCt + ((size_t)(b * 2 + kv) * NKEY + keyidx) * 64 + d;
;                             *(u32x2*)p = (u32x2){cvt_pk_bf16(v0[0], v0[1]), cvt_pk_bf16(v0[2], v0[3])}; *(u32x2*)(p + 16) = (u32x2){cvt_pk_bf16(v1[0], v1[1]), cvt_pk_bf16(v1[2], v1[3])};
;                         }
;                     }
.LBB0_297:
	s_and_b64 vcc, exec, s[52:53]
	s_mov_b64 s[96:97], -1
	s_cbranch_vccnz .LBB0_313
	s_and_b64 vcc, exec, s[48:49]
	s_cbranch_vccnz .LBB0_308
	s_andn2_b64 vcc, exec, s[12:13]
	s_cbranch_vccnz .LBB0_305
	s_andn2_b64 vcc, exec, s[22:23]
	s_cbranch_vccnz .LBB0_302
	v_lshl_add_u64 v[90:91], v[162:163], 0, v[112:113]
	v_cvt_pk_bf16_f32 v92, v86, v87
	v_cvt_pk_bf16_f32 v93, v88, v89
	s_mov_b64 s[96:97], 0
	v_mov_b64_e32 v[216:217], v[92:93]
	v_cvt_pk_bf16_f32 v92, v82, v83
	v_cvt_pk_bf16_f32 v93, v84, v85
.LBB0_302:
	s_andn2_b64 vcc, exec, s[96:97]
	s_cbranch_vccnz .LBB0_304
	s_add_i32 s15, s16, 0xfffff980
	s_ashr_i32 s15, s15, 7
	s_add_i32 s15, s14, s15
	v_mad_i64_i32 v[90:91], s[60:61], s15, v196, v[0:1]
	v_lshlrev_b64 v[90:91], 8, v[90:91]
	s_mov_b64 s[60:61], 0x100
	v_lshl_add_u64 v[90:91], v[156:157], 0, v[90:91]
	v_cvt_pk_bf16_f32 v92, v86, v87
	v_cvt_pk_bf16_f32 v93, v88, v89
	v_mov_b64_e32 v[216:217], v[92:93]
	v_cvt_pk_bf16_f32 v92, v82, v83
	v_cvt_pk_bf16_f32 v93, v84, v85

; __device__ __forceinline__ unsigned cvt_pk_bf16(float lo, float hi) { unsigned r; asm volatile("v_cvt_pk_bf16_f32 %0, %1, %2" : "=v"(r) : "v"(lo), "v"(hi)); return r; }
;     __device__ __forceinline__ void operator()(const f32x4 (&acc)[2][2][4][2], const Unit& u, int wr, int wc, int fr, int fq) const {
;     ...
;                     } else if (pn <= 8) {
;                         const int cv = (pn - 7) * 256 + ctb, head = cv >> 7, e = cv & 127;
;                         bf16_t* p = VBt + ((size_t)(b * 4 + head) * NKEY + keyidx) * 128 + e;
;                         *(u32x2*)p = (u32x2){cvt_pk_bf16(v0[0], v0[1]), cvt_pk_bf16(v0[2], v0[3])}; *(u32x2*)(p + 16) = (u32x2){cvt_pk_bf16(v1[0], v1[1]), cvt_pk_bf16(v1[2], v1[3])};
.LBB0_305:
	s_andn2_b64 vcc, exec, s[96:97]
	s_cbranch_vccnz .LBB0_307
	s_or_b32 s15, s3, 1
	v_mad_i64_i32 v[90:91], s[60:61], s15, v196, v[0:1]
	v_lshlrev_b64 v[90:91], 8, v[90:91]
	s_mov_b64 s[60:61], 0x100
	v_lshl_add_u64 v[90:91], v[160:161], 0, v[90:91]
	v_cvt_pk_bf16_f32 v92, v86, v87
	v_cvt_pk_bf16_f32 v93, v88, v89
	v_mov_b64_e32 v[216:217], v[92:93]
	v_cvt_pk_bf16_f32 v92, v82, v83
	v_cvt_pk_bf16_f32 v93, v84, v85

; __device__ __forceinline__ unsigned cvt_pk_bf16(float lo, float hi) { unsigned r; asm volatile("v_cvt_pk_bf16_f32 %0, %1, %2" : "=v"(r) : "v"(lo), "v"(hi)); return r; }
;     __device__ __forceinline__ void operator()(const f32x4 (&acc)[2][2][4][2], const Unit& u, int wr, int wc, int fr, int fq) const {
;     ...
;                     } else if (pn <= 4) {
;                         v0 = v0 * QSCALE; v1 = v1 * QSCALE;
;                         bf16_t* p = (pn <= 3) ? QB + (size_t)r * 512 + (pn - 2) * 256 + ctb : QC + (size_t)r * 256 + ctb;
;                         *(u32x2*)p = (u32x2){cvt_pk_bf16(v0[0], v0[1]), cvt_pk_bf16(v0[2], v0[3])}; *(u32x2*)(p + 16) = (u32x2){cvt_pk_bf16(v1[0], v1[1]), cvt_pk_bf16(v1[2], v1[3])};
.LBB0_308:
	s_andn2_b64 vcc, exec, s[96:97]
	s_cbranch_vccnz .LBB0_310
	v_lshl_add_u64 v[108:109], s[8:9], 0, v[108:109]
	s_movk_i32 s96, 0xfc00
	v_lshl_add_u64 v[108:109], s[16:17], 1, v[108:109]
	s_mov_b32 s97, -1
	v_lshl_add_u64 v[90:91], s[0:1], 0, v[110:111]
	v_lshl_add_u64 v[108:109], v[108:109], 0, s[96:97]
	v_cndmask_b32_e64 v91, v109, v91, s[42:43]
	v_cndmask_b32_e64 v90, v108, v90, s[42:43]
	v_mov_b32_e32 v169, v1
	v_lshl_add_u64 v[108:109], v[90:91], 0, v[168:169]
	v_pk_mul_f32 v[92:93], v[88:89], s[74:75] op_sel_hi:[1,0]
	v_pk_mul_f32 v[94:95], v[86:87], s[74:75] op_sel_hi:[1,0]
	v_lshl_add_u64 v[90:91], v[108:109], 0, s[60:61]
	v_pk_mul_f32 v[96:97], v[84:85], s[74:75] op_sel_hi:[1,0]
	v_pk_mul_f32 v[112:113], v[82:83], s[74:75] op_sel_hi:[1,0]
	v_cvt_pk_bf16_f32 v94, v94, v95
	v_cvt_pk_bf16_f32 v95, v92, v93
	v_mov_b64_e32 v[216:217], v[94:95]
	v_cvt_pk_bf16_f32 v92, v112, v113
	v_cvt_pk_bf16_f32 v93, v96, v97

; __device__ __forceinline__ unsigned cvt_pk_bf16(float lo, float hi) { unsigned r; asm volatile("v_cvt_pk_bf16_f32 %0, %1, %2" : "=v"(r) : "v"(lo), "v"(hi)); return r; }
; __device__ __forceinline__ float gelu_tanh_f(float x) { const float y = 1.5957691216057308f * (x + 0.044715f * x * x * x); return x * __builtin_amdgcn_rcpf(1.f + __expf(-y)); }
;     __device__ __forceinline__ void operator()(const f32x4 (&acc)[2][2][4][2], const Unit& u, int wr, int wc, int fr, int fq) const {
;     ...
;                     if (pn <= 1) {
; #pragma unroll
;                         for (int i = 0; i < 4; ++i) { v0[i] = gelu_tanh_f(v0[i]); v1[i] = gelu_tanh_f(v1[i]); }
;                         bf16_t* p = UV + (size_t)r * 512 + pn * 256 + ctb;
;                         *(u32x2*)p = (u32x2){cvt_pk_bf16(v0[0], v0[1]), cvt_pk_bf16(v0[2], v0[3])}; *(u32x2*)(p + 16) = (u32x2){cvt_pk_bf16(v1[0], v1[1]), cvt_pk_bf16(v1[2], v1[3])};
.LBB0_312:
	v_mul_f32_e32 v122, 0x3d372713, v94
	v_mul_f32_e32 v122, v94, v122
	v_fma_f32 v122, v94, v122, v94
	v_mul_f32_e32 v122, 0xbfcc422a, v122
	v_mul_f32_e32 v122, 0x3fb8aa3b, v122
	v_exp_f32_e32 v122, v122
	v_mov_b32_e32 v169, v1
	v_add_f32_e32 v122, 1.0, v122
	v_rcp_f32_e32 v122, v122
	s_nop 0
	v_mul_f32_e32 v94, v94, v122
	v_mul_f32_e32 v122, 0x3d372713, v90
	v_mul_f32_e32 v122, v90, v122
	v_fma_f32 v122, v90, v122, v90
	v_mul_f32_e32 v122, 0xbfcc422a, v122
	v_mul_f32_e32 v122, 0x3fb8aa3b, v122
	v_exp_f32_e32 v122, v122
	s_nop 0
	v_add_f32_e32 v122, 1.0, v122
	v_rcp_f32_e32 v122, v122
	s_nop 0
	v_mul_f32_e32 v124, v90, v122
	v_mul_f32_e32 v90, 0x3d372713, v95
	v_mul_f32_e32 v90, v95, v90
	v_fma_f32 v90, v95, v90, v95
	v_mul_f32_e32 v90, 0xbfcc422a, v90
	v_mul_f32_e32 v90, 0x3fb8aa3b, v90
	v_exp_f32_e32 v90, v90
	v_lshl_add_u64 v[122:123], v[106:107], 0, v[168:169]
	v_add_f32_e32 v90, 1.0, v90
	v_rcp_f32_e32 v90, v90
	s_nop 0
	v_mul_f32_e32 v90, v95, v90
	v_mul_f32_e32 v95, 0x3d372713, v91
	v_mul_f32_e32 v95, v91, v95
	v_fma_f32 v95, v91, v95, v91
	v_mul_f32_e32 v95, 0xbfcc422a, v95
	v_mul_f32_e32 v95, 0x3fb8aa3b, v95
	v_exp_f32_e32 v95, v95
	v_cvt_pk_bf16_f32 v90, v94, v90
	s_nop 0
	v_add_f32_e32 v95, 1.0, v95
	v_rcp_f32_e32 v95, v95
	s_nop 0
	v_mul_f32_e32 v95, v91, v95
	v_mul_f32_e32 v91, 0x3d372713, v96
	v_mul_f32_e32 v91, v96, v91
	v_fma_f32 v91, v96, v91, v96
	v_mul_f32_e32 v91, 0xbfcc422a, v91
	v_mul_f32_e32 v91, 0x3fb8aa3b, v91
	v_exp_f32_e32 v91, v91
	s_nop 0
	v_add_f32_e32 v91, 1.0, v91
	v_rcp_f32_e32 v91, v91
	s_nop 0
	v_mul_f32_e32 v91, v96, v91
	v_mul_f32_e32 v96, 0x3d372713, v92
	v_mul_f32_e32 v96, v92, v96
	v_fma_f32 v96, v92, v96, v92
	v_mul_f32_e32 v96, 0xbfcc422a, v96
	v_mul_f32_e32 v96, 0x3fb8aa3b, v96
	v_exp_f32_e32 v96, v96
	s_nop 0
	v_add_f32_e32 v96, 1.0, v96
	v_rcp_f32_e32 v96, v96
	s_nop 0
	v_mul_f32_e32 v92, v92, v96
	v_mul_f32_e32 v96, 0x3d372713, v97
	v_mul_f32_e32 v96, v97, v96
	v_fma_f32 v96, v97, v96, v97
	v_mul_f32_e32 v96, 0xbfcc422a, v96
	v_mul_f32_e32 v96, 0x3fb8aa3b, v96
	v_exp_f32_e32 v96, v96
	s_nop 0
	v_add_f32_e32 v96, 1.0, v96
	v_rcp_f32_e32 v96, v96
	s_nop 0
	v_mul_f32_e32 v96, v97, v96
	v_mul_f32_e32 v97, 0x3d372713, v93
	v_mul_f32_e32 v97, v93, v97
	v_fma_f32 v97, v93, v97, v93
	v_mul_f32_e32 v97, 0xbfcc422a, v97
	v_mul_f32_e32 v97, 0x3fb8aa3b, v97
	v_exp_f32_e32 v97, v97
	v_cvt_pk_bf16_f32 v91, v91, v96
	v_mov_b64_e32 v[216:217], v[90:91]
	v_cvt_pk_bf16_f32 v124, v124, v95
	v_add_f32_e32 v97, 1.0, v97
	v_rcp_f32_e32 v97, v97
	s_nop 0
	v_mul_f32_e32 v93, v93, v97
	v_cvt_pk_bf16_f32 v125, v92, v93
	s_and_b64 vcc, exec, s[50:51]
	v_mov_b64_e32 v[218:219], v[124:125]
	s_nop 1
	v_permlane16_swap_b32_e32 v216, v218
	v_permlane16_swap_b32_e32 v217, v219
	v_lshl_add_u64 v[220:221], v[122:123], 0, v[222:223]
	flat_store_dwordx4 v[220:221], v[216:219]
	s_cbranch_vccnz .LBB0_297
	s_branch .LBB0_296

; __device__ __forceinline__ unsigned cvt_pk_bf16(float lo, float hi) { unsigned r; asm volatile("v_cvt_pk_bf16_f32 %0, %1, %2" : "=v"(r) : "v"(lo), "v"(hi)); return r; }
; __device__ __forceinline__ float gelu_tanh_f(float x) { const float y = 1.5957691216057308f * (x + 0.044715f * x * x * x); return x * __builtin_amdgcn_rcpf(1.f + __expf(-y)); }
; #define ROPE_FETCH(ai_, m_) do { const int s_ = (u.pm * BM + (ai_) * HALF + wr * 64 + (m_) * 16 + fr) & 2047, pos_ = (wc & 1) ? (s_ & 63) : (s_ >> 6); \
;             n01 = *(const f32x4*)(rope + pos_ * 16 + 4 * fq); n23 = *(const f32x4*)(rope + pos_ * 16 + 4 * fq + 2); } while (0)
;     __device__ __forceinline__ void operator()(const f32x4 (&acc)[2][2][4][2], const Unit& u, int wr, int wc, int fr, int fq) const {
;     ...
;         if (do_rope) ROPE_FETCH(0, 0);
; #pragma unroll
;         for (int ai = 0; ai < 2; ++ai)
; #pragma unroll
;             for (int m = 0; m < 4; ++m) {
;                 const f32x4 c01 = n01, c23 = n23;
;                 if (do_rope && (ai * 4 + m) < 7) ROPE_FETCH((ai * 4 + m + 1) >> 2, (ai * 4 + m + 1) & 3);
;     ...
;                     if (pn <= 1) {
; #pragma unroll
;                         for (int i = 0; i < 4; ++i) { v0[i] = gelu_tanh_f(v0[i]); v1[i] = gelu_tanh_f(v1[i]); }
;                         bf16_t* p = UV + (size_t)r * 512 + pn * 256 + ctb;
;                         *(u32x2*)p = (u32x2){cvt_pk_bf16(v0[0], v0[1]), cvt_pk_bf16(v0[2], v0[3])}; *(u32x2*)(p + 16) = (u32x2){cvt_pk_bf16(v1[0], v1[1]), cvt_pk_bf16(v1[2], v1[3])};
.LBB0_314:
	v_mul_f32_e32 v0, 0x3d372713, v86
	v_mul_f32_e32 v0, v86, v0
	v_fma_f32 v0, v86, v0, v86
	v_mul_f32_e32 v0, 0xbfcc422a, v0
	v_mul_f32_e32 v0, 0x3fb8aa3b, v0
	v_exp_f32_e32 v0, v0
	v_mov_b32_e32 v169, v1
	v_add_f32_e32 v0, 1.0, v0
	v_rcp_f32_e32 v0, v0
	s_nop 0
	v_mul_f32_e32 v0, v86, v0
	v_mul_f32_e32 v86, 0x3d372713, v82
	v_mul_f32_e32 v86, v82, v86
	v_fma_f32 v86, v82, v86, v82
	v_mul_f32_e32 v86, 0xbfcc422a, v86
	v_mul_f32_e32 v86, 0x3fb8aa3b, v86
	v_exp_f32_e32 v86, v86
	s_nop 0
	v_add_f32_e32 v86, 1.0, v86
	v_rcp_f32_e32 v86, v86
	s_nop 0
	v_mul_f32_e32 v86, v82, v86
	v_mul_f32_e32 v82, 0x3d372713, v87
	v_mul_f32_e32 v82, v87, v82
	v_fma_f32 v82, v87, v82, v87
	v_mul_f32_e32 v82, 0xbfcc422a, v82
	v_mul_f32_e32 v82, 0x3fb8aa3b, v82
	v_exp_f32_e32 v82, v82
	s_nop 0
	v_add_f32_e32 v82, 1.0, v82
	v_rcp_f32_e32 v82, v82
	s_nop 0
	v_mul_f32_e32 v87, v87, v82
	v_mul_f32_e32 v82, 0x3d372713, v83
	v_mul_f32_e32 v82, v83, v82
	v_fma_f32 v82, v83, v82, v83
	v_mul_f32_e32 v82, 0xbfcc422a, v82
	v_mul_f32_e32 v82, 0x3fb8aa3b, v82
	v_exp_f32_e32 v82, v82
	s_nop 0
	v_add_f32_e32 v82, 1.0, v82
	v_rcp_f32_e32 v82, v82
	s_nop 0
	v_mul_f32_e32 v92, v83, v82
	v_mul_f32_e32 v82, 0x3d372713, v88
	v_mul_f32_e32 v82, v88, v82
	v_fma_f32 v82, v88, v82, v88
	v_mul_f32_e32 v82, 0xbfcc422a, v82
	v_mul_f32_e32 v82, 0x3fb8aa3b, v82
	v_exp_f32_e32 v82, v82
	s_nop 0
	v_add_f32_e32 v82, 1.0, v82
	v_rcp_f32_e32 v82, v82
	s_nop 0
	v_mul_f32_e32 v88, v88, v82
	v_mul_f32_e32 v82, 0x3d372713, v84
	v_mul_f32_e32 v82, v84, v82
	v_fma_f32 v82, v84, v82, v84
	v_mul_f32_e32 v82, 0xbfcc422a, v82
	v_mul_f32_e32 v82, 0x3fb8aa3b, v82
	v_exp_f32_e32 v82, v82
	s_nop 0
	v_add_f32_e32 v82, 1.0, v82
	v_rcp_f32_e32 v82, v82
	s_nop 0
	v_mul_f32_e32 v93, v84, v82
	v_mul_f32_e32 v82, 0x3d372713, v89
	v_mul_f32_e32 v82, v89, v82
	v_fma_f32 v82, v89, v82, v89
	v_mul_f32_e32 v82, 0xbfcc422a, v82
	v_mul_f32_e32 v82, 0x3fb8aa3b, v82
	v_exp_f32_e32 v82, v82
	v_cvt_pk_bf16_f32 v84, v0, v87
	s_nop 0
	v_add_f32_e32 v82, 1.0, v82
	v_rcp_f32_e32 v82, v82
	s_nop 0
	v_mul_f32_e32 v89, v89, v82
	v_mul_f32_e32 v82, 0x3d372713, v85
	v_mul_f32_e32 v82, v85, v82
	v_fma_f32 v82, v85, v82, v85
	v_mul_f32_e32 v82, 0xbfcc422a, v82
	v_mul_f32_e32 v82, 0x3fb8aa3b, v82
	v_exp_f32_e32 v82, v82
	s_nop 0
	v_add_f32_e32 v82, 1.0, v82
	v_rcp_f32_e32 v82, v82
	s_nop 0
	v_mul_f32_e32 v94, v85, v82
	v_lshl_add_u64 v[82:83], v[106:107], 0, v[168:169]
	v_lshl_add_u64 v[90:91], v[82:83], 0, s[60:61]
	v_cvt_pk_bf16_f32 v85, v88, v89
	v_mov_b64_e32 v[216:217], v[84:85]
	v_cvt_pk_bf16_f32 v92, v86, v92
	v_cvt_pk_bf16_f32 v93, v93, v94
.LBB0_315:
	v_mov_b64_e32 v[218:219], v[92:93]
	s_nop 1
	v_permlane16_swap_b32_e32 v216, v218
	v_permlane16_swap_b32_e32 v217, v219
	v_lshl_add_u64 v[220:221], v[90:91], 0, v[222:223]
	flat_store_dwordx4 v[220:221], v[216:219]
	s_waitcnt vmcnt(0) lgkmcnt(0)
	v_mov_b64_e32 v[86:87], v[102:103]
	v_mov_b64_e32 v[82:83], v[98:99]
	s_and_b64 vcc, exec, s[54:55]
	v_mov_b64_e32 v[88:89], v[104:105]
	v_mov_b64_e32 v[84:85], v[100:101]
	s_cbranch_vccnz .LBB0_317
	s_lshr_b32 s15, s29, 6
	v_readlane_b32 s96, v255, 14
	s_add_i32 s15, s15, s96
	s_and_b32 s15, s15, 31
	v_mov_b32_e32 v0, s15
	v_cndmask_b32_e64 v0, v151, v0, s[38:39]
	v_lshlrev_b32_e32 v0, 7, v0
	v_lshl_add_u64 v[86:87], v[152:153], 0, v[0:1]
	flat_load_dwordx4 v[82:85], v[86:87]
	s_nop 0
	flat_load_dwordx4 v[86:89], v[86:87] offset:16

;     __device__ __forceinline__ void operator()(const f32x4 (&acc)[2][2][4][2], const Unit& u, int wr, int wc, int fr, int fq) const {
;     ...
;                 const int r = u.pm * BM + ai * HALF + wr * 64 + m * 16 + fr;
;                 int b, s, keyidx;
;                 if (lat) { b = r >> 11; s = r & 2047; keyidx = CTXL + s; } else { const int rc = r - T_LAT; b = rc >> 8; s = 0; keyidx = rc & 255; }
; #pragma unroll
;                 for (int bj = 0; bj < 2; ++bj) {
;                     f32x4 v0 = acc[ai][bj][m][0], v1 = acc[ai][bj][m][1];
;                     const bool is_rope = (pn >= 2 && pn <= 6) || (pn == 9 && bj == 0);
;                     if (is_rope && lat) {
;                         const float cs[4] = {c01[0], c01[2], c23[0], c23[2]}, sn[4] = {c01[1], c01[3], c23[1], c23[3]};
; #pragma unroll
;                         for (int i = 0; i < 4; ++i) { const float x0 = v0[i], x1 = v1[i]; v0[i] = x0 * cs[i] - x1 * sn[i]; v1[i] = x1 * cs[i] + x0 * sn[i]; }
;                     }
;                     const int ctb = bj * HALF + wc * 32 + 4 * fq;
;                     if (pn <= 1) {
; #pragma unroll
;                         for (int i = 0; i < 4; ++i) { v0[i] = gelu_tanh_f(v0[i]); v1[i] = gelu_tanh_f(v1[i]); }
;                         bf16_t* p = UV + (size_t)r * 512 + pn * 256 + ctb;
;                         *(u32x2*)p = (u32x2){cvt_pk_bf16(v0[0], v0[1]), cvt_pk_bf16(v0[2], v0[3])}; *(u32x2*)(p + 16) = (u32x2){cvt_pk_bf16(v1[0], v1[1]), cvt_pk_bf16(v1[2], v1[3])};
;                     } else if (pn <= 4) {
;                         v0 = v0 * QSCALE; v1 = v1 * QSCALE;
;                         bf16_t* p = (pn <= 3) ? QB + (size_t)r * 512 + (pn - 2) * 256 + ctb : QC + (size_t)r * 256 + ctb;
;                         *(u32x2*)p = (u32x2){cvt_pk_bf16(v0[0], v0[1]), cvt_pk_bf16(v0[2], v0[3])}; *(u32x2*)(p + 16) = (u32x2){cvt_pk_bf16(v1[0], v1[1]), cvt_pk_bf16(v1[2], v1[3])};
;                     } else if (pn <= 6) {
;                         const int ck = (pn - 5) * 256 + ctb, head = ck >> 7, cw = ck & 127;
;                         bf16_t* p = KB + ((size_t)(b * 4 + head) * NKEY + keyidx) * 128 + cw;
;                         *(u32x2*)p = (u32x2){cvt_pk_bf16(v0[0], v0[1]), cvt_pk_bf16(v0[2], v0[3])}; *(u32x2*)(p + 16) = (u32x2){cvt_pk_bf16(v1[0], v1[1]), cvt_pk_bf16(v1[2], v1[3])};
;                     } else if (pn <= 8) {
.LBB0_319:
	s_movk_i32 s15, 0x7ff
	v_bitop3_b32 v0, v170, s15, 48 bitop3:0xc8
	s_movk_i32 s15, 0xff
	v_add_u32_e32 v0, 0x100, v0
	v_bitop3_b32 v91, v170, s15, 48 bitop3:0xc8
	v_or_b32_e32 v90, 48, v170
	v_cndmask_b32_e64 v0, v91, v0, s[44:45]
	v_lshl_add_u64 v[92:93], s[18:19], 0, v[0:1]
	v_ashrrev_i32_e32 v91, 31, v90
	v_lshlrev_b64 v[96:97], 7, v[92:93]
	v_lshlrev_b64 v[92:93], 10, v[90:91]
	v_lshlrev_b64 v[94:95], 9, v[90:91]
	s_and_b64 vcc, exec, s[52:53]
	s_mov_b64 s[18:19], -1
	s_cbranch_vccnz .LBB0_349
	s_and_b64 vcc, exec, s[48:49]
	s_cbranch_vccnz .LBB0_330
	s_andn2_b64 vcc, exec, s[12:13]
	s_cbranch_vccnz .LBB0_327
	s_andn2_b64 vcc, exec, s[22:23]
	s_cbranch_vccnz .LBB0_324
	v_lshl_add_u64 v[106:107], v[154:155], 0, v[96:97]
	s_mov_b64 s[18:19], 0
	v_cvt_pk_bf16_f32 v90, v78, v79
	v_cvt_pk_bf16_f32 v91, v80, v81
	v_mov_b64_e32 v[216:217], v[90:91]
	v_cvt_pk_bf16_f32 v108, v74, v75
	v_cvt_pk_bf16_f32 v109, v76, v77
.LBB0_324:
	s_andn2_b64 vcc, exec, s[18:19]
	s_cbranch_vccnz .LBB0_326
	v_readlane_b32 s15, v255, 17
	s_ashr_i32 s15, s15, 7
	s_add_i32 s15, s14, s15
	v_mad_i64_i32 v[90:91], s[18:19], s15, v196, v[0:1]
	v_lshlrev_b64 v[90:91], 8, v[90:91]
	v_lshl_add_u64 v[106:107], v[156:157], 0, v[90:91]
	v_cvt_pk_bf16_f32 v90, v78, v79
	v_cvt_pk_bf16_f32 v91, v80, v81
	v_mov_b64_e32 v[216:217], v[90:91]
	v_cvt_pk_bf16_f32 v108, v74, v75
	v_cvt_pk_bf16_f32 v109, v76, v77

; __device__ __forceinline__ unsigned cvt_pk_bf16(float lo, float hi) { unsigned r; asm volatile("v_cvt_pk_bf16_f32 %0, %1, %2" : "=v"(r) : "v"(lo), "v"(hi)); return r; }
;     __device__ __forceinline__ void operator()(const f32x4 (&acc)[2][2][4][2], const Unit& u, int wr, int wc, int fr, int fq) const {
;     ...
;                     } else if (pn <= 8) {
;                         const int cv = (pn - 7) * 256 + ctb, head = cv >> 7, e = cv & 127;
;                         bf16_t* p = VBt + ((size_t)(b * 4 + head) * NKEY + keyidx) * 128 + e;
;                         *(u32x2*)p = (u32x2){cvt_pk_bf16(v0[0], v0[1]), cvt_pk_bf16(v0[2], v0[3])}; *(u32x2*)(p + 16) = (u32x2){cvt_pk_bf16(v1[0], v1[1]), cvt_pk_bf16(v1[2], v1[3])};
.LBB0_327:
	s_andn2_b64 vcc, exec, s[18:19]
	s_cbranch_vccnz .LBB0_329
	v_mad_i64_i32 v[90:91], s[18:19], s3, v196, v[0:1]
	v_lshlrev_b64 v[90:91], 8, v[90:91]
	v_lshl_add_u64 v[106:107], v[160:161], 0, v[90:91]
	v_cvt_pk_bf16_f32 v90, v78, v79
	v_cvt_pk_bf16_f32 v91, v80, v81
	v_mov_b64_e32 v[216:217], v[90:91]
	v_cvt_pk_bf16_f32 v108, v74, v75
	v_cvt_pk_bf16_f32 v109, v76, v77

; __device__ __forceinline__ unsigned cvt_pk_bf16(float lo, float hi) { unsigned r; asm volatile("v_cvt_pk_bf16_f32 %0, %1, %2" : "=v"(r) : "v"(lo), "v"(hi)); return r; }
;     __device__ __forceinline__ void operator()(const f32x4 (&acc)[2][2][4][2], const Unit& u, int wr, int wc, int fr, int fq) const {
;     ...
;                     } else if (pn <= 4) {
;                         v0 = v0 * QSCALE; v1 = v1 * QSCALE;
;                         bf16_t* p = (pn <= 3) ? QB + (size_t)r * 512 + (pn - 2) * 256 + ctb : QC + (size_t)r * 256 + ctb;
;                         *(u32x2*)p = (u32x2){cvt_pk_bf16(v0[0], v0[1]), cvt_pk_bf16(v0[2], v0[3])}; *(u32x2*)(p + 16) = (u32x2){cvt_pk_bf16(v1[0], v1[1]), cvt_pk_bf16(v1[2], v1[3])};
.LBB0_330:
	s_andn2_b64 vcc, exec, s[18:19]
	s_cbranch_vccnz .LBB0_332
	v_lshl_add_u64 v[114:115], s[8:9], 0, v[92:93]
	s_movk_i32 s18, 0xfc00
	v_lshl_add_u64 v[114:115], s[16:17], 1, v[114:115]
	s_mov_b32 s19, -1
	v_lshl_add_u64 v[106:107], s[0:1], 0, v[94:95]
	v_lshl_add_u64 v[114:115], v[114:115], 0, s[18:19]
	v_pk_mul_f32 v[108:109], v[78:79], s[74:75] op_sel_hi:[1,0]
	v_cndmask_b32_e64 v107, v115, v107, s[42:43]
	v_cndmask_b32_e64 v106, v114, v106, s[42:43]
	v_mov_b32_e32 v169, v1
	v_pk_mul_f32 v[90:91], v[80:81], s[74:75] op_sel_hi:[1,0]
	v_lshl_add_u64 v[106:107], v[106:107], 0, v[168:169]
	v_cvt_pk_bf16_f32 v108, v108, v109
	v_cvt_pk_bf16_f32 v109, v90, v91
	v_pk_mul_f32 v[110:111], v[76:77], s[74:75] op_sel_hi:[1,0]
	v_pk_mul_f32 v[112:113], v[74:75], s[74:75] op_sel_hi:[1,0]
	v_mov_b64_e32 v[216:217], v[108:109]
	v_cvt_pk_bf16_f32 v108, v112, v113
	v_cvt_pk_bf16_f32 v109, v110, v111

;     __device__ __forceinline__ void operator()(const f32x4 (&acc)[2][2][4][2], const Unit& u, int wr, int wc, int fr, int fq) const {
;     ...
;                 for (int bj = 0; bj < 2; ++bj) {
;                     f32x4 v0 = acc[ai][bj][m][0], v1 = acc[ai][bj][m][1];
;                     const bool is_rope = (pn >= 2 && pn <= 6) || (pn == 9 && bj == 0);
;                     if (is_rope && lat) {
;                         const float cs[4] = {c01[0], c01[2], c23[0], c23[2]}, sn[4] = {c01[1], c01[3], c23[1], c23[3]};
; #pragma unroll
;                         for (int i = 0; i < 4; ++i) { const float x0 = v0[i], x1 = v1[i]; v0[i] = x0 * cs[i] - x1 * sn[i]; v1[i] = x1 * cs[i] + x0 * sn[i]; }
;                     }
;                     const int ctb = bj * HALF + wc * 32 + 4 * fq;
;                     if (pn <= 1) {
; #pragma unroll
;                         for (int i = 0; i < 4; ++i) { v0[i] = gelu_tanh_f(v0[i]); v1[i] = gelu_tanh_f(v1[i]); }
;                         bf16_t* p = UV + (size_t)r * 512 + pn * 256 + ctb;
;                         *(u32x2*)p = (u32x2){cvt_pk_bf16(v0[0], v0[1]), cvt_pk_bf16(v0[2], v0[3])}; *(u32x2*)(p + 16) = (u32x2){cvt_pk_bf16(v1[0], v1[1]), cvt_pk_bf16(v1[2], v1[3])};
;                     } else if (pn <= 4) {
;                         v0 = v0 * QSCALE; v1 = v1 * QSCALE;
;                         bf16_t* p = (pn <= 3) ? QB + (size_t)r * 512 + (pn - 2) * 256 + ctb : QC + (size_t)r * 256 + ctb;
;                         *(u32x2*)p = (u32x2){cvt_pk_bf16(v0[0], v0[1]), cvt_pk_bf16(v0[2], v0[3])}; *(u32x2*)(p + 16) = (u32x2){cvt_pk_bf16(v1[0], v1[1]), cvt_pk_bf16(v1[2], v1[3])};
;                     } else if (pn <= 6) {
;                         const int ck = (pn - 5) * 256 + ctb, head = ck >> 7, cw = ck & 127;
;                         bf16_t* p = KB + ((size_t)(b * 4 + head) * NKEY + keyidx) * 128 + cw;
;                         *(u32x2*)p = (u32x2){cvt_pk_bf16(v0[0], v0[1]), cvt_pk_bf16(v0[2], v0[3])}; *(u32x2*)(p + 16) = (u32x2){cvt_pk_bf16(v1[0], v1[1]), cvt_pk_bf16(v1[2], v1[3])};
;                     } else if (pn <= 8) {
;                         const int cv = (pn - 7) * 256 + ctb, head = cv >> 7, e = cv & 127;
;                         bf16_t* p = VBt + ((size_t)(b * 4 + head) * NKEY + keyidx) * 128 + e;
.LBB0_333:
	s_and_b64 vcc, exec, s[50:51]
	v_mov_b64_e32 v[218:219], v[108:109]
	s_nop 1
	v_permlane16_swap_b32_e32 v216, v218
	v_permlane16_swap_b32_e32 v217, v219
	v_lshl_add_u64 v[220:221], v[106:107], 0, v[222:223]
	flat_store_dwordx4 v[220:221], v[216:219]
	s_cbranch_vccnz .LBB0_335

; __device__ __forceinline__ unsigned cvt_pk_bf16(float lo, float hi) { unsigned r; asm volatile("v_cvt_pk_bf16_f32 %0, %1, %2" : "=v"(r) : "v"(lo), "v"(hi)); return r; }
;     __device__ __forceinline__ void operator()(const f32x4 (&acc)[2][2][4][2], const Unit& u, int wr, int wc, int fr, int fq) const {
;     ...
;                     } else if (pn <= 6) {
;                         const int ck = (pn - 5) * 256 + ctb, head = ck >> 7, cw = ck & 127;
;                         bf16_t* p = KB + ((size_t)(b * 4 + head) * NKEY + keyidx) * 128 + cw;
;                         *(u32x2*)p = (u32x2){cvt_pk_bf16(v0[0], v0[1]), cvt_pk_bf16(v0[2], v0[3])}; *(u32x2*)(p + 16) = (u32x2){cvt_pk_bf16(v1[0], v1[1]), cvt_pk_bf16(v1[2], v1[3])};
;                     } else if (pn <= 8) {
;                         const int cv = (pn - 7) * 256 + ctb, head = cv >> 7, e = cv & 127;
;                         bf16_t* p = VBt + ((size_t)(b * 4 + head) * NKEY + keyidx) * 128 + e;
;                         *(u32x2*)p = (u32x2){cvt_pk_bf16(v0[0], v0[1]), cvt_pk_bf16(v0[2], v0[3])}; *(u32x2*)(p + 16) = (u32x2){cvt_pk_bf16(v1[0], v1[1]), cvt_pk_bf16(v1[2], v1[3])};
;                     } else {
;                         const int kv = wc >> 1, d = (wc & 1) * 32 + 4 * fq;
;                         if (bj == 0) {
;                             bf16_t* p = KC + ((size_t)(b * 2 + kv) * NKEY + keyidx) * 64 + d;
;                             *(u32x2*)p = (u32x2){cvt_pk_bf16(v0[0], v0[1]), cvt_pk_bf16(v0[2], v0[3])}; *(u32x2*)(p + 16) = (u32x2){cvt_pk_bf16(v1[0], v1[1]), cvt_pk_bf16(v1[2], v1[3])};
;                         } else {
;                             bf16_t* p = VCt + ((size_t)(b * 2 + kv) * NKEY + keyidx) * 64 + d;
;                             *(u32x2*)p = (u32x2){cvt_pk_bf16(v0[0], v0[1]), cvt_pk_bf16(v0[2], v0[3])}; *(u32x2*)(p + 16) = (u32x2){cvt_pk_bf16(v1[0], v1[1]), cvt_pk_bf16(v1[2], v1[3])};
;                         }
;                     }
.LBB0_335:
	s_and_b64 vcc, exec, s[52:53]
	s_mov_b64 s[18:19], -1
	s_cbranch_vccnz .LBB0_351
	s_and_b64 vcc, exec, s[48:49]
	s_cbranch_vccnz .LBB0_346
	s_andn2_b64 vcc, exec, s[12:13]
	s_cbranch_vccnz .LBB0_343
	s_andn2_b64 vcc, exec, s[22:23]
	s_cbranch_vccnz .LBB0_340
	v_lshl_add_u64 v[74:75], v[162:163], 0, v[96:97]
	v_cvt_pk_bf16_f32 v76, v70, v71
	v_cvt_pk_bf16_f32 v77, v72, v73
	s_mov_b64 s[18:19], 0
	v_mov_b64_e32 v[216:217], v[76:77]
	v_cvt_pk_bf16_f32 v76, v66, v67
	v_cvt_pk_bf16_f32 v77, v68, v69
.LBB0_340:
	s_andn2_b64 vcc, exec, s[18:19]
	s_cbranch_vccnz .LBB0_342
	s_add_i32 s15, s20, 0xfffff980
	s_ashr_i32 s15, s15, 7
	s_add_i32 s14, s14, s15
	v_mad_i64_i32 v[74:75], s[14:15], s14, v196, v[0:1]
	v_lshlrev_b64 v[74:75], 8, v[74:75]
	v_lshl_add_u64 v[74:75], v[156:157], 0, v[74:75]
	v_cvt_pk_bf16_f32 v76, v70, v71
	v_cvt_pk_bf16_f32 v77, v72, v73
	v_mov_b64_e32 v[216:217], v[76:77]
	v_cvt_pk_bf16_f32 v76, v66, v67
	v_cvt_pk_bf16_f32 v77, v68, v69

; __device__ __forceinline__ unsigned cvt_pk_bf16(float lo, float hi) { unsigned r; asm volatile("v_cvt_pk_bf16_f32 %0, %1, %2" : "=v"(r) : "v"(lo), "v"(hi)); return r; }
;     __device__ __forceinline__ void operator()(const f32x4 (&acc)[2][2][4][2], const Unit& u, int wr, int wc, int fr, int fq) const {
;     ...
;                     } else if (pn <= 8) {
;                         const int cv = (pn - 7) * 256 + ctb, head = cv >> 7, e = cv & 127;
;                         bf16_t* p = VBt + ((size_t)(b * 4 + head) * NKEY + keyidx) * 128 + e;
;                         *(u32x2*)p = (u32x2){cvt_pk_bf16(v0[0], v0[1]), cvt_pk_bf16(v0[2], v0[3])}; *(u32x2*)(p + 16) = (u32x2){cvt_pk_bf16(v1[0], v1[1]), cvt_pk_bf16(v1[2], v1[3])};
.LBB0_343:
	s_andn2_b64 vcc, exec, s[18:19]
	s_cbranch_vccnz .LBB0_345
	s_or_b32 s3, s3, 1
	v_mad_i64_i32 v[74:75], s[14:15], s3, v196, v[0:1]
	v_lshlrev_b64 v[74:75], 8, v[74:75]
	v_lshl_add_u64 v[74:75], v[160:161], 0, v[74:75]
	v_cvt_pk_bf16_f32 v76, v70, v71
	v_cvt_pk_bf16_f32 v77, v72, v73
	v_mov_b64_e32 v[216:217], v[76:77]
	v_cvt_pk_bf16_f32 v76, v66, v67
	v_cvt_pk_bf16_f32 v77, v68, v69

; __device__ __forceinline__ unsigned cvt_pk_bf16(float lo, float hi) { unsigned r; asm volatile("v_cvt_pk_bf16_f32 %0, %1, %2" : "=v"(r) : "v"(lo), "v"(hi)); return r; }
;     __device__ __forceinline__ void operator()(const f32x4 (&acc)[2][2][4][2], const Unit& u, int wr, int wc, int fr, int fq) const {
;     ...
;                     } else if (pn <= 4) {
;                         v0 = v0 * QSCALE; v1 = v1 * QSCALE;
;                         bf16_t* p = (pn <= 3) ? QB + (size_t)r * 512 + (pn - 2) * 256 + ctb : QC + (size_t)r * 256 + ctb;
;                         *(u32x2*)p = (u32x2){cvt_pk_bf16(v0[0], v0[1]), cvt_pk_bf16(v0[2], v0[3])}; *(u32x2*)(p + 16) = (u32x2){cvt_pk_bf16(v1[0], v1[1]), cvt_pk_bf16(v1[2], v1[3])};
.LBB0_346:
	s_andn2_b64 vcc, exec, s[18:19]
	s_cbranch_vccnz .LBB0_348
	v_lshl_add_u64 v[92:93], s[8:9], 0, v[92:93]
	s_movk_i32 s14, 0xfc00
	v_lshl_add_u64 v[92:93], s[16:17], 1, v[92:93]
	s_mov_b32 s15, -1
	v_lshl_add_u64 v[74:75], s[0:1], 0, v[94:95]
	v_lshl_add_u64 v[92:93], v[92:93], 0, s[14:15]
	v_cndmask_b32_e64 v75, v93, v75, s[42:43]
	v_cndmask_b32_e64 v74, v92, v74, s[42:43]
	v_mov_b32_e32 v169, v1
	v_lshl_add_u64 v[92:93], v[74:75], 0, v[168:169]
	v_pk_mul_f32 v[76:77], v[72:73], s[74:75] op_sel_hi:[1,0]
	v_pk_mul_f32 v[78:79], v[70:71], s[74:75] op_sel_hi:[1,0]
	v_lshl_add_u64 v[74:75], v[92:93], 0, s[60:61]
	v_pk_mul_f32 v[80:81], v[68:69], s[74:75] op_sel_hi:[1,0]
	v_pk_mul_f32 v[96:97], v[66:67], s[74:75] op_sel_hi:[1,0]
	v_cvt_pk_bf16_f32 v78, v78, v79
	v_cvt_pk_bf16_f32 v79, v76, v77
	v_mov_b64_e32 v[216:217], v[78:79]
	v_cvt_pk_bf16_f32 v76, v96, v97
	v_cvt_pk_bf16_f32 v77, v80, v81

; __device__ __forceinline__ unsigned cvt_pk_bf16(float lo, float hi) { unsigned r; asm volatile("v_cvt_pk_bf16_f32 %0, %1, %2" : "=v"(r) : "v"(lo), "v"(hi)); return r; }
; __device__ __forceinline__ float gelu_tanh_f(float x) { const float y = 1.5957691216057308f * (x + 0.044715f * x * x * x); return x * __builtin_amdgcn_rcpf(1.f + __expf(-y)); }
;     __device__ __forceinline__ void operator()(const f32x4 (&acc)[2][2][4][2], const Unit& u, int wr, int wc, int fr, int fq) const {
;     ...
;                     if (pn <= 1) {
; #pragma unroll
;                         for (int i = 0; i < 4; ++i) { v0[i] = gelu_tanh_f(v0[i]); v1[i] = gelu_tanh_f(v1[i]); }
;                         bf16_t* p = UV + (size_t)r * 512 + pn * 256 + ctb;
;                         *(u32x2*)p = (u32x2){cvt_pk_bf16(v0[0], v0[1]), cvt_pk_bf16(v0[2], v0[3])}; *(u32x2*)(p + 16) = (u32x2){cvt_pk_bf16(v1[0], v1[1]), cvt_pk_bf16(v1[2], v1[3])};
.LBB0_350:
	v_mul_f32_e32 v106, 0x3d372713, v78
	v_mul_f32_e32 v106, v78, v106
	v_fma_f32 v106, v78, v106, v78
	v_mul_f32_e32 v106, 0xbfcc422a, v106
	v_mul_f32_e32 v106, 0x3fb8aa3b, v106
	v_exp_f32_e32 v106, v106
	v_mov_b32_e32 v169, v1
	v_add_f32_e32 v106, 1.0, v106
	v_rcp_f32_e32 v106, v106
	s_nop 0
	v_mul_f32_e32 v78, v78, v106
	v_mul_f32_e32 v106, 0x3d372713, v74
	v_mul_f32_e32 v106, v74, v106
	v_fma_f32 v106, v74, v106, v74
	v_mul_f32_e32 v106, 0xbfcc422a, v106
	v_mul_f32_e32 v106, 0x3fb8aa3b, v106
	v_exp_f32_e32 v106, v106
	s_nop 0
	v_add_f32_e32 v106, 1.0, v106
	v_rcp_f32_e32 v106, v106
	s_nop 0
	v_mul_f32_e32 v108, v74, v106
	v_mul_f32_e32 v74, 0x3d372713, v79
	v_mul_f32_e32 v74, v79, v74
	v_fma_f32 v74, v79, v74, v79
	v_mul_f32_e32 v74, 0xbfcc422a, v74
	v_mul_f32_e32 v74, 0x3fb8aa3b, v74
	v_exp_f32_e32 v74, v74
	v_lshl_add_u64 v[106:107], v[90:91], 0, v[168:169]
	v_add_f32_e32 v74, 1.0, v74
	v_rcp_f32_e32 v74, v74
	s_nop 0
	v_mul_f32_e32 v74, v79, v74
	v_mul_f32_e32 v79, 0x3d372713, v75
	v_mul_f32_e32 v79, v75, v79
	v_fma_f32 v79, v75, v79, v75
	v_mul_f32_e32 v79, 0xbfcc422a, v79
	v_mul_f32_e32 v79, 0x3fb8aa3b, v79
	v_exp_f32_e32 v79, v79
	v_cvt_pk_bf16_f32 v74, v78, v74
	s_nop 0
	v_add_f32_e32 v79, 1.0, v79
	v_rcp_f32_e32 v79, v79
	s_nop 0
	v_mul_f32_e32 v79, v75, v79
	v_mul_f32_e32 v75, 0x3d372713, v80
	v_mul_f32_e32 v75, v80, v75
	v_fma_f32 v75, v80, v75, v80
	v_mul_f32_e32 v75, 0xbfcc422a, v75
	v_mul_f32_e32 v75, 0x3fb8aa3b, v75
	v_exp_f32_e32 v75, v75
	s_nop 0
	v_add_f32_e32 v75, 1.0, v75
	v_rcp_f32_e32 v75, v75
	s_nop 0
	v_mul_f32_e32 v75, v80, v75
	v_mul_f32_e32 v80, 0x3d372713, v76
	v_mul_f32_e32 v80, v76, v80
	v_fma_f32 v80, v76, v80, v76
	v_mul_f32_e32 v80, 0xbfcc422a, v80
	v_mul_f32_e32 v80, 0x3fb8aa3b, v80
	v_exp_f32_e32 v80, v80
	s_nop 0
	v_add_f32_e32 v80, 1.0, v80
	v_rcp_f32_e32 v80, v80
	s_nop 0
	v_mul_f32_e32 v76, v76, v80
	v_mul_f32_e32 v80, 0x3d372713, v81
	v_mul_f32_e32 v80, v81, v80
	v_fma_f32 v80, v81, v80, v81
	v_mul_f32_e32 v80, 0xbfcc422a, v80
	v_mul_f32_e32 v80, 0x3fb8aa3b, v80
	v_exp_f32_e32 v80, v80
	s_nop 0
	v_add_f32_e32 v80, 1.0, v80
	v_rcp_f32_e32 v80, v80
	s_nop 0
	v_mul_f32_e32 v80, v81, v80
	v_mul_f32_e32 v81, 0x3d372713, v77
	v_mul_f32_e32 v81, v77, v81
	v_fma_f32 v81, v77, v81, v77
	v_mul_f32_e32 v81, 0xbfcc422a, v81
	v_mul_f32_e32 v81, 0x3fb8aa3b, v81
	v_exp_f32_e32 v81, v81
	v_cvt_pk_bf16_f32 v75, v75, v80
	v_mov_b64_e32 v[216:217], v[74:75]
	v_cvt_pk_bf16_f32 v108, v108, v79
	v_add_f32_e32 v81, 1.0, v81
	v_rcp_f32_e32 v81, v81
	s_nop 0
	v_mul_f32_e32 v77, v77, v81
	v_cvt_pk_bf16_f32 v109, v76, v77
	s_and_b64 vcc, exec, s[50:51]
	v_mov_b64_e32 v[218:219], v[108:109]
	s_nop 1
	v_permlane16_swap_b32_e32 v216, v218
	v_permlane16_swap_b32_e32 v217, v219
	v_lshl_add_u64 v[220:221], v[106:107], 0, v[222:223]
	flat_store_dwordx4 v[220:221], v[216:219]
	s_cbranch_vccnz .LBB0_335
	s_branch .LBB0_334

; __device__ __forceinline__ unsigned cvt_pk_bf16(float lo, float hi) { unsigned r; asm volatile("v_cvt_pk_bf16_f32 %0, %1, %2" : "=v"(r) : "v"(lo), "v"(hi)); return r; }
; __device__ __forceinline__ float gelu_tanh_f(float x) { const float y = 1.5957691216057308f * (x + 0.044715f * x * x * x); return x * __builtin_amdgcn_rcpf(1.f + __expf(-y)); }
; #define ROPE_FETCH(ai_, m_) do { const int s_ = (u.pm * BM + (ai_) * HALF + wr * 64 + (m_) * 16 + fr) & 2047, pos_ = (wc & 1) ? (s_ & 63) : (s_ >> 6); \
;             n01 = *(const f32x4*)(rope + pos_ * 16 + 4 * fq); n23 = *(const f32x4*)(rope + pos_ * 16 + 4 * fq + 2); } while (0)
;     __device__ __forceinline__ void operator()(const f32x4 (&acc)[2][2][4][2], const Unit& u, int wr, int wc, int fr, int fq) const {
;     ...
;         if (do_rope) ROPE_FETCH(0, 0);
; #pragma unroll
;         for (int ai = 0; ai < 2; ++ai)
; #pragma unroll
;             for (int m = 0; m < 4; ++m) {
;                 const f32x4 c01 = n01, c23 = n23;
;                 if (do_rope && (ai * 4 + m) < 7) ROPE_FETCH((ai * 4 + m + 1) >> 2, (ai * 4 + m + 1) & 3);
;     ...
;                     if (pn <= 1) {
; #pragma unroll
;                         for (int i = 0; i < 4; ++i) { v0[i] = gelu_tanh_f(v0[i]); v1[i] = gelu_tanh_f(v1[i]); }
;                         bf16_t* p = UV + (size_t)r * 512 + pn * 256 + ctb;
;                         *(u32x2*)p = (u32x2){cvt_pk_bf16(v0[0], v0[1]), cvt_pk_bf16(v0[2], v0[3])}; *(u32x2*)(p + 16) = (u32x2){cvt_pk_bf16(v1[0], v1[1]), cvt_pk_bf16(v1[2], v1[3])};
.LBB0_352:
	v_mul_f32_e32 v0, 0x3d372713, v70
	v_mul_f32_e32 v0, v70, v0
	v_fma_f32 v0, v70, v0, v70
	v_mul_f32_e32 v0, 0xbfcc422a, v0
	v_mul_f32_e32 v0, 0x3fb8aa3b, v0
	v_exp_f32_e32 v0, v0
	v_mov_b32_e32 v169, v1
	v_add_f32_e32 v0, 1.0, v0
	v_rcp_f32_e32 v0, v0
	s_nop 0
	v_mul_f32_e32 v0, v70, v0
	v_mul_f32_e32 v70, 0x3d372713, v66
	v_mul_f32_e32 v70, v66, v70
	v_fma_f32 v70, v66, v70, v66
	v_mul_f32_e32 v70, 0xbfcc422a, v70
	v_mul_f32_e32 v70, 0x3fb8aa3b, v70
	v_exp_f32_e32 v70, v70
	s_nop 0
	v_add_f32_e32 v70, 1.0, v70
	v_rcp_f32_e32 v70, v70
	s_nop 0
	v_mul_f32_e32 v70, v66, v70
	v_mul_f32_e32 v66, 0x3d372713, v71
	v_mul_f32_e32 v66, v71, v66
	v_fma_f32 v66, v71, v66, v71
	v_mul_f32_e32 v66, 0xbfcc422a, v66
	v_mul_f32_e32 v66, 0x3fb8aa3b, v66
	v_exp_f32_e32 v66, v66
	s_nop 0
	v_add_f32_e32 v66, 1.0, v66
	v_rcp_f32_e32 v66, v66
	s_nop 0
	v_mul_f32_e32 v71, v71, v66
	v_mul_f32_e32 v66, 0x3d372713, v67
	v_mul_f32_e32 v66, v67, v66
	v_fma_f32 v66, v67, v66, v67
	v_mul_f32_e32 v66, 0xbfcc422a, v66
	v_mul_f32_e32 v66, 0x3fb8aa3b, v66
	v_exp_f32_e32 v66, v66
	s_nop 0
	v_add_f32_e32 v66, 1.0, v66
	v_rcp_f32_e32 v66, v66
	s_nop 0
	v_mul_f32_e32 v76, v67, v66
	v_mul_f32_e32 v66, 0x3d372713, v72
	v_mul_f32_e32 v66, v72, v66
	v_fma_f32 v66, v72, v66, v72
	v_mul_f32_e32 v66, 0xbfcc422a, v66
	v_mul_f32_e32 v66, 0x3fb8aa3b, v66
	v_exp_f32_e32 v66, v66
	s_nop 0
	v_add_f32_e32 v66, 1.0, v66
	v_rcp_f32_e32 v66, v66
	s_nop 0
	v_mul_f32_e32 v72, v72, v66
	v_mul_f32_e32 v66, 0x3d372713, v68
	v_mul_f32_e32 v66, v68, v66
	v_fma_f32 v66, v68, v66, v68
	v_mul_f32_e32 v66, 0xbfcc422a, v66
	v_mul_f32_e32 v66, 0x3fb8aa3b, v66
	v_exp_f32_e32 v66, v66
	s_nop 0
	v_add_f32_e32 v66, 1.0, v66
	v_rcp_f32_e32 v66, v66
	s_nop 0
	v_mul_f32_e32 v77, v68, v66
	v_mul_f32_e32 v66, 0x3d372713, v73
	v_mul_f32_e32 v66, v73, v66
	v_fma_f32 v66, v73, v66, v73
	v_mul_f32_e32 v66, 0xbfcc422a, v66
	v_mul_f32_e32 v66, 0x3fb8aa3b, v66
	v_exp_f32_e32 v66, v66
	v_cvt_pk_bf16_f32 v68, v0, v71
	s_nop 0
	v_add_f32_e32 v66, 1.0, v66
	v_rcp_f32_e32 v66, v66
	s_nop 0
	v_mul_f32_e32 v73, v73, v66
	v_mul_f32_e32 v66, 0x3d372713, v69
	v_mul_f32_e32 v66, v69, v66
	v_fma_f32 v66, v69, v66, v69
	v_mul_f32_e32 v66, 0xbfcc422a, v66
	v_mul_f32_e32 v66, 0x3fb8aa3b, v66
	v_exp_f32_e32 v66, v66
	s_nop 0
	v_add_f32_e32 v66, 1.0, v66
	v_rcp_f32_e32 v66, v66
	s_nop 0
	v_mul_f32_e32 v78, v69, v66
	v_lshl_add_u64 v[66:67], v[90:91], 0, v[168:169]
	v_lshl_add_u64 v[74:75], v[66:67], 0, s[60:61]
	v_cvt_pk_bf16_f32 v69, v72, v73
	v_mov_b64_e32 v[216:217], v[68:69]
	v_cvt_pk_bf16_f32 v76, v70, v76
	v_cvt_pk_bf16_f32 v77, v77, v78
.LBB0_353:
	v_mov_b64_e32 v[218:219], v[76:77]
	s_nop 1
	v_permlane16_swap_b32_e32 v216, v218
	v_permlane16_swap_b32_e32 v217, v219
	v_lshl_add_u64 v[220:221], v[74:75], 0, v[222:223]
	flat_store_dwordx4 v[220:221], v[216:219]
	s_waitcnt vmcnt(0) lgkmcnt(0)
	v_mov_b64_e32 v[70:71], v[86:87]
	v_mov_b64_e32 v[66:67], v[82:83]
	s_and_b64 vcc, exec, s[54:55]
	v_mov_b64_e32 v[72:73], v[88:89]
	v_mov_b64_e32 v[68:69], v[84:85]
	s_cbranch_vccnz .LBB0_355
	s_lshr_b32 s3, s29, 6
	v_readlane_b32 s14, v255, 14
	s_add_i32 s3, s3, s14
	s_and_b32 s3, s3, 31
	v_mov_b32_e32 v0, s3
	v_cndmask_b32_e64 v0, v208, v0, s[38:39]
	v_lshlrev_b32_e32 v0, 7, v0
	v_lshl_add_u64 v[70:71], v[152:153], 0, v[0:1]
	flat_load_dwordx4 v[66:69], v[70:71]
	s_nop 0
	flat_load_dwordx4 v[70:73], v[70:71] offset:16

;     __device__ __forceinline__ void operator()(const f32x4 (&acc)[2][2][4][2], const Unit& u, int wr, int wc, int fr, int fq) const {
;     ...
;                 const int r = u.pm * BM + ai * HALF + wr * 64 + m * 16 + fr;
;                 int b, s, keyidx;
;                 if (lat) { b = r >> 11; s = r & 2047; keyidx = CTXL + s; } else { const int rc = r - T_LAT; b = rc >> 8; s = 0; keyidx = rc & 255; }
; #pragma unroll
;                 for (int bj = 0; bj < 2; ++bj) {
;                     f32x4 v0 = acc[ai][bj][m][0], v1 = acc[ai][bj][m][1];
;                     const bool is_rope = (pn >= 2 && pn <= 6) || (pn == 9 && bj == 0);
;                     if (is_rope && lat) {
;                         const float cs[4] = {c01[0], c01[2], c23[0], c23[2]}, sn[4] = {c01[1], c01[3], c23[1], c23[3]};
; #pragma unroll
;                         for (int i = 0; i < 4; ++i) { const float x0 = v0[i], x1 = v1[i]; v0[i] = x0 * cs[i] - x1 * sn[i]; v1[i] = x1 * cs[i] + x0 * sn[i]; }
;                     }
;                     const int ctb = bj * HALF + wc * 32 + 4 * fq;
;                     if (pn <= 1) {
; #pragma unroll
;                         for (int i = 0; i < 4; ++i) { v0[i] = gelu_tanh_f(v0[i]); v1[i] = gelu_tanh_f(v1[i]); }
;                         bf16_t* p = UV + (size_t)r * 512 + pn * 256 + ctb;
;                         *(u32x2*)p = (u32x2){cvt_pk_bf16(v0[0], v0[1]), cvt_pk_bf16(v0[2], v0[3])}; *(u32x2*)(p + 16) = (u32x2){cvt_pk_bf16(v1[0], v1[1]), cvt_pk_bf16(v1[2], v1[3])};
;                     } else if (pn <= 4) {
;                         v0 = v0 * QSCALE; v1 = v1 * QSCALE;
;                         bf16_t* p = (pn <= 3) ? QB + (size_t)r * 512 + (pn - 2) * 256 + ctb : QC + (size_t)r * 256 + ctb;
;                         *(u32x2*)p = (u32x2){cvt_pk_bf16(v0[0], v0[1]), cvt_pk_bf16(v0[2], v0[3])}; *(u32x2*)(p + 16) = (u32x2){cvt_pk_bf16(v1[0], v1[1]), cvt_pk_bf16(v1[2], v1[3])};
;                     } else if (pn <= 6) {
;                         const int ck = (pn - 5) * 256 + ctb, head = ck >> 7, cw = ck & 127;
;                         bf16_t* p = KB + ((size_t)(b * 4 + head) * NKEY + keyidx) * 128 + cw;
;                         *(u32x2*)p = (u32x2){cvt_pk_bf16(v0[0], v0[1]), cvt_pk_bf16(v0[2], v0[3])}; *(u32x2*)(p + 16) = (u32x2){cvt_pk_bf16(v1[0], v1[1]), cvt_pk_bf16(v1[2], v1[3])};
;                     } else if (pn <= 8) {
.LBB0_357:
	s_add_i32 s3, s26, 0x80
	s_addk_i32 s26, 0xc080
	s_ashr_i32 s18, s26, 8
	s_ashr_i32 s19, s3, 11
	s_and_b64 s[14:15], s[44:45], exec
	v_or_b32_e32 v74, s3, v151
	v_bitop3_b32 v0, s3, v194, v151 bitop3:0xc8
	v_bitop3_b32 v75, s3, v195, v151 bitop3:0xc8
	s_cselect_b32 s3, s19, s18
	v_add_u32_e32 v0, 0x100, v0
	s_lshl_b32 s14, s3, 1
	v_readlane_b32 s15, v255, 13
	v_cndmask_b32_e64 v0, v75, v0, s[44:45]
	s_or_b32 s15, s14, s15
	v_mad_i64_i32 v[76:77], s[18:19], s15, v196, v[0:1]
	s_lshl_b32 s14, s3, 2
	v_ashrrev_i32_e32 v75, 31, v74
	v_lshlrev_b64 v[90:91], 7, v[76:77]
	s_add_i32 s3, s14, s25
	v_lshlrev_b64 v[78:79], 10, v[74:75]
	v_lshlrev_b64 v[80:81], 9, v[74:75]
	s_and_b64 vcc, exec, s[52:53]
	s_mov_b64 s[18:19], -1
	s_cbranch_vccnz .LBB0_387
	s_and_b64 vcc, exec, s[48:49]
	s_cbranch_vccnz .LBB0_368
	s_andn2_b64 vcc, exec, s[12:13]
	s_cbranch_vccnz .LBB0_365
	s_andn2_b64 vcc, exec, s[22:23]
	s_cbranch_vccnz .LBB0_362
	v_lshl_add_u64 v[92:93], v[154:155], 0, v[90:91]
	s_mov_b64 s[18:19], 0
	v_cvt_pk_bf16_f32 v76, v62, v63
	v_cvt_pk_bf16_f32 v77, v64, v65
	v_mov_b64_e32 v[216:217], v[76:77]
	v_cvt_pk_bf16_f32 v94, v58, v59
	v_cvt_pk_bf16_f32 v95, v60, v61
.LBB0_362:
	s_andn2_b64 vcc, exec, s[18:19]
	s_cbranch_vccnz .LBB0_364
	v_readlane_b32 s18, v255, 17
	s_ashr_i32 s18, s18, 7
	s_add_i32 s18, s14, s18
	v_mad_i64_i32 v[76:77], s[18:19], s18, v196, v[0:1]
	v_lshlrev_b64 v[76:77], 8, v[76:77]
	v_lshl_add_u64 v[92:93], v[156:157], 0, v[76:77]
	v_cvt_pk_bf16_f32 v76, v62, v63
	v_cvt_pk_bf16_f32 v77, v64, v65
	v_mov_b64_e32 v[216:217], v[76:77]
	v_cvt_pk_bf16_f32 v94, v58, v59
	v_cvt_pk_bf16_f32 v95, v60, v61

; __device__ __forceinline__ unsigned cvt_pk_bf16(float lo, float hi) { unsigned r; asm volatile("v_cvt_pk_bf16_f32 %0, %1, %2" : "=v"(r) : "v"(lo), "v"(hi)); return r; }
;     __device__ __forceinline__ void operator()(const f32x4 (&acc)[2][2][4][2], const Unit& u, int wr, int wc, int fr, int fq) const {
;     ...
;                     } else if (pn <= 8) {
;                         const int cv = (pn - 7) * 256 + ctb, head = cv >> 7, e = cv & 127;
;                         bf16_t* p = VBt + ((size_t)(b * 4 + head) * NKEY + keyidx) * 128 + e;
;                         *(u32x2*)p = (u32x2){cvt_pk_bf16(v0[0], v0[1]), cvt_pk_bf16(v0[2], v0[3])}; *(u32x2*)(p + 16) = (u32x2){cvt_pk_bf16(v1[0], v1[1]), cvt_pk_bf16(v1[2], v1[3])};
.LBB0_365:
	s_andn2_b64 vcc, exec, s[18:19]
	s_cbranch_vccnz .LBB0_367
	v_mad_i64_i32 v[76:77], s[18:19], s3, v196, v[0:1]
	v_lshlrev_b64 v[76:77], 8, v[76:77]
	v_lshl_add_u64 v[92:93], v[160:161], 0, v[76:77]
	v_cvt_pk_bf16_f32 v76, v62, v63
	v_cvt_pk_bf16_f32 v77, v64, v65
	v_mov_b64_e32 v[216:217], v[76:77]
	v_cvt_pk_bf16_f32 v94, v58, v59
	v_cvt_pk_bf16_f32 v95, v60, v61

; __device__ __forceinline__ unsigned cvt_pk_bf16(float lo, float hi) { unsigned r; asm volatile("v_cvt_pk_bf16_f32 %0, %1, %2" : "=v"(r) : "v"(lo), "v"(hi)); return r; }
;     __device__ __forceinline__ void operator()(const f32x4 (&acc)[2][2][4][2], const Unit& u, int wr, int wc, int fr, int fq) const {
;     ...
;                     } else if (pn <= 4) {
;                         v0 = v0 * QSCALE; v1 = v1 * QSCALE;
;                         bf16_t* p = (pn <= 3) ? QB + (size_t)r * 512 + (pn - 2) * 256 + ctb : QC + (size_t)r * 256 + ctb;
;                         *(u32x2*)p = (u32x2){cvt_pk_bf16(v0[0], v0[1]), cvt_pk_bf16(v0[2], v0[3])}; *(u32x2*)(p + 16) = (u32x2){cvt_pk_bf16(v1[0], v1[1]), cvt_pk_bf16(v1[2], v1[3])};
.LBB0_368:
	s_andn2_b64 vcc, exec, s[18:19]
	s_cbranch_vccnz .LBB0_370
	v_lshl_add_u64 v[100:101], s[8:9], 0, v[78:79]
	s_movk_i32 s18, 0xfc00
	v_lshl_add_u64 v[100:101], s[16:17], 1, v[100:101]
	s_mov_b32 s19, -1
	v_lshl_add_u64 v[92:93], s[0:1], 0, v[80:81]
	v_lshl_add_u64 v[100:101], v[100:101], 0, s[18:19]
	v_pk_mul_f32 v[94:95], v[62:63], s[74:75] op_sel_hi:[1,0]
	v_cndmask_b32_e64 v93, v101, v93, s[42:43]
	v_cndmask_b32_e64 v92, v100, v92, s[42:43]
	v_mov_b32_e32 v169, v1
	v_pk_mul_f32 v[76:77], v[64:65], s[74:75] op_sel_hi:[1,0]
	v_lshl_add_u64 v[92:93], v[92:93], 0, v[168:169]
	v_cvt_pk_bf16_f32 v94, v94, v95
	v_cvt_pk_bf16_f32 v95, v76, v77
	v_pk_mul_f32 v[96:97], v[60:61], s[74:75] op_sel_hi:[1,0]
	v_pk_mul_f32 v[98:99], v[58:59], s[74:75] op_sel_hi:[1,0]
	v_mov_b64_e32 v[216:217], v[94:95]
	v_cvt_pk_bf16_f32 v94, v98, v99
	v_cvt_pk_bf16_f32 v95, v96, v97

;     __device__ __forceinline__ void operator()(const f32x4 (&acc)[2][2][4][2], const Unit& u, int wr, int wc, int fr, int fq) const {
;     ...
;                 for (int bj = 0; bj < 2; ++bj) {
;                     f32x4 v0 = acc[ai][bj][m][0], v1 = acc[ai][bj][m][1];
;                     const bool is_rope = (pn >= 2 && pn <= 6) || (pn == 9 && bj == 0);
;                     if (is_rope && lat) {
;                         const float cs[4] = {c01[0], c01[2], c23[0], c23[2]}, sn[4] = {c01[1], c01[3], c23[1], c23[3]};
; #pragma unroll
;                         for (int i = 0; i < 4; ++i) { const float x0 = v0[i], x1 = v1[i]; v0[i] = x0 * cs[i] - x1 * sn[i]; v1[i] = x1 * cs[i] + x0 * sn[i]; }
;                     }
;                     const int ctb = bj * HALF + wc * 32 + 4 * fq;
;                     if (pn <= 1) {
; #pragma unroll
;                         for (int i = 0; i < 4; ++i) { v0[i] = gelu_tanh_f(v0[i]); v1[i] = gelu_tanh_f(v1[i]); }
;                         bf16_t* p = UV + (size_t)r * 512 + pn * 256 + ctb;
;                         *(u32x2*)p = (u32x2){cvt_pk_bf16(v0[0], v0[1]), cvt_pk_bf16(v0[2], v0[3])}; *(u32x2*)(p + 16) = (u32x2){cvt_pk_bf16(v1[0], v1[1]), cvt_pk_bf16(v1[2], v1[3])};
;                     } else if (pn <= 4) {
;                         v0 = v0 * QSCALE; v1 = v1 * QSCALE;
;                         bf16_t* p = (pn <= 3) ? QB + (size_t)r * 512 + (pn - 2) * 256 + ctb : QC + (size_t)r * 256 + ctb;
;                         *(u32x2*)p = (u32x2){cvt_pk_bf16(v0[0], v0[1]), cvt_pk_bf16(v0[2], v0[3])}; *(u32x2*)(p + 16) = (u32x2){cvt_pk_bf16(v1[0], v1[1]), cvt_pk_bf16(v1[2], v1[3])};
;                     } else if (pn <= 6) {
;                         const int ck = (pn - 5) * 256 + ctb, head = ck >> 7, cw = ck & 127;
;                         bf16_t* p = KB + ((size_t)(b * 4 + head) * NKEY + keyidx) * 128 + cw;
;                         *(u32x2*)p = (u32x2){cvt_pk_bf16(v0[0], v0[1]), cvt_pk_bf16(v0[2], v0[3])}; *(u32x2*)(p + 16) = (u32x2){cvt_pk_bf16(v1[0], v1[1]), cvt_pk_bf16(v1[2], v1[3])};
;                     } else if (pn <= 8) {
;                         const int cv = (pn - 7) * 256 + ctb, head = cv >> 7, e = cv & 127;
;                         bf16_t* p = VBt + ((size_t)(b * 4 + head) * NKEY + keyidx) * 128 + e;
.LBB0_371:
	s_and_b64 vcc, exec, s[50:51]
	v_mov_b64_e32 v[218:219], v[94:95]
	s_nop 1
	v_permlane16_swap_b32_e32 v216, v218
	v_permlane16_swap_b32_e32 v217, v219
	v_lshl_add_u64 v[220:221], v[92:93], 0, v[222:223]
	flat_store_dwordx4 v[220:221], v[216:219]
	s_cbranch_vccnz .LBB0_373

; __device__ __forceinline__ unsigned cvt_pk_bf16(float lo, float hi) { unsigned r; asm volatile("v_cvt_pk_bf16_f32 %0, %1, %2" : "=v"(r) : "v"(lo), "v"(hi)); return r; }
;     __device__ __forceinline__ void operator()(const f32x4 (&acc)[2][2][4][2], const Unit& u, int wr, int wc, int fr, int fq) const {
;     ...
;                     } else if (pn <= 6) {
;                         const int ck = (pn - 5) * 256 + ctb, head = ck >> 7, cw = ck & 127;
;                         bf16_t* p = KB + ((size_t)(b * 4 + head) * NKEY + keyidx) * 128 + cw;
;                         *(u32x2*)p = (u32x2){cvt_pk_bf16(v0[0], v0[1]), cvt_pk_bf16(v0[2], v0[3])}; *(u32x2*)(p + 16) = (u32x2){cvt_pk_bf16(v1[0], v1[1]), cvt_pk_bf16(v1[2], v1[3])};
;                     } else if (pn <= 8) {
;                         const int cv = (pn - 7) * 256 + ctb, head = cv >> 7, e = cv & 127;
;                         bf16_t* p = VBt + ((size_t)(b * 4 + head) * NKEY + keyidx) * 128 + e;
;                         *(u32x2*)p = (u32x2){cvt_pk_bf16(v0[0], v0[1]), cvt_pk_bf16(v0[2], v0[3])}; *(u32x2*)(p + 16) = (u32x2){cvt_pk_bf16(v1[0], v1[1]), cvt_pk_bf16(v1[2], v1[3])};
;                     } else {
;                         const int kv = wc >> 1, d = (wc & 1) * 32 + 4 * fq;
;                         if (bj == 0) {
;                             bf16_t* p = KC + ((size_t)(b * 2 + kv) * NKEY + keyidx) * 64 + d;
;                             *(u32x2*)p = (u32x2){cvt_pk_bf16(v0[0], v0[1]), cvt_pk_bf16(v0[2], v0[3])}; *(u32x2*)(p + 16) = (u32x2){cvt_pk_bf16(v1[0], v1[1]), cvt_pk_bf16(v1[2], v1[3])};
;                         } else {
;                             bf16_t* p = VCt + ((size_t)(b * 2 + kv) * NKEY + keyidx) * 64 + d;
;                             *(u32x2*)p = (u32x2){cvt_pk_bf16(v0[0], v0[1]), cvt_pk_bf16(v0[2], v0[3])}; *(u32x2*)(p + 16) = (u32x2){cvt_pk_bf16(v1[0], v1[1]), cvt_pk_bf16(v1[2], v1[3])};
;                         }
;                     }
.LBB0_373:
	s_and_b64 vcc, exec, s[52:53]
	s_mov_b64 s[18:19], -1
	s_cbranch_vccnz .LBB0_389
	s_and_b64 vcc, exec, s[48:49]
	s_cbranch_vccnz .LBB0_384
	s_andn2_b64 vcc, exec, s[12:13]
	s_cbranch_vccnz .LBB0_381
	s_andn2_b64 vcc, exec, s[22:23]
	s_cbranch_vccnz .LBB0_378
	v_lshl_add_u64 v[58:59], v[162:163], 0, v[90:91]
	v_cvt_pk_bf16_f32 v60, v54, v55
	v_cvt_pk_bf16_f32 v61, v56, v57
	s_mov_b64 s[18:19], 0
	v_mov_b64_e32 v[216:217], v[60:61]
	v_cvt_pk_bf16_f32 v60, v50, v51
	v_cvt_pk_bf16_f32 v61, v52, v53
.LBB0_378:
	s_andn2_b64 vcc, exec, s[18:19]
	s_cbranch_vccnz .LBB0_380
	s_add_i32 s18, s16, 0xfffff980
	s_ashr_i32 s18, s18, 7
	s_add_i32 s18, s14, s18
	v_mad_i64_i32 v[58:59], s[18:19], s18, v196, v[0:1]
	v_lshlrev_b64 v[58:59], 8, v[58:59]
	v_lshl_add_u64 v[58:59], v[156:157], 0, v[58:59]
	v_cvt_pk_bf16_f32 v60, v54, v55
	v_cvt_pk_bf16_f32 v61, v56, v57
	v_mov_b64_e32 v[216:217], v[60:61]
	v_cvt_pk_bf16_f32 v60, v50, v51
	v_cvt_pk_bf16_f32 v61, v52, v53

; __device__ __forceinline__ unsigned cvt_pk_bf16(float lo, float hi) { unsigned r; asm volatile("v_cvt_pk_bf16_f32 %0, %1, %2" : "=v"(r) : "v"(lo), "v"(hi)); return r; }
;     __device__ __forceinline__ void operator()(const f32x4 (&acc)[2][2][4][2], const Unit& u, int wr, int wc, int fr, int fq) const {
;     ...
;                     } else if (pn <= 8) {
;                         const int cv = (pn - 7) * 256 + ctb, head = cv >> 7, e = cv & 127;
;                         bf16_t* p = VBt + ((size_t)(b * 4 + head) * NKEY + keyidx) * 128 + e;
;                         *(u32x2*)p = (u32x2){cvt_pk_bf16(v0[0], v0[1]), cvt_pk_bf16(v0[2], v0[3])}; *(u32x2*)(p + 16) = (u32x2){cvt_pk_bf16(v1[0], v1[1]), cvt_pk_bf16(v1[2], v1[3])};
.LBB0_381:
	s_andn2_b64 vcc, exec, s[18:19]
	s_cbranch_vccnz .LBB0_383
	s_or_b32 s18, s3, 1
	v_mad_i64_i32 v[58:59], s[18:19], s18, v196, v[0:1]
	v_lshlrev_b64 v[58:59], 8, v[58:59]
	v_lshl_add_u64 v[58:59], v[160:161], 0, v[58:59]
	v_cvt_pk_bf16_f32 v60, v54, v55
	v_cvt_pk_bf16_f32 v61, v56, v57
	v_mov_b64_e32 v[216:217], v[60:61]
	v_cvt_pk_bf16_f32 v60, v50, v51
	v_cvt_pk_bf16_f32 v61, v52, v53

; __device__ __forceinline__ unsigned cvt_pk_bf16(float lo, float hi) { unsigned r; asm volatile("v_cvt_pk_bf16_f32 %0, %1, %2" : "=v"(r) : "v"(lo), "v"(hi)); return r; }
;     __device__ __forceinline__ void operator()(const f32x4 (&acc)[2][2][4][2], const Unit& u, int wr, int wc, int fr, int fq) const {
;     ...
;                     } else if (pn <= 4) {
;                         v0 = v0 * QSCALE; v1 = v1 * QSCALE;
;                         bf16_t* p = (pn <= 3) ? QB + (size_t)r * 512 + (pn - 2) * 256 + ctb : QC + (size_t)r * 256 + ctb;
;                         *(u32x2*)p = (u32x2){cvt_pk_bf16(v0[0], v0[1]), cvt_pk_bf16(v0[2], v0[3])}; *(u32x2*)(p + 16) = (u32x2){cvt_pk_bf16(v1[0], v1[1]), cvt_pk_bf16(v1[2], v1[3])};
.LBB0_384:
	s_andn2_b64 vcc, exec, s[18:19]
	s_cbranch_vccnz .LBB0_386
	v_lshl_add_u64 v[78:79], s[8:9], 0, v[78:79]
	s_movk_i32 s18, 0xfc00
	v_lshl_add_u64 v[78:79], s[16:17], 1, v[78:79]
	s_mov_b32 s19, -1
	v_lshl_add_u64 v[58:59], s[0:1], 0, v[80:81]
	v_lshl_add_u64 v[78:79], v[78:79], 0, s[18:19]
	v_cndmask_b32_e64 v59, v79, v59, s[42:43]
	v_cndmask_b32_e64 v58, v78, v58, s[42:43]
	v_mov_b32_e32 v169, v1
	v_lshl_add_u64 v[78:79], v[58:59], 0, v[168:169]
	v_pk_mul_f32 v[60:61], v[56:57], s[74:75] op_sel_hi:[1,0]
	v_pk_mul_f32 v[62:63], v[54:55], s[74:75] op_sel_hi:[1,0]
	v_lshl_add_u64 v[58:59], v[78:79], 0, s[60:61]
	v_pk_mul_f32 v[64:65], v[52:53], s[74:75] op_sel_hi:[1,0]
	v_pk_mul_f32 v[82:83], v[50:51], s[74:75] op_sel_hi:[1,0]
	v_cvt_pk_bf16_f32 v62, v62, v63
	v_cvt_pk_bf16_f32 v63, v60, v61
	v_mov_b64_e32 v[216:217], v[62:63]
	v_cvt_pk_bf16_f32 v60, v82, v83
	v_cvt_pk_bf16_f32 v61, v64, v65

; __device__ __forceinline__ unsigned cvt_pk_bf16(float lo, float hi) { unsigned r; asm volatile("v_cvt_pk_bf16_f32 %0, %1, %2" : "=v"(r) : "v"(lo), "v"(hi)); return r; }
; __device__ __forceinline__ float gelu_tanh_f(float x) { const float y = 1.5957691216057308f * (x + 0.044715f * x * x * x); return x * __builtin_amdgcn_rcpf(1.f + __expf(-y)); }
;     __device__ __forceinline__ void operator()(const f32x4 (&acc)[2][2][4][2], const Unit& u, int wr, int wc, int fr, int fq) const {
;     ...
;                     if (pn <= 1) {
; #pragma unroll
;                         for (int i = 0; i < 4; ++i) { v0[i] = gelu_tanh_f(v0[i]); v1[i] = gelu_tanh_f(v1[i]); }
;                         bf16_t* p = UV + (size_t)r * 512 + pn * 256 + ctb;
;                         *(u32x2*)p = (u32x2){cvt_pk_bf16(v0[0], v0[1]), cvt_pk_bf16(v0[2], v0[3])}; *(u32x2*)(p + 16) = (u32x2){cvt_pk_bf16(v1[0], v1[1]), cvt_pk_bf16(v1[2], v1[3])};
.LBB0_388:
	v_mul_f32_e32 v75, 0x3d372713, v62
	v_mul_f32_e32 v75, v62, v75
	v_fma_f32 v75, v62, v75, v62
	v_mul_f32_e32 v75, 0xbfcc422a, v75
	v_mul_f32_e32 v75, 0x3fb8aa3b, v75
	v_exp_f32_e32 v75, v75
	v_mov_b32_e32 v169, v1
	v_lshl_add_u64 v[92:93], v[76:77], 0, v[168:169]
	v_add_f32_e32 v75, 1.0, v75
	v_rcp_f32_e32 v75, v75
	s_nop 0
	v_mul_f32_e32 v62, v62, v75
	v_mul_f32_e32 v75, 0x3d372713, v58
	v_mul_f32_e32 v75, v58, v75
	v_fma_f32 v75, v58, v75, v58
	v_mul_f32_e32 v75, 0xbfcc422a, v75
	v_mul_f32_e32 v75, 0x3fb8aa3b, v75
	v_exp_f32_e32 v75, v75
	s_nop 0
	v_add_f32_e32 v75, 1.0, v75
	v_rcp_f32_e32 v75, v75
	s_nop 0
	v_mul_f32_e32 v75, v58, v75
	v_mul_f32_e32 v58, 0x3d372713, v63
	v_mul_f32_e32 v58, v63, v58
	v_fma_f32 v58, v63, v58, v63
	v_mul_f32_e32 v58, 0xbfcc422a, v58
	v_mul_f32_e32 v58, 0x3fb8aa3b, v58
	v_exp_f32_e32 v58, v58
	s_nop 0
	v_add_f32_e32 v58, 1.0, v58
	v_rcp_f32_e32 v58, v58
	s_nop 0
	v_mul_f32_e32 v58, v63, v58
	v_mul_f32_e32 v63, 0x3d372713, v59
	v_mul_f32_e32 v63, v59, v63
	v_fma_f32 v63, v59, v63, v59
	v_mul_f32_e32 v63, 0xbfcc422a, v63
	v_mul_f32_e32 v63, 0x3fb8aa3b, v63
	v_exp_f32_e32 v63, v63
	v_cvt_pk_bf16_f32 v58, v62, v58
	s_nop 0
	v_add_f32_e32 v63, 1.0, v63
	v_rcp_f32_e32 v63, v63
	s_nop 0
	v_mul_f32_e32 v63, v59, v63
	v_mul_f32_e32 v59, 0x3d372713, v64
	v_mul_f32_e32 v59, v64, v59
	v_fma_f32 v59, v64, v59, v64
	v_mul_f32_e32 v59, 0xbfcc422a, v59
	v_mul_f32_e32 v59, 0x3fb8aa3b, v59
	v_exp_f32_e32 v59, v59
	s_nop 0
	v_add_f32_e32 v59, 1.0, v59
	v_rcp_f32_e32 v59, v59
	s_nop 0
	v_mul_f32_e32 v59, v64, v59
	v_mul_f32_e32 v64, 0x3d372713, v60
	v_mul_f32_e32 v64, v60, v64
	v_fma_f32 v64, v60, v64, v60
	v_mul_f32_e32 v64, 0xbfcc422a, v64
	v_mul_f32_e32 v64, 0x3fb8aa3b, v64
	v_exp_f32_e32 v64, v64
	s_nop 0
	v_add_f32_e32 v64, 1.0, v64
	v_rcp_f32_e32 v64, v64
	s_nop 0
	v_mul_f32_e32 v60, v60, v64
	v_mul_f32_e32 v64, 0x3d372713, v65
	v_mul_f32_e32 v64, v65, v64
	v_fma_f32 v64, v65, v64, v65
	v_mul_f32_e32 v64, 0xbfcc422a, v64
	v_mul_f32_e32 v64, 0x3fb8aa3b, v64
	v_exp_f32_e32 v64, v64
	s_nop 0
	v_add_f32_e32 v64, 1.0, v64
	v_rcp_f32_e32 v64, v64
	s_nop 0
	v_mul_f32_e32 v64, v65, v64
	v_mul_f32_e32 v65, 0x3d372713, v61
	v_mul_f32_e32 v65, v61, v65
	v_fma_f32 v65, v61, v65, v61
	v_mul_f32_e32 v65, 0xbfcc422a, v65
	v_mul_f32_e32 v65, 0x3fb8aa3b, v65
	v_exp_f32_e32 v65, v65
	v_cvt_pk_bf16_f32 v59, v59, v64
	v_mov_b64_e32 v[216:217], v[58:59]
	v_cvt_pk_bf16_f32 v94, v75, v63
	v_add_f32_e32 v65, 1.0, v65
	v_rcp_f32_e32 v65, v65
	s_nop 0
	v_mul_f32_e32 v61, v61, v65
	v_cvt_pk_bf16_f32 v95, v60, v61
	s_and_b64 vcc, exec, s[50:51]
	v_mov_b64_e32 v[218:219], v[94:95]
	s_nop 1
	v_permlane16_swap_b32_e32 v216, v218
	v_permlane16_swap_b32_e32 v217, v219
	v_lshl_add_u64 v[220:221], v[92:93], 0, v[222:223]
	flat_store_dwordx4 v[220:221], v[216:219]
	s_cbranch_vccnz .LBB0_373
	s_branch .LBB0_372

; __device__ __forceinline__ unsigned cvt_pk_bf16(float lo, float hi) { unsigned r; asm volatile("v_cvt_pk_bf16_f32 %0, %1, %2" : "=v"(r) : "v"(lo), "v"(hi)); return r; }
; __device__ __forceinline__ float gelu_tanh_f(float x) { const float y = 1.5957691216057308f * (x + 0.044715f * x * x * x); return x * __builtin_amdgcn_rcpf(1.f + __expf(-y)); }
; #define ROPE_FETCH(ai_, m_) do { const int s_ = (u.pm * BM + (ai_) * HALF + wr * 64 + (m_) * 16 + fr) & 2047, pos_ = (wc & 1) ? (s_ & 63) : (s_ >> 6); \
;             n01 = *(const f32x4*)(rope + pos_ * 16 + 4 * fq); n23 = *(const f32x4*)(rope + pos_ * 16 + 4 * fq + 2); } while (0)
;     __device__ __forceinline__ void operator()(const f32x4 (&acc)[2][2][4][2], const Unit& u, int wr, int wc, int fr, int fq) const {
;     ...
;         if (do_rope) ROPE_FETCH(0, 0);
; #pragma unroll
;         for (int ai = 0; ai < 2; ++ai)
; #pragma unroll
;             for (int m = 0; m < 4; ++m) {
;                 const f32x4 c01 = n01, c23 = n23;
;                 if (do_rope && (ai * 4 + m) < 7) ROPE_FETCH((ai * 4 + m + 1) >> 2, (ai * 4 + m + 1) & 3);
;     ...
;                     if (pn <= 1) {
; #pragma unroll
;                         for (int i = 0; i < 4; ++i) { v0[i] = gelu_tanh_f(v0[i]); v1[i] = gelu_tanh_f(v1[i]); }
;                         bf16_t* p = UV + (size_t)r * 512 + pn * 256 + ctb;
;                         *(u32x2*)p = (u32x2){cvt_pk_bf16(v0[0], v0[1]), cvt_pk_bf16(v0[2], v0[3])}; *(u32x2*)(p + 16) = (u32x2){cvt_pk_bf16(v1[0], v1[1]), cvt_pk_bf16(v1[2], v1[3])};
.LBB0_390:
	v_mul_f32_e32 v0, 0x3d372713, v54
	v_mul_f32_e32 v0, v54, v0
	v_fma_f32 v0, v54, v0, v54
	v_mul_f32_e32 v0, 0xbfcc422a, v0
	v_mul_f32_e32 v0, 0x3fb8aa3b, v0
	v_exp_f32_e32 v0, v0
	v_mov_b32_e32 v169, v1
	v_add_f32_e32 v0, 1.0, v0
	v_rcp_f32_e32 v0, v0
	s_nop 0
	v_mul_f32_e32 v0, v54, v0
	v_mul_f32_e32 v54, 0x3d372713, v50
	v_mul_f32_e32 v54, v50, v54
	v_fma_f32 v54, v50, v54, v50
	v_mul_f32_e32 v54, 0xbfcc422a, v54
	v_mul_f32_e32 v54, 0x3fb8aa3b, v54
	v_exp_f32_e32 v54, v54
	s_nop 0
	v_add_f32_e32 v54, 1.0, v54
	v_rcp_f32_e32 v54, v54
	s_nop 0
	v_mul_f32_e32 v54, v50, v54
	v_mul_f32_e32 v50, 0x3d372713, v55
	v_mul_f32_e32 v50, v55, v50
	v_fma_f32 v50, v55, v50, v55
	v_mul_f32_e32 v50, 0xbfcc422a, v50
	v_mul_f32_e32 v50, 0x3fb8aa3b, v50
	v_exp_f32_e32 v50, v50
	s_nop 0
	v_add_f32_e32 v50, 1.0, v50
	v_rcp_f32_e32 v50, v50
	s_nop 0
	v_mul_f32_e32 v55, v55, v50
	v_mul_f32_e32 v50, 0x3d372713, v51
	v_mul_f32_e32 v50, v51, v50
	v_fma_f32 v50, v51, v50, v51
	v_mul_f32_e32 v50, 0xbfcc422a, v50
	v_mul_f32_e32 v50, 0x3fb8aa3b, v50
	v_exp_f32_e32 v50, v50
	s_nop 0
	v_add_f32_e32 v50, 1.0, v50
	v_rcp_f32_e32 v50, v50
	s_nop 0
	v_mul_f32_e32 v60, v51, v50
	v_mul_f32_e32 v50, 0x3d372713, v56
	v_mul_f32_e32 v50, v56, v50
	v_fma_f32 v50, v56, v50, v56
	v_mul_f32_e32 v50, 0xbfcc422a, v50
	v_mul_f32_e32 v50, 0x3fb8aa3b, v50
	v_exp_f32_e32 v50, v50
	s_nop 0
	v_add_f32_e32 v50, 1.0, v50
	v_rcp_f32_e32 v50, v50
	s_nop 0
	v_mul_f32_e32 v56, v56, v50
	v_mul_f32_e32 v50, 0x3d372713, v52
	v_mul_f32_e32 v50, v52, v50
	v_fma_f32 v50, v52, v50, v52
	v_mul_f32_e32 v50, 0xbfcc422a, v50
	v_mul_f32_e32 v50, 0x3fb8aa3b, v50
	v_exp_f32_e32 v50, v50
	s_nop 0
	v_add_f32_e32 v50, 1.0, v50
	v_rcp_f32_e32 v50, v50
	s_nop 0
	v_mul_f32_e32 v61, v52, v50
	v_mul_f32_e32 v50, 0x3d372713, v57
	v_mul_f32_e32 v50, v57, v50
	v_fma_f32 v50, v57, v50, v57
	v_mul_f32_e32 v50, 0xbfcc422a, v50
	v_mul_f32_e32 v50, 0x3fb8aa3b, v50
	v_exp_f32_e32 v50, v50
	v_cvt_pk_bf16_f32 v52, v0, v55
	s_nop 0
	v_add_f32_e32 v50, 1.0, v50
	v_rcp_f32_e32 v50, v50
	s_nop 0
	v_mul_f32_e32 v57, v57, v50
	v_mul_f32_e32 v50, 0x3d372713, v53
	v_mul_f32_e32 v50, v53, v50
	v_fma_f32 v50, v53, v50, v53
	v_mul_f32_e32 v50, 0xbfcc422a, v50
	v_mul_f32_e32 v50, 0x3fb8aa3b, v50
	v_exp_f32_e32 v50, v50
	s_nop 0
	v_add_f32_e32 v50, 1.0, v50
	v_rcp_f32_e32 v50, v50
	s_nop 0
	v_mul_f32_e32 v62, v53, v50
	v_lshl_add_u64 v[50:51], v[76:77], 0, v[168:169]
	v_lshl_add_u64 v[58:59], v[50:51], 0, s[60:61]
	v_cvt_pk_bf16_f32 v53, v56, v57
	v_mov_b64_e32 v[216:217], v[52:53]
	v_cvt_pk_bf16_f32 v60, v54, v60
	v_cvt_pk_bf16_f32 v61, v61, v62
.LBB0_391:
	v_mov_b64_e32 v[218:219], v[60:61]
	s_nop 1
	v_permlane16_swap_b32_e32 v216, v218
	v_permlane16_swap_b32_e32 v217, v219
	v_lshl_add_u64 v[220:221], v[58:59], 0, v[222:223]
	flat_store_dwordx4 v[220:221], v[216:219]
	s_waitcnt vmcnt(0) lgkmcnt(0)
	v_mov_b64_e32 v[54:55], v[70:71]
	v_mov_b64_e32 v[50:51], v[66:67]
	s_and_b64 vcc, exec, s[54:55]
	v_mov_b64_e32 v[56:57], v[72:73]
	v_mov_b64_e32 v[52:53], v[68:69]
	s_cbranch_vccnz .LBB0_393
	s_lshr_b32 s18, s29, 6
	v_readlane_b32 s19, v255, 14
	s_add_i32 s18, s18, s19
	s_and_b32 s18, s18, 31
	v_mov_b32_e32 v0, s18
	v_cndmask_b32_e64 v0, v209, v0, s[38:39]
	v_lshlrev_b32_e32 v0, 7, v0
	v_lshl_add_u64 v[54:55], v[152:153], 0, v[0:1]
	flat_load_dwordx4 v[50:53], v[54:55]
	s_nop 0
	flat_load_dwordx4 v[54:57], v[54:55] offset:16

;     __device__ __forceinline__ void operator()(const f32x4 (&acc)[2][2][4][2], const Unit& u, int wr, int wc, int fr, int fq) const {
;     ...
;                 const int r = u.pm * BM + ai * HALF + wr * 64 + m * 16 + fr;
;                 int b, s, keyidx;
;                 if (lat) { b = r >> 11; s = r & 2047; keyidx = CTXL + s; } else { const int rc = r - T_LAT; b = rc >> 8; s = 0; keyidx = rc & 255; }
; #pragma unroll
;                 for (int bj = 0; bj < 2; ++bj) {
;                     f32x4 v0 = acc[ai][bj][m][0], v1 = acc[ai][bj][m][1];
;                     const bool is_rope = (pn >= 2 && pn <= 6) || (pn == 9 && bj == 0);
;                     if (is_rope && lat) {
;                         const float cs[4] = {c01[0], c01[2], c23[0], c23[2]}, sn[4] = {c01[1], c01[3], c23[1], c23[3]};
; #pragma unroll
;                         for (int i = 0; i < 4; ++i) { const float x0 = v0[i], x1 = v1[i]; v0[i] = x0 * cs[i] - x1 * sn[i]; v1[i] = x1 * cs[i] + x0 * sn[i]; }
;                     }
;                     const int ctb = bj * HALF + wc * 32 + 4 * fq;
;                     if (pn <= 1) {
; #pragma unroll
;                         for (int i = 0; i < 4; ++i) { v0[i] = gelu_tanh_f(v0[i]); v1[i] = gelu_tanh_f(v1[i]); }
;                         bf16_t* p = UV + (size_t)r * 512 + pn * 256 + ctb;
;                         *(u32x2*)p = (u32x2){cvt_pk_bf16(v0[0], v0[1]), cvt_pk_bf16(v0[2], v0[3])}; *(u32x2*)(p + 16) = (u32x2){cvt_pk_bf16(v1[0], v1[1]), cvt_pk_bf16(v1[2], v1[3])};
;                     } else if (pn <= 4) {
;                         v0 = v0 * QSCALE; v1 = v1 * QSCALE;
;                         bf16_t* p = (pn <= 3) ? QB + (size_t)r * 512 + (pn - 2) * 256 + ctb : QC + (size_t)r * 256 + ctb;
;                         *(u32x2*)p = (u32x2){cvt_pk_bf16(v0[0], v0[1]), cvt_pk_bf16(v0[2], v0[3])}; *(u32x2*)(p + 16) = (u32x2){cvt_pk_bf16(v1[0], v1[1]), cvt_pk_bf16(v1[2], v1[3])};
;                     } else if (pn <= 6) {
;                         const int ck = (pn - 5) * 256 + ctb, head = ck >> 7, cw = ck & 127;
;                         bf16_t* p = KB + ((size_t)(b * 4 + head) * NKEY + keyidx) * 128 + cw;
;                         *(u32x2*)p = (u32x2){cvt_pk_bf16(v0[0], v0[1]), cvt_pk_bf16(v0[2], v0[3])}; *(u32x2*)(p + 16) = (u32x2){cvt_pk_bf16(v1[0], v1[1]), cvt_pk_bf16(v1[2], v1[3])};
;                     } else if (pn <= 8) {
.LBB0_395:
	s_mul_hi_i32 s19, s15, 0x900
	s_mul_i32 s18, s15, 0x900
	s_movk_i32 s15, 0x7df
	v_bitop3_b32 v0, v74, s15, 16 bitop3:0xc8
	s_movk_i32 s15, 0xdf
	v_add_u32_e32 v0, 0x100, v0
	v_bitop3_b32 v59, v74, s15, 16 bitop3:0xc8
	v_or_b32_e32 v58, 16, v74
	v_cndmask_b32_e64 v0, v59, v0, s[44:45]
	v_lshl_add_u64 v[60:61], s[18:19], 0, v[0:1]
	v_ashrrev_i32_e32 v59, 31, v58
	v_lshlrev_b64 v[64:65], 7, v[60:61]
	v_lshlrev_b64 v[60:61], 10, v[58:59]
	v_lshlrev_b64 v[62:63], 9, v[58:59]
	s_and_b64 vcc, exec, s[52:53]
	s_mov_b64 s[96:97], -1
	s_cbranch_vccnz .LBB0_425
	s_and_b64 vcc, exec, s[48:49]
	s_cbranch_vccnz .LBB0_406
	s_andn2_b64 vcc, exec, s[12:13]
	s_cbranch_vccnz .LBB0_403
	s_andn2_b64 vcc, exec, s[22:23]
	s_cbranch_vccnz .LBB0_400
	v_lshl_add_u64 v[76:77], v[154:155], 0, v[64:65]
	s_mov_b64 s[96:97], 0
	v_cvt_pk_bf16_f32 v58, v46, v47
	v_cvt_pk_bf16_f32 v59, v48, v49
	v_mov_b64_e32 v[216:217], v[58:59]
	v_cvt_pk_bf16_f32 v78, v42, v43
	v_cvt_pk_bf16_f32 v79, v44, v45
.LBB0_400:
	s_andn2_b64 vcc, exec, s[96:97]
	s_cbranch_vccnz .LBB0_402
	v_readlane_b32 s15, v255, 17
	s_ashr_i32 s15, s15, 7
	s_add_i32 s15, s14, s15
	v_mad_i64_i32 v[58:59], s[60:61], s15, v196, v[0:1]
	v_lshlrev_b64 v[58:59], 8, v[58:59]
	s_mov_b64 s[60:61], 0x100
	v_lshl_add_u64 v[76:77], v[156:157], 0, v[58:59]
	v_cvt_pk_bf16_f32 v58, v46, v47
	v_cvt_pk_bf16_f32 v59, v48, v49
	v_mov_b64_e32 v[216:217], v[58:59]
	v_cvt_pk_bf16_f32 v78, v42, v43
	v_cvt_pk_bf16_f32 v79, v44, v45

; __device__ __forceinline__ unsigned cvt_pk_bf16(float lo, float hi) { unsigned r; asm volatile("v_cvt_pk_bf16_f32 %0, %1, %2" : "=v"(r) : "v"(lo), "v"(hi)); return r; }
;     __device__ __forceinline__ void operator()(const f32x4 (&acc)[2][2][4][2], const Unit& u, int wr, int wc, int fr, int fq) const {
;     ...
;                     } else if (pn <= 8) {
;                         const int cv = (pn - 7) * 256 + ctb, head = cv >> 7, e = cv & 127;
;                         bf16_t* p = VBt + ((size_t)(b * 4 + head) * NKEY + keyidx) * 128 + e;
;                         *(u32x2*)p = (u32x2){cvt_pk_bf16(v0[0], v0[1]), cvt_pk_bf16(v0[2], v0[3])}; *(u32x2*)(p + 16) = (u32x2){cvt_pk_bf16(v1[0], v1[1]), cvt_pk_bf16(v1[2], v1[3])};
.LBB0_403:
	s_andn2_b64 vcc, exec, s[96:97]
	s_cbranch_vccnz .LBB0_405
	v_mad_i64_i32 v[58:59], s[60:61], s3, v196, v[0:1]
	v_lshlrev_b64 v[58:59], 8, v[58:59]
	s_mov_b64 s[60:61], 0x100
	v_lshl_add_u64 v[76:77], v[160:161], 0, v[58:59]
	v_cvt_pk_bf16_f32 v58, v46, v47
	v_cvt_pk_bf16_f32 v59, v48, v49
	v_mov_b64_e32 v[216:217], v[58:59]
	v_cvt_pk_bf16_f32 v78, v42, v43
	v_cvt_pk_bf16_f32 v79, v44, v45

; __device__ __forceinline__ unsigned cvt_pk_bf16(float lo, float hi) { unsigned r; asm volatile("v_cvt_pk_bf16_f32 %0, %1, %2" : "=v"(r) : "v"(lo), "v"(hi)); return r; }
;     __device__ __forceinline__ void operator()(const f32x4 (&acc)[2][2][4][2], const Unit& u, int wr, int wc, int fr, int fq) const {
;     ...
;                     } else if (pn <= 4) {
;                         v0 = v0 * QSCALE; v1 = v1 * QSCALE;
;                         bf16_t* p = (pn <= 3) ? QB + (size_t)r * 512 + (pn - 2) * 256 + ctb : QC + (size_t)r * 256 + ctb;
;                         *(u32x2*)p = (u32x2){cvt_pk_bf16(v0[0], v0[1]), cvt_pk_bf16(v0[2], v0[3])}; *(u32x2*)(p + 16) = (u32x2){cvt_pk_bf16(v1[0], v1[1]), cvt_pk_bf16(v1[2], v1[3])};
.LBB0_406:
	s_andn2_b64 vcc, exec, s[96:97]
	s_cbranch_vccnz .LBB0_408
	v_lshl_add_u64 v[84:85], s[8:9], 0, v[60:61]
	s_movk_i32 s96, 0xfc00
	v_lshl_add_u64 v[84:85], s[16:17], 1, v[84:85]
	s_mov_b32 s97, -1
	v_lshl_add_u64 v[76:77], s[0:1], 0, v[62:63]
	v_lshl_add_u64 v[84:85], v[84:85], 0, s[96:97]
	v_pk_mul_f32 v[78:79], v[46:47], s[74:75] op_sel_hi:[1,0]
	v_cndmask_b32_e64 v77, v85, v77, s[42:43]
	v_cndmask_b32_e64 v76, v84, v76, s[42:43]
	v_mov_b32_e32 v169, v1
	v_pk_mul_f32 v[58:59], v[48:49], s[74:75] op_sel_hi:[1,0]
	v_lshl_add_u64 v[76:77], v[76:77], 0, v[168:169]
	v_cvt_pk_bf16_f32 v78, v78, v79
	v_cvt_pk_bf16_f32 v79, v58, v59
	v_pk_mul_f32 v[80:81], v[44:45], s[74:75] op_sel_hi:[1,0]
	v_pk_mul_f32 v[82:83], v[42:43], s[74:75] op_sel_hi:[1,0]
	v_mov_b64_e32 v[216:217], v[78:79]
	v_cvt_pk_bf16_f32 v78, v82, v83
	v_cvt_pk_bf16_f32 v79, v80, v81

;     __device__ __forceinline__ void operator()(const f32x4 (&acc)[2][2][4][2], const Unit& u, int wr, int wc, int fr, int fq) const {
;     ...
;                 for (int bj = 0; bj < 2; ++bj) {
;                     f32x4 v0 = acc[ai][bj][m][0], v1 = acc[ai][bj][m][1];
;                     const bool is_rope = (pn >= 2 && pn <= 6) || (pn == 9 && bj == 0);
;                     if (is_rope && lat) {
;                         const float cs[4] = {c01[0], c01[2], c23[0], c23[2]}, sn[4] = {c01[1], c01[3], c23[1], c23[3]};
; #pragma unroll
;                         for (int i = 0; i < 4; ++i) { const float x0 = v0[i], x1 = v1[i]; v0[i] = x0 * cs[i] - x1 * sn[i]; v1[i] = x1 * cs[i] + x0 * sn[i]; }
;                     }
;                     const int ctb = bj * HALF + wc * 32 + 4 * fq;
;                     if (pn <= 1) {
; #pragma unroll
;                         for (int i = 0; i < 4; ++i) { v0[i] = gelu_tanh_f(v0[i]); v1[i] = gelu_tanh_f(v1[i]); }
;                         bf16_t* p = UV + (size_t)r * 512 + pn * 256 + ctb;
;                         *(u32x2*)p = (u32x2){cvt_pk_bf16(v0[0], v0[1]), cvt_pk_bf16(v0[2], v0[3])}; *(u32x2*)(p + 16) = (u32x2){cvt_pk_bf16(v1[0], v1[1]), cvt_pk_bf16(v1[2], v1[3])};
;                     } else if (pn <= 4) {
;                         v0 = v0 * QSCALE; v1 = v1 * QSCALE;
;                         bf16_t* p = (pn <= 3) ? QB + (size_t)r * 512 + (pn - 2) * 256 + ctb : QC + (size_t)r * 256 + ctb;
;                         *(u32x2*)p = (u32x2){cvt_pk_bf16(v0[0], v0[1]), cvt_pk_bf16(v0[2], v0[3])}; *(u32x2*)(p + 16) = (u32x2){cvt_pk_bf16(v1[0], v1[1]), cvt_pk_bf16(v1[2], v1[3])};
;                     } else if (pn <= 6) {
;                         const int ck = (pn - 5) * 256 + ctb, head = ck >> 7, cw = ck & 127;
;                         bf16_t* p = KB + ((size_t)(b * 4 + head) * NKEY + keyidx) * 128 + cw;
;                         *(u32x2*)p = (u32x2){cvt_pk_bf16(v0[0], v0[1]), cvt_pk_bf16(v0[2], v0[3])}; *(u32x2*)(p + 16) = (u32x2){cvt_pk_bf16(v1[0], v1[1]), cvt_pk_bf16(v1[2], v1[3])};
;                     } else if (pn <= 8) {
;                         const int cv = (pn - 7) * 256 + ctb, head = cv >> 7, e = cv & 127;
;                         bf16_t* p = VBt + ((size_t)(b * 4 + head) * NKEY + keyidx) * 128 + e;
.LBB0_409:
	s_and_b64 vcc, exec, s[50:51]
	v_mov_b64_e32 v[218:219], v[78:79]
	s_nop 1
	v_permlane16_swap_b32_e32 v216, v218
	v_permlane16_swap_b32_e32 v217, v219
	v_lshl_add_u64 v[220:221], v[76:77], 0, v[222:223]
	flat_store_dwordx4 v[220:221], v[216:219]
	s_cbranch_vccnz .LBB0_411

; __device__ __forceinline__ unsigned cvt_pk_bf16(float lo, float hi) { unsigned r; asm volatile("v_cvt_pk_bf16_f32 %0, %1, %2" : "=v"(r) : "v"(lo), "v"(hi)); return r; }
;     __device__ __forceinline__ void operator()(const f32x4 (&acc)[2][2][4][2], const Unit& u, int wr, int wc, int fr, int fq) const {
;     ...
;                     } else if (pn <= 6) {
;                         const int ck = (pn - 5) * 256 + ctb, head = ck >> 7, cw = ck & 127;
;                         bf16_t* p = KB + ((size_t)(b * 4 + head) * NKEY + keyidx) * 128 + cw;
;                         *(u32x2*)p = (u32x2){cvt_pk_bf16(v0[0], v0[1]), cvt_pk_bf16(v0[2], v0[3])}; *(u32x2*)(p + 16) = (u32x2){cvt_pk_bf16(v1[0], v1[1]), cvt_pk_bf16(v1[2], v1[3])};
;                     } else if (pn <= 8) {
;                         const int cv = (pn - 7) * 256 + ctb, head = cv >> 7, e = cv & 127;
;                         bf16_t* p = VBt + ((size_t)(b * 4 + head) * NKEY + keyidx) * 128 + e;
;                         *(u32x2*)p = (u32x2){cvt_pk_bf16(v0[0], v0[1]), cvt_pk_bf16(v0[2], v0[3])}; *(u32x2*)(p + 16) = (u32x2){cvt_pk_bf16(v1[0], v1[1]), cvt_pk_bf16(v1[2], v1[3])};
;                     } else {
;                         const int kv = wc >> 1, d = (wc & 1) * 32 + 4 * fq;
;                         if (bj == 0) {
;                             bf16_t* p = KC + ((size_t)(b * 2 + kv) * NKEY + keyidx) * 64 + d;
;                             *(u32x2*)p = (u32x2){cvt_pk_bf16(v0[0], v0[1]), cvt_pk_bf16(v0[2], v0[3])}; *(u32x2*)(p + 16) = (u32x2){cvt_pk_bf16(v1[0], v1[1]), cvt_pk_bf16(v1[2], v1[3])};
;                         } else {
;                             bf16_t* p = VCt + ((size_t)(b * 2 + kv) * NKEY + keyidx) * 64 + d;
;                             *(u32x2*)p = (u32x2){cvt_pk_bf16(v0[0], v0[1]), cvt_pk_bf16(v0[2], v0[3])}; *(u32x2*)(p + 16) = (u32x2){cvt_pk_bf16(v1[0], v1[1]), cvt_pk_bf16(v1[2], v1[3])};
;                         }
;                     }
.LBB0_411:
	s_and_b64 vcc, exec, s[52:53]
	s_mov_b64 s[96:97], -1
	s_cbranch_vccnz .LBB0_427
	s_and_b64 vcc, exec, s[48:49]
	s_cbranch_vccnz .LBB0_422
	s_andn2_b64 vcc, exec, s[12:13]
	s_cbranch_vccnz .LBB0_419
	s_andn2_b64 vcc, exec, s[22:23]
	s_cbranch_vccnz .LBB0_416
	v_lshl_add_u64 v[42:43], v[162:163], 0, v[64:65]
	v_cvt_pk_bf16_f32 v44, v38, v39
	v_cvt_pk_bf16_f32 v45, v40, v41
	s_mov_b64 s[96:97], 0
	v_mov_b64_e32 v[216:217], v[44:45]
	v_cvt_pk_bf16_f32 v44, v34, v35
	v_cvt_pk_bf16_f32 v45, v36, v37
.LBB0_416:
	s_andn2_b64 vcc, exec, s[96:97]
	s_cbranch_vccnz .LBB0_418
	s_add_i32 s15, s20, 0xfffff980
	s_ashr_i32 s15, s15, 7
	s_add_i32 s15, s14, s15
	v_mad_i64_i32 v[42:43], s[60:61], s15, v196, v[0:1]
	v_lshlrev_b64 v[42:43], 8, v[42:43]
	s_mov_b64 s[60:61], 0x100
	v_lshl_add_u64 v[42:43], v[156:157], 0, v[42:43]
	v_cvt_pk_bf16_f32 v44, v38, v39
	v_cvt_pk_bf16_f32 v45, v40, v41
	v_mov_b64_e32 v[216:217], v[44:45]
	v_cvt_pk_bf16_f32 v44, v34, v35
	v_cvt_pk_bf16_f32 v45, v36, v37

; __device__ __forceinline__ unsigned cvt_pk_bf16(float lo, float hi) { unsigned r; asm volatile("v_cvt_pk_bf16_f32 %0, %1, %2" : "=v"(r) : "v"(lo), "v"(hi)); return r; }
;     __device__ __forceinline__ void operator()(const f32x4 (&acc)[2][2][4][2], const Unit& u, int wr, int wc, int fr, int fq) const {
;     ...
;                     } else if (pn <= 8) {
;                         const int cv = (pn - 7) * 256 + ctb, head = cv >> 7, e = cv & 127;
;                         bf16_t* p = VBt + ((size_t)(b * 4 + head) * NKEY + keyidx) * 128 + e;
;                         *(u32x2*)p = (u32x2){cvt_pk_bf16(v0[0], v0[1]), cvt_pk_bf16(v0[2], v0[3])}; *(u32x2*)(p + 16) = (u32x2){cvt_pk_bf16(v1[0], v1[1]), cvt_pk_bf16(v1[2], v1[3])};
.LBB0_419:
	s_andn2_b64 vcc, exec, s[96:97]
	s_cbranch_vccnz .LBB0_421
	s_or_b32 s15, s3, 1
	v_mad_i64_i32 v[42:43], s[60:61], s15, v196, v[0:1]
	v_lshlrev_b64 v[42:43], 8, v[42:43]
	s_mov_b64 s[60:61], 0x100
	v_lshl_add_u64 v[42:43], v[160:161], 0, v[42:43]
	v_cvt_pk_bf16_f32 v44, v38, v39
	v_cvt_pk_bf16_f32 v45, v40, v41
	v_mov_b64_e32 v[216:217], v[44:45]
	v_cvt_pk_bf16_f32 v44, v34, v35
	v_cvt_pk_bf16_f32 v45, v36, v37

; __device__ __forceinline__ unsigned cvt_pk_bf16(float lo, float hi) { unsigned r; asm volatile("v_cvt_pk_bf16_f32 %0, %1, %2" : "=v"(r) : "v"(lo), "v"(hi)); return r; }
;     __device__ __forceinline__ void operator()(const f32x4 (&acc)[2][2][4][2], const Unit& u, int wr, int wc, int fr, int fq) const {
;     ...
;                     } else if (pn <= 4) {
;                         v0 = v0 * QSCALE; v1 = v1 * QSCALE;
;                         bf16_t* p = (pn <= 3) ? QB + (size_t)r * 512 + (pn - 2) * 256 + ctb : QC + (size_t)r * 256 + ctb;
;                         *(u32x2*)p = (u32x2){cvt_pk_bf16(v0[0], v0[1]), cvt_pk_bf16(v0[2], v0[3])}; *(u32x2*)(p + 16) = (u32x2){cvt_pk_bf16(v1[0], v1[1]), cvt_pk_bf16(v1[2], v1[3])};
.LBB0_422:
	s_andn2_b64 vcc, exec, s[96:97]
	s_cbranch_vccnz .LBB0_424
	v_lshl_add_u64 v[60:61], s[8:9], 0, v[60:61]
	s_movk_i32 s96, 0xfc00
	v_lshl_add_u64 v[60:61], s[16:17], 1, v[60:61]
	s_mov_b32 s97, -1
	v_lshl_add_u64 v[42:43], s[0:1], 0, v[62:63]
	v_lshl_add_u64 v[60:61], v[60:61], 0, s[96:97]
	v_cndmask_b32_e64 v43, v61, v43, s[42:43]
	v_cndmask_b32_e64 v42, v60, v42, s[42:43]
	v_mov_b32_e32 v169, v1
	v_lshl_add_u64 v[60:61], v[42:43], 0, v[168:169]
	v_pk_mul_f32 v[44:45], v[40:41], s[74:75] op_sel_hi:[1,0]
	v_pk_mul_f32 v[46:47], v[38:39], s[74:75] op_sel_hi:[1,0]
	v_lshl_add_u64 v[42:43], v[60:61], 0, s[60:61]
	v_pk_mul_f32 v[48:49], v[36:37], s[74:75] op_sel_hi:[1,0]
	v_pk_mul_f32 v[64:65], v[34:35], s[74:75] op_sel_hi:[1,0]
	v_cvt_pk_bf16_f32 v46, v46, v47
	v_cvt_pk_bf16_f32 v47, v44, v45
	v_mov_b64_e32 v[216:217], v[46:47]
	v_cvt_pk_bf16_f32 v44, v64, v65
	v_cvt_pk_bf16_f32 v45, v48, v49

; __device__ __forceinline__ unsigned cvt_pk_bf16(float lo, float hi) { unsigned r; asm volatile("v_cvt_pk_bf16_f32 %0, %1, %2" : "=v"(r) : "v"(lo), "v"(hi)); return r; }
; __device__ __forceinline__ float gelu_tanh_f(float x) { const float y = 1.5957691216057308f * (x + 0.044715f * x * x * x); return x * __builtin_amdgcn_rcpf(1.f + __expf(-y)); }
;     __device__ __forceinline__ void operator()(const f32x4 (&acc)[2][2][4][2], const Unit& u, int wr, int wc, int fr, int fq) const {
;     ...
;                     if (pn <= 1) {
; #pragma unroll
;                         for (int i = 0; i < 4; ++i) { v0[i] = gelu_tanh_f(v0[i]); v1[i] = gelu_tanh_f(v1[i]); }
;                         bf16_t* p = UV + (size_t)r * 512 + pn * 256 + ctb;
;                         *(u32x2*)p = (u32x2){cvt_pk_bf16(v0[0], v0[1]), cvt_pk_bf16(v0[2], v0[3])}; *(u32x2*)(p + 16) = (u32x2){cvt_pk_bf16(v1[0], v1[1]), cvt_pk_bf16(v1[2], v1[3])};
.LBB0_426:
	v_mul_f32_e32 v75, 0x3d372713, v46
	v_mul_f32_e32 v75, v46, v75
	v_fma_f32 v75, v46, v75, v46
	v_mul_f32_e32 v75, 0xbfcc422a, v75
	v_mul_f32_e32 v75, 0x3fb8aa3b, v75
	v_exp_f32_e32 v75, v75
	v_mov_b32_e32 v169, v1
	v_lshl_add_u64 v[76:77], v[58:59], 0, v[168:169]
	v_add_f32_e32 v75, 1.0, v75
	v_rcp_f32_e32 v75, v75
	s_nop 0
	v_mul_f32_e32 v46, v46, v75
	v_mul_f32_e32 v75, 0x3d372713, v42
	v_mul_f32_e32 v75, v42, v75
	v_fma_f32 v75, v42, v75, v42
	v_mul_f32_e32 v75, 0xbfcc422a, v75
	v_mul_f32_e32 v75, 0x3fb8aa3b, v75
	v_exp_f32_e32 v75, v75
	s_nop 0
	v_add_f32_e32 v75, 1.0, v75
	v_rcp_f32_e32 v75, v75
	s_nop 0
	v_mul_f32_e32 v75, v42, v75
	v_mul_f32_e32 v42, 0x3d372713, v47
	v_mul_f32_e32 v42, v47, v42
	v_fma_f32 v42, v47, v42, v47
	v_mul_f32_e32 v42, 0xbfcc422a, v42
	v_mul_f32_e32 v42, 0x3fb8aa3b, v42
	v_exp_f32_e32 v42, v42
	s_nop 0
	v_add_f32_e32 v42, 1.0, v42
	v_rcp_f32_e32 v42, v42
	s_nop 0
	v_mul_f32_e32 v42, v47, v42
	v_mul_f32_e32 v47, 0x3d372713, v43
	v_mul_f32_e32 v47, v43, v47
	v_fma_f32 v47, v43, v47, v43
	v_mul_f32_e32 v47, 0xbfcc422a, v47
	v_mul_f32_e32 v47, 0x3fb8aa3b, v47
	v_exp_f32_e32 v47, v47
	v_cvt_pk_bf16_f32 v42, v46, v42
	s_nop 0
	v_add_f32_e32 v47, 1.0, v47
	v_rcp_f32_e32 v47, v47
	s_nop 0
	v_mul_f32_e32 v47, v43, v47
	v_mul_f32_e32 v43, 0x3d372713, v48
	v_mul_f32_e32 v43, v48, v43
	v_fma_f32 v43, v48, v43, v48
	v_mul_f32_e32 v43, 0xbfcc422a, v43
	v_mul_f32_e32 v43, 0x3fb8aa3b, v43
	v_exp_f32_e32 v43, v43
	s_nop 0
	v_add_f32_e32 v43, 1.0, v43
	v_rcp_f32_e32 v43, v43
	s_nop 0
	v_mul_f32_e32 v43, v48, v43
	v_mul_f32_e32 v48, 0x3d372713, v44
	v_mul_f32_e32 v48, v44, v48
	v_fma_f32 v48, v44, v48, v44
	v_mul_f32_e32 v48, 0xbfcc422a, v48
	v_mul_f32_e32 v48, 0x3fb8aa3b, v48
	v_exp_f32_e32 v48, v48
	s_nop 0
	v_add_f32_e32 v48, 1.0, v48
	v_rcp_f32_e32 v48, v48
	s_nop 0
	v_mul_f32_e32 v44, v44, v48
	v_mul_f32_e32 v48, 0x3d372713, v49
	v_mul_f32_e32 v48, v49, v48
	v_fma_f32 v48, v49, v48, v49
	v_mul_f32_e32 v48, 0xbfcc422a, v48
	v_mul_f32_e32 v48, 0x3fb8aa3b, v48
	v_exp_f32_e32 v48, v48
	s_nop 0
	v_add_f32_e32 v48, 1.0, v48
	v_rcp_f32_e32 v48, v48
	s_nop 0
	v_mul_f32_e32 v48, v49, v48
	v_mul_f32_e32 v49, 0x3d372713, v45
	v_mul_f32_e32 v49, v45, v49
	v_fma_f32 v49, v45, v49, v45
	v_mul_f32_e32 v49, 0xbfcc422a, v49
	v_mul_f32_e32 v49, 0x3fb8aa3b, v49
	v_exp_f32_e32 v49, v49
	v_cvt_pk_bf16_f32 v43, v43, v48
	v_mov_b64_e32 v[216:217], v[42:43]
	v_cvt_pk_bf16_f32 v78, v75, v47
	v_add_f32_e32 v49, 1.0, v49
	v_rcp_f32_e32 v49, v49
	s_nop 0
	v_mul_f32_e32 v45, v45, v49
	v_cvt_pk_bf16_f32 v79, v44, v45
	s_and_b64 vcc, exec, s[50:51]
	v_mov_b64_e32 v[218:219], v[78:79]
	s_nop 1
	v_permlane16_swap_b32_e32 v216, v218
	v_permlane16_swap_b32_e32 v217, v219
	v_lshl_add_u64 v[220:221], v[76:77], 0, v[222:223]
	flat_store_dwordx4 v[220:221], v[216:219]
	s_cbranch_vccnz .LBB0_411
	s_branch .LBB0_410

; __device__ __forceinline__ unsigned cvt_pk_bf16(float lo, float hi) { unsigned r; asm volatile("v_cvt_pk_bf16_f32 %0, %1, %2" : "=v"(r) : "v"(lo), "v"(hi)); return r; }
; __device__ __forceinline__ float gelu_tanh_f(float x) { const float y = 1.5957691216057308f * (x + 0.044715f * x * x * x); return x * __builtin_amdgcn_rcpf(1.f + __expf(-y)); }
; #define ROPE_FETCH(ai_, m_) do { const int s_ = (u.pm * BM + (ai_) * HALF + wr * 64 + (m_) * 16 + fr) & 2047, pos_ = (wc & 1) ? (s_ & 63) : (s_ >> 6); \
;             n01 = *(const f32x4*)(rope + pos_ * 16 + 4 * fq); n23 = *(const f32x4*)(rope + pos_ * 16 + 4 * fq + 2); } while (0)
;     __device__ __forceinline__ void operator()(const f32x4 (&acc)[2][2][4][2], const Unit& u, int wr, int wc, int fr, int fq) const {
;     ...
;         if (do_rope) ROPE_FETCH(0, 0);
; #pragma unroll
;         for (int ai = 0; ai < 2; ++ai)
; #pragma unroll
;             for (int m = 0; m < 4; ++m) {
;                 const f32x4 c01 = n01, c23 = n23;
;                 if (do_rope && (ai * 4 + m) < 7) ROPE_FETCH((ai * 4 + m + 1) >> 2, (ai * 4 + m + 1) & 3);
;     ...
;                     if (pn <= 1) {
; #pragma unroll
;                         for (int i = 0; i < 4; ++i) { v0[i] = gelu_tanh_f(v0[i]); v1[i] = gelu_tanh_f(v1[i]); }
;                         bf16_t* p = UV + (size_t)r * 512 + pn * 256 + ctb;
;                         *(u32x2*)p = (u32x2){cvt_pk_bf16(v0[0], v0[1]), cvt_pk_bf16(v0[2], v0[3])}; *(u32x2*)(p + 16) = (u32x2){cvt_pk_bf16(v1[0], v1[1]), cvt_pk_bf16(v1[2], v1[3])};
.LBB0_428:
	v_mul_f32_e32 v0, 0x3d372713, v38
	v_mul_f32_e32 v0, v38, v0
	v_fma_f32 v0, v38, v0, v38
	v_mul_f32_e32 v0, 0xbfcc422a, v0
	v_mul_f32_e32 v0, 0x3fb8aa3b, v0
	v_exp_f32_e32 v0, v0
	v_mov_b32_e32 v169, v1
	v_add_f32_e32 v0, 1.0, v0
	v_rcp_f32_e32 v0, v0
	s_nop 0
	v_mul_f32_e32 v0, v38, v0
	v_mul_f32_e32 v38, 0x3d372713, v34
	v_mul_f32_e32 v38, v34, v38
	v_fma_f32 v38, v34, v38, v34
	v_mul_f32_e32 v38, 0xbfcc422a, v38
	v_mul_f32_e32 v38, 0x3fb8aa3b, v38
	v_exp_f32_e32 v38, v38
	s_nop 0
	v_add_f32_e32 v38, 1.0, v38
	v_rcp_f32_e32 v38, v38
	s_nop 0
	v_mul_f32_e32 v38, v34, v38
	v_mul_f32_e32 v34, 0x3d372713, v39
	v_mul_f32_e32 v34, v39, v34
	v_fma_f32 v34, v39, v34, v39
	v_mul_f32_e32 v34, 0xbfcc422a, v34
	v_mul_f32_e32 v34, 0x3fb8aa3b, v34
	v_exp_f32_e32 v34, v34
	s_nop 0
	v_add_f32_e32 v34, 1.0, v34
	v_rcp_f32_e32 v34, v34
	s_nop 0
	v_mul_f32_e32 v39, v39, v34
	v_mul_f32_e32 v34, 0x3d372713, v35
	v_mul_f32_e32 v34, v35, v34
	v_fma_f32 v34, v35, v34, v35
	v_mul_f32_e32 v34, 0xbfcc422a, v34
	v_mul_f32_e32 v34, 0x3fb8aa3b, v34
	v_exp_f32_e32 v34, v34
	s_nop 0
	v_add_f32_e32 v34, 1.0, v34
	v_rcp_f32_e32 v34, v34
	s_nop 0
	v_mul_f32_e32 v44, v35, v34
	v_mul_f32_e32 v34, 0x3d372713, v40
	v_mul_f32_e32 v34, v40, v34
	v_fma_f32 v34, v40, v34, v40
	v_mul_f32_e32 v34, 0xbfcc422a, v34
	v_mul_f32_e32 v34, 0x3fb8aa3b, v34
	v_exp_f32_e32 v34, v34
	s_nop 0
	v_add_f32_e32 v34, 1.0, v34
	v_rcp_f32_e32 v34, v34
	s_nop 0
	v_mul_f32_e32 v40, v40, v34
	v_mul_f32_e32 v34, 0x3d372713, v36
	v_mul_f32_e32 v34, v36, v34
	v_fma_f32 v34, v36, v34, v36
	v_mul_f32_e32 v34, 0xbfcc422a, v34
	v_mul_f32_e32 v34, 0x3fb8aa3b, v34
	v_exp_f32_e32 v34, v34
	s_nop 0
	v_add_f32_e32 v34, 1.0, v34
	v_rcp_f32_e32 v34, v34
	s_nop 0
	v_mul_f32_e32 v45, v36, v34
	v_mul_f32_e32 v34, 0x3d372713, v41
	v_mul_f32_e32 v34, v41, v34
	v_fma_f32 v34, v41, v34, v41
	v_mul_f32_e32 v34, 0xbfcc422a, v34
	v_mul_f32_e32 v34, 0x3fb8aa3b, v34
	v_exp_f32_e32 v34, v34
	v_cvt_pk_bf16_f32 v36, v0, v39
	s_nop 0
	v_add_f32_e32 v34, 1.0, v34
	v_rcp_f32_e32 v34, v34
	s_nop 0
	v_mul_f32_e32 v41, v41, v34
	v_mul_f32_e32 v34, 0x3d372713, v37
	v_mul_f32_e32 v34, v37, v34
	v_fma_f32 v34, v37, v34, v37
	v_mul_f32_e32 v34, 0xbfcc422a, v34
	v_mul_f32_e32 v34, 0x3fb8aa3b, v34
	v_exp_f32_e32 v34, v34
	s_nop 0
	v_add_f32_e32 v34, 1.0, v34
	v_rcp_f32_e32 v34, v34
	s_nop 0
	v_mul_f32_e32 v46, v37, v34
	v_lshl_add_u64 v[34:35], v[58:59], 0, v[168:169]
	v_lshl_add_u64 v[42:43], v[34:35], 0, s[60:61]
	v_cvt_pk_bf16_f32 v37, v40, v41
	v_mov_b64_e32 v[216:217], v[36:37]
	v_cvt_pk_bf16_f32 v44, v38, v44
	v_cvt_pk_bf16_f32 v45, v45, v46
.LBB0_429:
	v_mov_b64_e32 v[218:219], v[44:45]
	s_nop 1
	v_permlane16_swap_b32_e32 v216, v218
	v_permlane16_swap_b32_e32 v217, v219
	v_lshl_add_u64 v[220:221], v[42:43], 0, v[222:223]
	flat_store_dwordx4 v[220:221], v[216:219]
	s_waitcnt vmcnt(0) lgkmcnt(0)
	v_mov_b64_e32 v[38:39], v[54:55]
	v_mov_b64_e32 v[34:35], v[50:51]
	s_and_b64 vcc, exec, s[54:55]
	v_mov_b64_e32 v[40:41], v[56:57]
	v_mov_b64_e32 v[36:37], v[52:53]
	s_cbranch_vccnz .LBB0_431
	s_lshr_b32 s15, s29, 6
	v_readlane_b32 s25, v255, 14
	s_add_i32 s15, s15, s25
	s_and_b32 s15, s15, 31
	v_mov_b32_e32 v0, s15
	v_cndmask_b32_e64 v0, v210, v0, s[38:39]
	v_lshlrev_b32_e32 v0, 7, v0
	v_lshl_add_u64 v[38:39], v[152:153], 0, v[0:1]
	flat_load_dwordx4 v[34:37], v[38:39]
	s_nop 0
	flat_load_dwordx4 v[38:41], v[38:39] offset:16

;     __device__ __forceinline__ void operator()(const f32x4 (&acc)[2][2][4][2], const Unit& u, int wr, int wc, int fr, int fq) const {
;     ...
;                 const int r = u.pm * BM + ai * HALF + wr * 64 + m * 16 + fr;
;                 int b, s, keyidx;
;                 if (lat) { b = r >> 11; s = r & 2047; keyidx = CTXL + s; } else { const int rc = r - T_LAT; b = rc >> 8; s = 0; keyidx = rc & 255; }
; #pragma unroll
;                 for (int bj = 0; bj < 2; ++bj) {
;                     f32x4 v0 = acc[ai][bj][m][0], v1 = acc[ai][bj][m][1];
;                     const bool is_rope = (pn >= 2 && pn <= 6) || (pn == 9 && bj == 0);
;                     if (is_rope && lat) {
;                         const float cs[4] = {c01[0], c01[2], c23[0], c23[2]}, sn[4] = {c01[1], c01[3], c23[1], c23[3]};
; #pragma unroll
;                         for (int i = 0; i < 4; ++i) { const float x0 = v0[i], x1 = v1[i]; v0[i] = x0 * cs[i] - x1 * sn[i]; v1[i] = x1 * cs[i] + x0 * sn[i]; }
;                     }
;                     const int ctb = bj * HALF + wc * 32 + 4 * fq;
;                     if (pn <= 1) {
; #pragma unroll
;                         for (int i = 0; i < 4; ++i) { v0[i] = gelu_tanh_f(v0[i]); v1[i] = gelu_tanh_f(v1[i]); }
;                         bf16_t* p = UV + (size_t)r * 512 + pn * 256 + ctb;
;                         *(u32x2*)p = (u32x2){cvt_pk_bf16(v0[0], v0[1]), cvt_pk_bf16(v0[2], v0[3])}; *(u32x2*)(p + 16) = (u32x2){cvt_pk_bf16(v1[0], v1[1]), cvt_pk_bf16(v1[2], v1[3])};
;                     } else if (pn <= 4) {
;                         v0 = v0 * QSCALE; v1 = v1 * QSCALE;
;                         bf16_t* p = (pn <= 3) ? QB + (size_t)r * 512 + (pn - 2) * 256 + ctb : QC + (size_t)r * 256 + ctb;
;                         *(u32x2*)p = (u32x2){cvt_pk_bf16(v0[0], v0[1]), cvt_pk_bf16(v0[2], v0[3])}; *(u32x2*)(p + 16) = (u32x2){cvt_pk_bf16(v1[0], v1[1]), cvt_pk_bf16(v1[2], v1[3])};
;                     } else if (pn <= 6) {
;                         const int ck = (pn - 5) * 256 + ctb, head = ck >> 7, cw = ck & 127;
;                         bf16_t* p = KB + ((size_t)(b * 4 + head) * NKEY + keyidx) * 128 + cw;
;                         *(u32x2*)p = (u32x2){cvt_pk_bf16(v0[0], v0[1]), cvt_pk_bf16(v0[2], v0[3])}; *(u32x2*)(p + 16) = (u32x2){cvt_pk_bf16(v1[0], v1[1]), cvt_pk_bf16(v1[2], v1[3])};
;                     } else if (pn <= 8) {
.LBB0_433:
	s_movk_i32 s15, 0x7ef
	v_bitop3_b32 v0, v74, s15, 32 bitop3:0xc8
	s_movk_i32 s15, 0xef
	v_add_u32_e32 v0, 0x100, v0
	v_bitop3_b32 v43, v74, s15, 32 bitop3:0xc8
	v_or_b32_e32 v42, 32, v74
	v_cndmask_b32_e64 v0, v43, v0, s[44:45]
	v_lshl_add_u64 v[44:45], s[18:19], 0, v[0:1]
	v_ashrrev_i32_e32 v43, 31, v42
	v_lshlrev_b64 v[48:49], 7, v[44:45]
	v_lshlrev_b64 v[44:45], 10, v[42:43]
	v_lshlrev_b64 v[46:47], 9, v[42:43]
	s_and_b64 vcc, exec, s[52:53]
	s_mov_b64 s[54:55], -1
	s_cbranch_vccnz .LBB0_463
	s_and_b64 vcc, exec, s[48:49]
	s_cbranch_vccnz .LBB0_444
	s_andn2_b64 vcc, exec, s[12:13]
	s_cbranch_vccnz .LBB0_441
	s_andn2_b64 vcc, exec, s[22:23]
	s_cbranch_vccnz .LBB0_438
	v_lshl_add_u64 v[58:59], v[154:155], 0, v[48:49]
	s_mov_b64 s[54:55], 0
	v_cvt_pk_bf16_f32 v42, v30, v31
	v_cvt_pk_bf16_f32 v43, v32, v33
	v_mov_b64_e32 v[216:217], v[42:43]
	v_cvt_pk_bf16_f32 v60, v26, v27
	v_cvt_pk_bf16_f32 v61, v28, v29
.LBB0_438:
	s_andn2_b64 vcc, exec, s[54:55]
	s_cbranch_vccnz .LBB0_440
	v_readlane_b32 s15, v255, 17
	s_ashr_i32 s15, s15, 7
	s_add_i32 s15, s14, s15
	v_mad_i64_i32 v[42:43], s[54:55], s15, v196, v[0:1]
	v_lshlrev_b64 v[42:43], 8, v[42:43]
	v_lshl_add_u64 v[58:59], v[156:157], 0, v[42:43]
	v_cvt_pk_bf16_f32 v42, v30, v31
	v_cvt_pk_bf16_f32 v43, v32, v33
	v_mov_b64_e32 v[216:217], v[42:43]
	v_cvt_pk_bf16_f32 v60, v26, v27
	v_cvt_pk_bf16_f32 v61, v28, v29

; __device__ __forceinline__ unsigned cvt_pk_bf16(float lo, float hi) { unsigned r; asm volatile("v_cvt_pk_bf16_f32 %0, %1, %2" : "=v"(r) : "v"(lo), "v"(hi)); return r; }
;     __device__ __forceinline__ void operator()(const f32x4 (&acc)[2][2][4][2], const Unit& u, int wr, int wc, int fr, int fq) const {
;     ...
;                     } else if (pn <= 8) {
;                         const int cv = (pn - 7) * 256 + ctb, head = cv >> 7, e = cv & 127;
;                         bf16_t* p = VBt + ((size_t)(b * 4 + head) * NKEY + keyidx) * 128 + e;
;                         *(u32x2*)p = (u32x2){cvt_pk_bf16(v0[0], v0[1]), cvt_pk_bf16(v0[2], v0[3])}; *(u32x2*)(p + 16) = (u32x2){cvt_pk_bf16(v1[0], v1[1]), cvt_pk_bf16(v1[2], v1[3])};
.LBB0_441:
	s_andn2_b64 vcc, exec, s[54:55]
	s_cbranch_vccnz .LBB0_443
	v_mad_i64_i32 v[42:43], s[54:55], s3, v196, v[0:1]
	v_lshlrev_b64 v[42:43], 8, v[42:43]
	v_lshl_add_u64 v[58:59], v[160:161], 0, v[42:43]
	v_cvt_pk_bf16_f32 v42, v30, v31
	v_cvt_pk_bf16_f32 v43, v32, v33
	v_mov_b64_e32 v[216:217], v[42:43]
	v_cvt_pk_bf16_f32 v60, v26, v27
	v_cvt_pk_bf16_f32 v61, v28, v29

; __device__ __forceinline__ unsigned cvt_pk_bf16(float lo, float hi) { unsigned r; asm volatile("v_cvt_pk_bf16_f32 %0, %1, %2" : "=v"(r) : "v"(lo), "v"(hi)); return r; }
;     __device__ __forceinline__ void operator()(const f32x4 (&acc)[2][2][4][2], const Unit& u, int wr, int wc, int fr, int fq) const {
;     ...
;                     } else if (pn <= 4) {
;                         v0 = v0 * QSCALE; v1 = v1 * QSCALE;
;                         bf16_t* p = (pn <= 3) ? QB + (size_t)r * 512 + (pn - 2) * 256 + ctb : QC + (size_t)r * 256 + ctb;
;                         *(u32x2*)p = (u32x2){cvt_pk_bf16(v0[0], v0[1]), cvt_pk_bf16(v0[2], v0[3])}; *(u32x2*)(p + 16) = (u32x2){cvt_pk_bf16(v1[0], v1[1]), cvt_pk_bf16(v1[2], v1[3])};
.LBB0_444:
	s_andn2_b64 vcc, exec, s[54:55]
	s_cbranch_vccnz .LBB0_446
	v_lshl_add_u64 v[66:67], s[8:9], 0, v[44:45]
	s_movk_i32 s54, 0xfc00
	v_lshl_add_u64 v[66:67], s[16:17], 1, v[66:67]
	s_mov_b32 s55, -1
	v_lshl_add_u64 v[58:59], s[0:1], 0, v[46:47]
	v_lshl_add_u64 v[66:67], v[66:67], 0, s[54:55]
	v_pk_mul_f32 v[60:61], v[30:31], s[74:75] op_sel_hi:[1,0]
	v_cndmask_b32_e64 v59, v67, v59, s[42:43]
	v_cndmask_b32_e64 v58, v66, v58, s[42:43]
	v_mov_b32_e32 v169, v1
	v_pk_mul_f32 v[42:43], v[32:33], s[74:75] op_sel_hi:[1,0]
	v_lshl_add_u64 v[58:59], v[58:59], 0, v[168:169]
	v_cvt_pk_bf16_f32 v60, v60, v61
	v_cvt_pk_bf16_f32 v61, v42, v43
	v_pk_mul_f32 v[62:63], v[28:29], s[74:75] op_sel_hi:[1,0]
	v_pk_mul_f32 v[64:65], v[26:27], s[74:75] op_sel_hi:[1,0]
	v_mov_b64_e32 v[216:217], v[60:61]
	v_cvt_pk_bf16_f32 v60, v64, v65
	v_cvt_pk_bf16_f32 v61, v62, v63

;     __device__ __forceinline__ void operator()(const f32x4 (&acc)[2][2][4][2], const Unit& u, int wr, int wc, int fr, int fq) const {
;     ...
;                 for (int bj = 0; bj < 2; ++bj) {
;                     f32x4 v0 = acc[ai][bj][m][0], v1 = acc[ai][bj][m][1];
;                     const bool is_rope = (pn >= 2 && pn <= 6) || (pn == 9 && bj == 0);
;                     if (is_rope && lat) {
;                         const float cs[4] = {c01[0], c01[2], c23[0], c23[2]}, sn[4] = {c01[1], c01[3], c23[1], c23[3]};
; #pragma unroll
;                         for (int i = 0; i < 4; ++i) { const float x0 = v0[i], x1 = v1[i]; v0[i] = x0 * cs[i] - x1 * sn[i]; v1[i] = x1 * cs[i] + x0 * sn[i]; }
;                     }
;                     const int ctb = bj * HALF + wc * 32 + 4 * fq;
;                     if (pn <= 1) {
; #pragma unroll
;                         for (int i = 0; i < 4; ++i) { v0[i] = gelu_tanh_f(v0[i]); v1[i] = gelu_tanh_f(v1[i]); }
;                         bf16_t* p = UV + (size_t)r * 512 + pn * 256 + ctb;
;                         *(u32x2*)p = (u32x2){cvt_pk_bf16(v0[0], v0[1]), cvt_pk_bf16(v0[2], v0[3])}; *(u32x2*)(p + 16) = (u32x2){cvt_pk_bf16(v1[0], v1[1]), cvt_pk_bf16(v1[2], v1[3])};
;                     } else if (pn <= 4) {
;                         v0 = v0 * QSCALE; v1 = v1 * QSCALE;
;                         bf16_t* p = (pn <= 3) ? QB + (size_t)r * 512 + (pn - 2) * 256 + ctb : QC + (size_t)r * 256 + ctb;
;                         *(u32x2*)p = (u32x2){cvt_pk_bf16(v0[0], v0[1]), cvt_pk_bf16(v0[2], v0[3])}; *(u32x2*)(p + 16) = (u32x2){cvt_pk_bf16(v1[0], v1[1]), cvt_pk_bf16(v1[2], v1[3])};
;                     } else if (pn <= 6) {
;                         const int ck = (pn - 5) * 256 + ctb, head = ck >> 7, cw = ck & 127;
;                         bf16_t* p = KB + ((size_t)(b * 4 + head) * NKEY + keyidx) * 128 + cw;
;                         *(u32x2*)p = (u32x2){cvt_pk_bf16(v0[0], v0[1]), cvt_pk_bf16(v0[2], v0[3])}; *(u32x2*)(p + 16) = (u32x2){cvt_pk_bf16(v1[0], v1[1]), cvt_pk_bf16(v1[2], v1[3])};
;                     } else if (pn <= 8) {
;                         const int cv = (pn - 7) * 256 + ctb, head = cv >> 7, e = cv & 127;
;                         bf16_t* p = VBt + ((size_t)(b * 4 + head) * NKEY + keyidx) * 128 + e;
.LBB0_447:
	s_and_b64 vcc, exec, s[50:51]
	v_mov_b64_e32 v[218:219], v[60:61]
	s_nop 1
	v_permlane16_swap_b32_e32 v216, v218
	v_permlane16_swap_b32_e32 v217, v219
	v_lshl_add_u64 v[220:221], v[58:59], 0, v[222:223]
	flat_store_dwordx4 v[220:221], v[216:219]
	s_cbranch_vccnz .LBB0_449

; __device__ __forceinline__ unsigned cvt_pk_bf16(float lo, float hi) { unsigned r; asm volatile("v_cvt_pk_bf16_f32 %0, %1, %2" : "=v"(r) : "v"(lo), "v"(hi)); return r; }
;     __device__ __forceinline__ void operator()(const f32x4 (&acc)[2][2][4][2], const Unit& u, int wr, int wc, int fr, int fq) const {
;     ...
;                     } else if (pn <= 6) {
;                         const int ck = (pn - 5) * 256 + ctb, head = ck >> 7, cw = ck & 127;
;                         bf16_t* p = KB + ((size_t)(b * 4 + head) * NKEY + keyidx) * 128 + cw;
;                         *(u32x2*)p = (u32x2){cvt_pk_bf16(v0[0], v0[1]), cvt_pk_bf16(v0[2], v0[3])}; *(u32x2*)(p + 16) = (u32x2){cvt_pk_bf16(v1[0], v1[1]), cvt_pk_bf16(v1[2], v1[3])};
;                     } else if (pn <= 8) {
;                         const int cv = (pn - 7) * 256 + ctb, head = cv >> 7, e = cv & 127;
;                         bf16_t* p = VBt + ((size_t)(b * 4 + head) * NKEY + keyidx) * 128 + e;
;                         *(u32x2*)p = (u32x2){cvt_pk_bf16(v0[0], v0[1]), cvt_pk_bf16(v0[2], v0[3])}; *(u32x2*)(p + 16) = (u32x2){cvt_pk_bf16(v1[0], v1[1]), cvt_pk_bf16(v1[2], v1[3])};
;                     } else {
;                         const int kv = wc >> 1, d = (wc & 1) * 32 + 4 * fq;
;                         if (bj == 0) {
;                             bf16_t* p = KC + ((size_t)(b * 2 + kv) * NKEY + keyidx) * 64 + d;
;                             *(u32x2*)p = (u32x2){cvt_pk_bf16(v0[0], v0[1]), cvt_pk_bf16(v0[2], v0[3])}; *(u32x2*)(p + 16) = (u32x2){cvt_pk_bf16(v1[0], v1[1]), cvt_pk_bf16(v1[2], v1[3])};
;                         } else {
;                             bf16_t* p = VCt + ((size_t)(b * 2 + kv) * NKEY + keyidx) * 64 + d;
;                             *(u32x2*)p = (u32x2){cvt_pk_bf16(v0[0], v0[1]), cvt_pk_bf16(v0[2], v0[3])}; *(u32x2*)(p + 16) = (u32x2){cvt_pk_bf16(v1[0], v1[1]), cvt_pk_bf16(v1[2], v1[3])};
;                         }
;                     }
.LBB0_449:
	s_and_b64 vcc, exec, s[52:53]
	s_mov_b64 s[54:55], -1
	s_cbranch_vccnz .LBB0_465
	s_and_b64 vcc, exec, s[48:49]
	s_cbranch_vccnz .LBB0_460
	s_andn2_b64 vcc, exec, s[12:13]
	s_cbranch_vccnz .LBB0_457
	s_andn2_b64 vcc, exec, s[22:23]
	s_cbranch_vccnz .LBB0_454
	v_lshl_add_u64 v[26:27], v[162:163], 0, v[48:49]
	v_cvt_pk_bf16_f32 v28, v22, v23
	v_cvt_pk_bf16_f32 v29, v24, v25
	s_mov_b64 s[54:55], 0
	v_mov_b64_e32 v[216:217], v[28:29]
	v_cvt_pk_bf16_f32 v28, v18, v19
	v_cvt_pk_bf16_f32 v29, v20, v21
.LBB0_454:
	s_andn2_b64 vcc, exec, s[54:55]
	s_cbranch_vccnz .LBB0_456
	s_add_i32 s15, s16, 0xfffff980
	s_ashr_i32 s15, s15, 7
	s_add_i32 s15, s14, s15
	v_mad_i64_i32 v[26:27], s[54:55], s15, v196, v[0:1]
	v_lshlrev_b64 v[26:27], 8, v[26:27]
	v_lshl_add_u64 v[26:27], v[156:157], 0, v[26:27]
	v_cvt_pk_bf16_f32 v28, v22, v23
	v_cvt_pk_bf16_f32 v29, v24, v25
	v_mov_b64_e32 v[216:217], v[28:29]
	v_cvt_pk_bf16_f32 v28, v18, v19
	v_cvt_pk_bf16_f32 v29, v20, v21

; __device__ __forceinline__ unsigned cvt_pk_bf16(float lo, float hi) { unsigned r; asm volatile("v_cvt_pk_bf16_f32 %0, %1, %2" : "=v"(r) : "v"(lo), "v"(hi)); return r; }
;     __device__ __forceinline__ void operator()(const f32x4 (&acc)[2][2][4][2], const Unit& u, int wr, int wc, int fr, int fq) const {
;     ...
;                     } else if (pn <= 8) {
;                         const int cv = (pn - 7) * 256 + ctb, head = cv >> 7, e = cv & 127;
;                         bf16_t* p = VBt + ((size_t)(b * 4 + head) * NKEY + keyidx) * 128 + e;
;                         *(u32x2*)p = (u32x2){cvt_pk_bf16(v0[0], v0[1]), cvt_pk_bf16(v0[2], v0[3])}; *(u32x2*)(p + 16) = (u32x2){cvt_pk_bf16(v1[0], v1[1]), cvt_pk_bf16(v1[2], v1[3])};
.LBB0_457:
	s_andn2_b64 vcc, exec, s[54:55]
	s_cbranch_vccnz .LBB0_459
	s_or_b32 s15, s3, 1
	v_mad_i64_i32 v[26:27], s[54:55], s15, v196, v[0:1]
	v_lshlrev_b64 v[26:27], 8, v[26:27]
	v_lshl_add_u64 v[26:27], v[160:161], 0, v[26:27]
	v_cvt_pk_bf16_f32 v28, v22, v23
	v_cvt_pk_bf16_f32 v29, v24, v25
	v_mov_b64_e32 v[216:217], v[28:29]
	v_cvt_pk_bf16_f32 v28, v18, v19
	v_cvt_pk_bf16_f32 v29, v20, v21

; __device__ __forceinline__ unsigned cvt_pk_bf16(float lo, float hi) { unsigned r; asm volatile("v_cvt_pk_bf16_f32 %0, %1, %2" : "=v"(r) : "v"(lo), "v"(hi)); return r; }
;     __device__ __forceinline__ void operator()(const f32x4 (&acc)[2][2][4][2], const Unit& u, int wr, int wc, int fr, int fq) const {
;     ...
;                     } else if (pn <= 4) {
;                         v0 = v0 * QSCALE; v1 = v1 * QSCALE;
;                         bf16_t* p = (pn <= 3) ? QB + (size_t)r * 512 + (pn - 2) * 256 + ctb : QC + (size_t)r * 256 + ctb;
;                         *(u32x2*)p = (u32x2){cvt_pk_bf16(v0[0], v0[1]), cvt_pk_bf16(v0[2], v0[3])}; *(u32x2*)(p + 16) = (u32x2){cvt_pk_bf16(v1[0], v1[1]), cvt_pk_bf16(v1[2], v1[3])};
.LBB0_460:
	s_andn2_b64 vcc, exec, s[54:55]
	s_cbranch_vccnz .LBB0_462
	v_lshl_add_u64 v[44:45], s[8:9], 0, v[44:45]
	s_movk_i32 s54, 0xfc00
	v_lshl_add_u64 v[44:45], s[16:17], 1, v[44:45]
	s_mov_b32 s55, -1
	v_lshl_add_u64 v[26:27], s[0:1], 0, v[46:47]
	v_lshl_add_u64 v[44:45], v[44:45], 0, s[54:55]
	v_cndmask_b32_e64 v27, v45, v27, s[42:43]
	v_cndmask_b32_e64 v26, v44, v26, s[42:43]
	v_mov_b32_e32 v169, v1
	v_lshl_add_u64 v[44:45], v[26:27], 0, v[168:169]
	v_pk_mul_f32 v[28:29], v[24:25], s[74:75] op_sel_hi:[1,0]
	v_pk_mul_f32 v[30:31], v[22:23], s[74:75] op_sel_hi:[1,0]
	v_lshl_add_u64 v[26:27], v[44:45], 0, s[60:61]
	v_pk_mul_f32 v[32:33], v[20:21], s[74:75] op_sel_hi:[1,0]
	v_pk_mul_f32 v[48:49], v[18:19], s[74:75] op_sel_hi:[1,0]
	v_cvt_pk_bf16_f32 v30, v30, v31
	v_cvt_pk_bf16_f32 v31, v28, v29
	v_mov_b64_e32 v[216:217], v[30:31]
	v_cvt_pk_bf16_f32 v28, v48, v49
	v_cvt_pk_bf16_f32 v29, v32, v33

; __device__ __forceinline__ unsigned cvt_pk_bf16(float lo, float hi) { unsigned r; asm volatile("v_cvt_pk_bf16_f32 %0, %1, %2" : "=v"(r) : "v"(lo), "v"(hi)); return r; }
; __device__ __forceinline__ float gelu_tanh_f(float x) { const float y = 1.5957691216057308f * (x + 0.044715f * x * x * x); return x * __builtin_amdgcn_rcpf(1.f + __expf(-y)); }
;     __device__ __forceinline__ void operator()(const f32x4 (&acc)[2][2][4][2], const Unit& u, int wr, int wc, int fr, int fq) const {
;     ...
;                     if (pn <= 1) {
; #pragma unroll
;                         for (int i = 0; i < 4; ++i) { v0[i] = gelu_tanh_f(v0[i]); v1[i] = gelu_tanh_f(v1[i]); }
;                         bf16_t* p = UV + (size_t)r * 512 + pn * 256 + ctb;
;                         *(u32x2*)p = (u32x2){cvt_pk_bf16(v0[0], v0[1]), cvt_pk_bf16(v0[2], v0[3])}; *(u32x2*)(p + 16) = (u32x2){cvt_pk_bf16(v1[0], v1[1]), cvt_pk_bf16(v1[2], v1[3])};
.LBB0_464:
	v_mul_f32_e32 v58, 0x3d372713, v30
	v_mul_f32_e32 v58, v30, v58
	v_fma_f32 v58, v30, v58, v30
	v_mul_f32_e32 v58, 0xbfcc422a, v58
	v_mul_f32_e32 v58, 0x3fb8aa3b, v58
	v_exp_f32_e32 v58, v58
	v_mov_b32_e32 v169, v1
	v_add_f32_e32 v58, 1.0, v58
	v_rcp_f32_e32 v58, v58
	s_nop 0
	v_mul_f32_e32 v30, v30, v58
	v_mul_f32_e32 v58, 0x3d372713, v26
	v_mul_f32_e32 v58, v26, v58
	v_fma_f32 v58, v26, v58, v26
	v_mul_f32_e32 v58, 0xbfcc422a, v58
	v_mul_f32_e32 v58, 0x3fb8aa3b, v58
	v_exp_f32_e32 v58, v58
	s_nop 0
	v_add_f32_e32 v58, 1.0, v58
	v_rcp_f32_e32 v58, v58
	s_nop 0
	v_mul_f32_e32 v60, v26, v58
	v_mul_f32_e32 v26, 0x3d372713, v31
	v_mul_f32_e32 v26, v31, v26
	v_fma_f32 v26, v31, v26, v31
	v_mul_f32_e32 v26, 0xbfcc422a, v26
	v_mul_f32_e32 v26, 0x3fb8aa3b, v26
	v_exp_f32_e32 v26, v26
	v_lshl_add_u64 v[58:59], v[42:43], 0, v[168:169]
	v_add_f32_e32 v26, 1.0, v26
	v_rcp_f32_e32 v26, v26
	s_nop 0
	v_mul_f32_e32 v26, v31, v26
	v_mul_f32_e32 v31, 0x3d372713, v27
	v_mul_f32_e32 v31, v27, v31
	v_fma_f32 v31, v27, v31, v27
	v_mul_f32_e32 v31, 0xbfcc422a, v31
	v_mul_f32_e32 v31, 0x3fb8aa3b, v31
	v_exp_f32_e32 v31, v31
	v_cvt_pk_bf16_f32 v26, v30, v26
	s_nop 0
	v_add_f32_e32 v31, 1.0, v31
	v_rcp_f32_e32 v31, v31
	s_nop 0
	v_mul_f32_e32 v31, v27, v31
	v_mul_f32_e32 v27, 0x3d372713, v32
	v_mul_f32_e32 v27, v32, v27
	v_fma_f32 v27, v32, v27, v32
	v_mul_f32_e32 v27, 0xbfcc422a, v27
	v_mul_f32_e32 v27, 0x3fb8aa3b, v27
	v_exp_f32_e32 v27, v27
	s_nop 0
	v_add_f32_e32 v27, 1.0, v27
	v_rcp_f32_e32 v27, v27
	s_nop 0
	v_mul_f32_e32 v27, v32, v27
	v_mul_f32_e32 v32, 0x3d372713, v28
	v_mul_f32_e32 v32, v28, v32
	v_fma_f32 v32, v28, v32, v28
	v_mul_f32_e32 v32, 0xbfcc422a, v32
	v_mul_f32_e32 v32, 0x3fb8aa3b, v32
	v_exp_f32_e32 v32, v32
	s_nop 0
	v_add_f32_e32 v32, 1.0, v32
	v_rcp_f32_e32 v32, v32
	s_nop 0
	v_mul_f32_e32 v28, v28, v32
	v_mul_f32_e32 v32, 0x3d372713, v33
	v_mul_f32_e32 v32, v33, v32
	v_fma_f32 v32, v33, v32, v33
	v_mul_f32_e32 v32, 0xbfcc422a, v32
	v_mul_f32_e32 v32, 0x3fb8aa3b, v32
	v_exp_f32_e32 v32, v32
	s_nop 0
	v_add_f32_e32 v32, 1.0, v32
	v_rcp_f32_e32 v32, v32
	s_nop 0
	v_mul_f32_e32 v32, v33, v32
	v_mul_f32_e32 v33, 0x3d372713, v29
	v_mul_f32_e32 v33, v29, v33
	v_fma_f32 v33, v29, v33, v29
	v_mul_f32_e32 v33, 0xbfcc422a, v33
	v_mul_f32_e32 v33, 0x3fb8aa3b, v33
	v_exp_f32_e32 v33, v33
	v_cvt_pk_bf16_f32 v27, v27, v32
	v_mov_b64_e32 v[216:217], v[26:27]
	v_cvt_pk_bf16_f32 v60, v60, v31
	v_add_f32_e32 v33, 1.0, v33
	v_rcp_f32_e32 v33, v33
	s_nop 0
	v_mul_f32_e32 v29, v29, v33
	v_cvt_pk_bf16_f32 v61, v28, v29
	s_and_b64 vcc, exec, s[50:51]
	v_mov_b64_e32 v[218:219], v[60:61]
	s_nop 1
	v_permlane16_swap_b32_e32 v216, v218
	v_permlane16_swap_b32_e32 v217, v219
	v_lshl_add_u64 v[220:221], v[58:59], 0, v[222:223]
	flat_store_dwordx4 v[220:221], v[216:219]
	s_cbranch_vccnz .LBB0_449
	s_branch .LBB0_448

;     __device__ __forceinline__ void operator()(const f32x4 (&acc)[2][2][4][2], const Unit& u, int wr, int wc, int fr, int fq) const {
;     ...
;                     const bool is_rope = (pn >= 2 && pn <= 6) || (pn == 9 && bj == 0);
;                     if (is_rope && lat) {
;                         const float cs[4] = {c01[0], c01[2], c23[0], c23[2]}, sn[4] = {c01[1], c01[3], c23[1], c23[3]};
; #pragma unroll
;                         for (int i = 0; i < 4; ++i) { const float x0 = v0[i], x1 = v1[i]; v0[i] = x0 * cs[i] - x1 * sn[i]; v1[i] = x1 * cs[i] + x0 * sn[i]; }
;                     }
;                     const int ctb = bj * HALF + wc * 32 + 4 * fq;
;                     if (pn <= 1) {
; #pragma unroll
;                         for (int i = 0; i < 4; ++i) { v0[i] = gelu_tanh_f(v0[i]); v1[i] = gelu_tanh_f(v1[i]); }
;                         bf16_t* p = UV + (size_t)r * 512 + pn * 256 + ctb;
;                         *(u32x2*)p = (u32x2){cvt_pk_bf16(v0[0], v0[1]), cvt_pk_bf16(v0[2], v0[3])}; *(u32x2*)(p + 16) = (u32x2){cvt_pk_bf16(v1[0], v1[1]), cvt_pk_bf16(v1[2], v1[3])};
;                     } else if (pn <= 4) {
;                         v0 = v0 * QSCALE; v1 = v1 * QSCALE;
;                         bf16_t* p = (pn <= 3) ? QB + (size_t)r * 512 + (pn - 2) * 256 + ctb : QC + (size_t)r * 256 + ctb;
;                         *(u32x2*)p = (u32x2){cvt_pk_bf16(v0[0], v0[1]), cvt_pk_bf16(v0[2], v0[3])}; *(u32x2*)(p + 16) = (u32x2){cvt_pk_bf16(v1[0], v1[1]), cvt_pk_bf16(v1[2], v1[3])};
;                     } else if (pn <= 6) {
;                         const int ck = (pn - 5) * 256 + ctb, head = ck >> 7, cw = ck & 127;
;                         bf16_t* p = KB + ((size_t)(b * 4 + head) * NKEY + keyidx) * 128 + cw;
;                         *(u32x2*)p = (u32x2){cvt_pk_bf16(v0[0], v0[1]), cvt_pk_bf16(v0[2], v0[3])}; *(u32x2*)(p + 16) = (u32x2){cvt_pk_bf16(v1[0], v1[1]), cvt_pk_bf16(v1[2], v1[3])};
;                     } else if (pn <= 8) {
;                         const int cv = (pn - 7) * 256 + ctb, head = cv >> 7, e = cv & 127;
;                         bf16_t* p = VBt + ((size_t)(b * 4 + head) * NKEY + keyidx) * 128 + e;
;                         *(u32x2*)p = (u32x2){cvt_pk_bf16(v0[0], v0[1]), cvt_pk_bf16(v0[2], v0[3])}; *(u32x2*)(p + 16) = (u32x2){cvt_pk_bf16(v1[0], v1[1]), cvt_pk_bf16(v1[2], v1[3])};
;                     } else {
.LBB0_466:
	v_mul_f32_e32 v0, 0x3d372713, v22
	v_mul_f32_e32 v0, v22, v0
	v_fma_f32 v0, v22, v0, v22
	v_mul_f32_e32 v0, 0xbfcc422a, v0
	v_mul_f32_e32 v0, 0x3fb8aa3b, v0
	v_exp_f32_e32 v0, v0
	v_mov_b32_e32 v169, v1
	v_add_f32_e32 v0, 1.0, v0
	v_rcp_f32_e32 v0, v0
	s_nop 0
	v_mul_f32_e32 v0, v22, v0
	v_mul_f32_e32 v22, 0x3d372713, v18
	v_mul_f32_e32 v22, v18, v22
	v_fma_f32 v22, v18, v22, v18
	v_mul_f32_e32 v22, 0xbfcc422a, v22
	v_mul_f32_e32 v22, 0x3fb8aa3b, v22
	v_exp_f32_e32 v22, v22
	s_nop 0
	v_add_f32_e32 v22, 1.0, v22
	v_rcp_f32_e32 v22, v22
	s_nop 0
	v_mul_f32_e32 v22, v18, v22
	v_mul_f32_e32 v18, 0x3d372713, v23
	v_mul_f32_e32 v18, v23, v18
	v_fma_f32 v18, v23, v18, v23
	v_mul_f32_e32 v18, 0xbfcc422a, v18
	v_mul_f32_e32 v18, 0x3fb8aa3b, v18
	v_exp_f32_e32 v18, v18
	s_nop 0
	v_add_f32_e32 v18, 1.0, v18
	v_rcp_f32_e32 v18, v18
	s_nop 0
	v_mul_f32_e32 v23, v23, v18
	v_mul_f32_e32 v18, 0x3d372713, v19
	v_mul_f32_e32 v18, v19, v18
	v_fma_f32 v18, v19, v18, v19
	v_mul_f32_e32 v18, 0xbfcc422a, v18
	v_mul_f32_e32 v18, 0x3fb8aa3b, v18
	v_exp_f32_e32 v18, v18
	s_nop 0
	v_add_f32_e32 v18, 1.0, v18
	v_rcp_f32_e32 v18, v18
	s_nop 0
	v_mul_f32_e32 v28, v19, v18
	v_mul_f32_e32 v18, 0x3d372713, v24
	v_mul_f32_e32 v18, v24, v18
	v_fma_f32 v18, v24, v18, v24
	v_mul_f32_e32 v18, 0xbfcc422a, v18
	v_mul_f32_e32 v18, 0x3fb8aa3b, v18
	v_exp_f32_e32 v18, v18
	s_nop 0
	v_add_f32_e32 v18, 1.0, v18
	v_rcp_f32_e32 v18, v18
	s_nop 0
	v_mul_f32_e32 v24, v24, v18
	v_mul_f32_e32 v18, 0x3d372713, v20
	v_mul_f32_e32 v18, v20, v18
	v_fma_f32 v18, v20, v18, v20
	v_mul_f32_e32 v18, 0xbfcc422a, v18
	v_mul_f32_e32 v18, 0x3fb8aa3b, v18
	v_exp_f32_e32 v18, v18
	s_nop 0
	v_add_f32_e32 v18, 1.0, v18
	v_rcp_f32_e32 v18, v18
	s_nop 0
	v_mul_f32_e32 v29, v20, v18
	v_mul_f32_e32 v18, 0x3d372713, v25
	v_mul_f32_e32 v18, v25, v18
	v_fma_f32 v18, v25, v18, v25
	v_mul_f32_e32 v18, 0xbfcc422a, v18
	v_mul_f32_e32 v18, 0x3fb8aa3b, v18
	v_exp_f32_e32 v18, v18
	v_cvt_pk_bf16_f32 v20, v0, v23
	s_nop 0
	v_add_f32_e32 v18, 1.0, v18
	v_rcp_f32_e32 v18, v18
	s_nop 0
	v_mul_f32_e32 v25, v25, v18
	v_mul_f32_e32 v18, 0x3d372713, v21
	v_mul_f32_e32 v18, v21, v18
	v_fma_f32 v18, v21, v18, v21
	v_mul_f32_e32 v18, 0xbfcc422a, v18
	v_mul_f32_e32 v18, 0x3fb8aa3b, v18
	v_exp_f32_e32 v18, v18
	s_nop 0
	v_add_f32_e32 v18, 1.0, v18
	v_rcp_f32_e32 v18, v18
	s_nop 0
	v_mul_f32_e32 v30, v21, v18
	v_lshl_add_u64 v[18:19], v[42:43], 0, v[168:169]
	v_lshl_add_u64 v[26:27], v[18:19], 0, s[60:61]
	v_cvt_pk_bf16_f32 v21, v24, v25
	v_mov_b64_e32 v[216:217], v[20:21]
	v_cvt_pk_bf16_f32 v28, v22, v28
	v_cvt_pk_bf16_f32 v29, v29, v30
.LBB0_467:
	v_mov_b64_e32 v[218:219], v[28:29]
	s_nop 1
	v_permlane16_swap_b32_e32 v216, v218
	v_permlane16_swap_b32_e32 v217, v219
	v_lshl_add_u64 v[220:221], v[26:27], 0, v[222:223]
	flat_store_dwordx4 v[220:221], v[216:219]
	s_and_b64 vcc, exec, s[46:47]
	s_cbranch_vccnz .LBB0_469
	s_waitcnt vmcnt(0) lgkmcnt(0)
	v_mul_f32_e32 v26, v12, v39
	v_mul_f32_e32 v28, v12, v38
	v_mov_b32_e32 v12, v17
	v_mov_b32_e32 v20, v35
	v_mov_b32_e32 v21, v37
	v_mul_f32_e32 v24, v16, v38
	v_mul_f32_e32 v30, v16, v39
	v_pk_mul_f32 v[32:33], v[12:13], v[40:41]
	v_mov_b32_e32 v16, v13
	v_mov_b32_e32 v18, v34
	v_mov_b32_e32 v19, v36
	v_pk_mul_f32 v[22:23], v[10:11], v[20:21]
	v_mov_b32_e32 v25, v32
	v_mov_b32_e32 v27, v33
	v_pk_mul_f32 v[12:13], v[16:17], v[40:41]
	v_pk_mul_f32 v[10:11], v[10:11], v[18:19]
	v_pk_fma_f32 v[18:19], v[14:15], v[18:19], v[22:23] neg_lo:[0,0,1] neg_hi:[0,0,1]
	v_pk_add_f32 v[22:23], v[24:25], v[26:27] neg_lo:[0,1] neg_hi:[0,1]
	v_mov_b32_e32 v31, v13
	v_mov_b32_e32 v29, v12
	v_pk_fma_f32 v[10:11], v[14:15], v[20:21], v[10:11]
	v_pk_add_f32 v[12:13], v[30:31], v[28:29]
	v_mov_b32_e32 v14, v18
	v_mov_b32_e32 v15, v19
	v_mov_b32_e32 v16, v22
	v_mov_b32_e32 v17, v23
.LBB0_469:
	s_movk_i32 s15, 0x7ff
	v_bitop3_b32 v0, v74, s15, 48 bitop3:0xc8
	s_movk_i32 s15, 0xff
	v_add_u32_e32 v0, 0x100, v0
	v_bitop3_b32 v19, v74, s15, 48 bitop3:0xc8
	v_or_b32_e32 v18, 48, v74
	v_cndmask_b32_e64 v0, v19, v0, s[44:45]
	v_lshl_add_u64 v[20:21], s[18:19], 0, v[0:1]
	v_ashrrev_i32_e32 v19, 31, v18
	v_lshlrev_b64 v[24:25], 7, v[20:21]
	v_lshlrev_b64 v[20:21], 10, v[18:19]
	v_lshlrev_b64 v[22:23], 9, v[18:19]
	s_and_b64 vcc, exec, s[52:53]
	s_mov_b64 s[18:19], -1
	s_cbranch_vccnz .LBB0_499
	s_and_b64 vcc, exec, s[48:49]
	s_cbranch_vccnz .LBB0_480
	s_andn2_b64 vcc, exec, s[12:13]
	s_cbranch_vccnz .LBB0_477
	s_andn2_b64 vcc, exec, s[22:23]
	s_cbranch_vccnz .LBB0_474
	v_lshl_add_u64 v[26:27], v[154:155], 0, v[24:25]
	s_mov_b64 s[18:19], 0
	v_cvt_pk_bf16_f32 v18, v14, v15
	v_cvt_pk_bf16_f32 v19, v16, v17
	v_mov_b64_e32 v[216:217], v[18:19]
	v_cvt_pk_bf16_f32 v28, v10, v11
	v_cvt_pk_bf16_f32 v29, v12, v13
.LBB0_474:
	s_andn2_b64 vcc, exec, s[18:19]
	s_cbranch_vccnz .LBB0_476
	v_readlane_b32 s15, v255, 17
	s_ashr_i32 s15, s15, 7
	s_add_i32 s15, s14, s15
	v_mad_i64_i32 v[18:19], s[18:19], s15, v196, v[0:1]
	v_lshlrev_b64 v[18:19], 8, v[18:19]
	v_lshl_add_u64 v[26:27], v[156:157], 0, v[18:19]
	v_cvt_pk_bf16_f32 v18, v14, v15
	v_cvt_pk_bf16_f32 v19, v16, v17
	v_mov_b64_e32 v[216:217], v[18:19]
	v_cvt_pk_bf16_f32 v28, v10, v11
	v_cvt_pk_bf16_f32 v29, v12, v13

; __device__ __forceinline__ unsigned cvt_pk_bf16(float lo, float hi) { unsigned r; asm volatile("v_cvt_pk_bf16_f32 %0, %1, %2" : "=v"(r) : "v"(lo), "v"(hi)); return r; }
;     __device__ __forceinline__ void operator()(const f32x4 (&acc)[2][2][4][2], const Unit& u, int wr, int wc, int fr, int fq) const {
;     ...
;                     } else if (pn <= 8) {
;                         const int cv = (pn - 7) * 256 + ctb, head = cv >> 7, e = cv & 127;
;                         bf16_t* p = VBt + ((size_t)(b * 4 + head) * NKEY + keyidx) * 128 + e;
;                         *(u32x2*)p = (u32x2){cvt_pk_bf16(v0[0], v0[1]), cvt_pk_bf16(v0[2], v0[3])}; *(u32x2*)(p + 16) = (u32x2){cvt_pk_bf16(v1[0], v1[1]), cvt_pk_bf16(v1[2], v1[3])};
.LBB0_477:
	s_andn2_b64 vcc, exec, s[18:19]
	s_cbranch_vccnz .LBB0_479
	v_mad_i64_i32 v[18:19], s[18:19], s3, v196, v[0:1]
	v_lshlrev_b64 v[18:19], 8, v[18:19]
	v_lshl_add_u64 v[26:27], v[160:161], 0, v[18:19]
	v_cvt_pk_bf16_f32 v18, v14, v15
	v_cvt_pk_bf16_f32 v19, v16, v17
	v_mov_b64_e32 v[216:217], v[18:19]
	v_cvt_pk_bf16_f32 v28, v10, v11
	v_cvt_pk_bf16_f32 v29, v12, v13

; __device__ __forceinline__ unsigned cvt_pk_bf16(float lo, float hi) { unsigned r; asm volatile("v_cvt_pk_bf16_f32 %0, %1, %2" : "=v"(r) : "v"(lo), "v"(hi)); return r; }
;     __device__ __forceinline__ void operator()(const f32x4 (&acc)[2][2][4][2], const Unit& u, int wr, int wc, int fr, int fq) const {
;     ...
;                     } else if (pn <= 4) {
;                         v0 = v0 * QSCALE; v1 = v1 * QSCALE;
;                         bf16_t* p = (pn <= 3) ? QB + (size_t)r * 512 + (pn - 2) * 256 + ctb : QC + (size_t)r * 256 + ctb;
;                         *(u32x2*)p = (u32x2){cvt_pk_bf16(v0[0], v0[1]), cvt_pk_bf16(v0[2], v0[3])}; *(u32x2*)(p + 16) = (u32x2){cvt_pk_bf16(v1[0], v1[1]), cvt_pk_bf16(v1[2], v1[3])};
.LBB0_480:
	s_andn2_b64 vcc, exec, s[18:19]
	s_cbranch_vccnz .LBB0_482
	v_lshl_add_u64 v[42:43], s[8:9], 0, v[20:21]
	s_movk_i32 s18, 0xfc00
	v_lshl_add_u64 v[42:43], s[16:17], 1, v[42:43]
	s_mov_b32 s19, -1
	v_lshl_add_u64 v[26:27], s[0:1], 0, v[22:23]
	v_lshl_add_u64 v[42:43], v[42:43], 0, s[18:19]
	v_pk_mul_f32 v[28:29], v[14:15], s[74:75] op_sel_hi:[1,0]
	v_cndmask_b32_e64 v27, v43, v27, s[42:43]
	v_cndmask_b32_e64 v26, v42, v26, s[42:43]
	v_mov_b32_e32 v169, v1
	v_pk_mul_f32 v[18:19], v[16:17], s[74:75] op_sel_hi:[1,0]
	v_lshl_add_u64 v[26:27], v[26:27], 0, v[168:169]
	v_cvt_pk_bf16_f32 v28, v28, v29
	v_cvt_pk_bf16_f32 v29, v18, v19
	v_pk_mul_f32 v[30:31], v[12:13], s[74:75] op_sel_hi:[1,0]
	v_pk_mul_f32 v[32:33], v[10:11], s[74:75] op_sel_hi:[1,0]
	v_mov_b64_e32 v[216:217], v[28:29]
	v_cvt_pk_bf16_f32 v28, v32, v33
	v_cvt_pk_bf16_f32 v29, v30, v31

; __device__ __forceinline__ unsigned cvt_pk_bf16(float lo, float hi) { unsigned r; asm volatile("v_cvt_pk_bf16_f32 %0, %1, %2" : "=v"(r) : "v"(lo), "v"(hi)); return r; }
;     __device__ __forceinline__ void operator()(const f32x4 (&acc)[2][2][4][2], const Unit& u, int wr, int wc, int fr, int fq) const {
;     ...
;                         bf16_t* p = UV + (size_t)r * 512 + pn * 256 + ctb;
;                         *(u32x2*)p = (u32x2){cvt_pk_bf16(v0[0], v0[1]), cvt_pk_bf16(v0[2], v0[3])}; *(u32x2*)(p + 16) = (u32x2){cvt_pk_bf16(v1[0], v1[1]), cvt_pk_bf16(v1[2], v1[3])};
.LBB0_483:
	s_and_b64 vcc, exec, s[50:51]
	v_mov_b64_e32 v[218:219], v[28:29]
	s_nop 1
	v_permlane16_swap_b32_e32 v216, v218
	v_permlane16_swap_b32_e32 v217, v219
	v_lshl_add_u64 v[220:221], v[26:27], 0, v[222:223]
	flat_store_dwordx4 v[220:221], v[216:219]
	s_cbranch_vccnz .LBB0_485

; __device__ __forceinline__ unsigned cvt_pk_bf16(float lo, float hi) { unsigned r; asm volatile("v_cvt_pk_bf16_f32 %0, %1, %2" : "=v"(r) : "v"(lo), "v"(hi)); return r; }
;     __device__ __forceinline__ void operator()(const f32x4 (&acc)[2][2][4][2], const Unit& u, int wr, int wc, int fr, int fq) const {
;     ...
;                     } else if (pn <= 6) {
;                         const int ck = (pn - 5) * 256 + ctb, head = ck >> 7, cw = ck & 127;
;                         bf16_t* p = KB + ((size_t)(b * 4 + head) * NKEY + keyidx) * 128 + cw;
;                         *(u32x2*)p = (u32x2){cvt_pk_bf16(v0[0], v0[1]), cvt_pk_bf16(v0[2], v0[3])}; *(u32x2*)(p + 16) = (u32x2){cvt_pk_bf16(v1[0], v1[1]), cvt_pk_bf16(v1[2], v1[3])};
;                     } else if (pn <= 8) {
;                         const int cv = (pn - 7) * 256 + ctb, head = cv >> 7, e = cv & 127;
;                         bf16_t* p = VBt + ((size_t)(b * 4 + head) * NKEY + keyidx) * 128 + e;
;                         *(u32x2*)p = (u32x2){cvt_pk_bf16(v0[0], v0[1]), cvt_pk_bf16(v0[2], v0[3])}; *(u32x2*)(p + 16) = (u32x2){cvt_pk_bf16(v1[0], v1[1]), cvt_pk_bf16(v1[2], v1[3])};
;                     } else {
;                         const int kv = wc >> 1, d = (wc & 1) * 32 + 4 * fq;
;                         if (bj == 0) {
;                             bf16_t* p = KC + ((size_t)(b * 2 + kv) * NKEY + keyidx) * 64 + d;
;                             *(u32x2*)p = (u32x2){cvt_pk_bf16(v0[0], v0[1]), cvt_pk_bf16(v0[2], v0[3])}; *(u32x2*)(p + 16) = (u32x2){cvt_pk_bf16(v1[0], v1[1]), cvt_pk_bf16(v1[2], v1[3])};
;                         } else {
;                             bf16_t* p = VCt + ((size_t)(b * 2 + kv) * NKEY + keyidx) * 64 + d;
;                             *(u32x2*)p = (u32x2){cvt_pk_bf16(v0[0], v0[1]), cvt_pk_bf16(v0[2], v0[3])}; *(u32x2*)(p + 16) = (u32x2){cvt_pk_bf16(v1[0], v1[1]), cvt_pk_bf16(v1[2], v1[3])};
;                         }
.LBB0_485:
	s_and_b64 vcc, exec, s[52:53]
	s_mov_b64 s[18:19], -1
	s_cbranch_vccnz .LBB0_501
	s_and_b64 vcc, exec, s[48:49]
	s_cbranch_vccnz .LBB0_496
	s_andn2_b64 vcc, exec, s[12:13]
	s_mov_b64 s[12:13], -1
	s_cbranch_vccnz .LBB0_493
	s_andn2_b64 vcc, exec, s[22:23]
	s_cbranch_vccnz .LBB0_490
	v_lshl_add_u64 v[10:11], v[162:163], 0, v[24:25]
	v_cvt_pk_bf16_f32 v12, v6, v7
	v_cvt_pk_bf16_f32 v13, v8, v9
	s_mov_b64 s[12:13], 0
	v_mov_b64_e32 v[216:217], v[12:13]
	v_cvt_pk_bf16_f32 v12, v2, v3
	v_cvt_pk_bf16_f32 v13, v4, v5
.LBB0_490:
	s_andn2_b64 vcc, exec, s[12:13]
	s_cbranch_vccnz .LBB0_492
	s_add_i32 s12, s20, 0xfffff980
	s_ashr_i32 s12, s12, 7
	s_add_i32 s14, s14, s12
	v_mad_i64_i32 v[10:11], s[12:13], s14, v196, v[0:1]
	v_lshlrev_b64 v[10:11], 8, v[10:11]
	v_lshl_add_u64 v[10:11], v[156:157], 0, v[10:11]
	v_cvt_pk_bf16_f32 v12, v6, v7
	v_cvt_pk_bf16_f32 v13, v8, v9
	v_mov_b64_e32 v[216:217], v[12:13]
	v_cvt_pk_bf16_f32 v12, v2, v3
	v_cvt_pk_bf16_f32 v13, v4, v5

; __device__ __forceinline__ unsigned cvt_pk_bf16(float lo, float hi) { unsigned r; asm volatile("v_cvt_pk_bf16_f32 %0, %1, %2" : "=v"(r) : "v"(lo), "v"(hi)); return r; }
;     __device__ __forceinline__ void operator()(const f32x4 (&acc)[2][2][4][2], const Unit& u, int wr, int wc, int fr, int fq) const {
;     ...
;                     } else if (pn <= 8) {
;                         const int cv = (pn - 7) * 256 + ctb, head = cv >> 7, e = cv & 127;
;                         bf16_t* p = VBt + ((size_t)(b * 4 + head) * NKEY + keyidx) * 128 + e;
;                         *(u32x2*)p = (u32x2){cvt_pk_bf16(v0[0], v0[1]), cvt_pk_bf16(v0[2], v0[3])}; *(u32x2*)(p + 16) = (u32x2){cvt_pk_bf16(v1[0], v1[1]), cvt_pk_bf16(v1[2], v1[3])};
.LBB0_493:
	s_andn2_b64 vcc, exec, s[12:13]
	s_cbranch_vccnz .LBB0_495
	s_or_b32 s3, s3, 1
	v_mad_i64_i32 v[10:11], s[12:13], s3, v196, v[0:1]
	v_lshlrev_b64 v[10:11], 8, v[10:11]
	v_lshl_add_u64 v[10:11], v[160:161], 0, v[10:11]
	v_cvt_pk_bf16_f32 v12, v6, v7
	v_cvt_pk_bf16_f32 v13, v8, v9
	v_mov_b64_e32 v[216:217], v[12:13]
	v_cvt_pk_bf16_f32 v12, v2, v3
	v_cvt_pk_bf16_f32 v13, v4, v5

; __device__ __forceinline__ unsigned cvt_pk_bf16(float lo, float hi) { unsigned r; asm volatile("v_cvt_pk_bf16_f32 %0, %1, %2" : "=v"(r) : "v"(lo), "v"(hi)); return r; }
;     __device__ __forceinline__ void operator()(const f32x4 (&acc)[2][2][4][2], const Unit& u, int wr, int wc, int fr, int fq) const {
;     ...
;                     } else if (pn <= 4) {
;                         v0 = v0 * QSCALE; v1 = v1 * QSCALE;
;                         bf16_t* p = (pn <= 3) ? QB + (size_t)r * 512 + (pn - 2) * 256 + ctb : QC + (size_t)r * 256 + ctb;
;                         *(u32x2*)p = (u32x2){cvt_pk_bf16(v0[0], v0[1]), cvt_pk_bf16(v0[2], v0[3])}; *(u32x2*)(p + 16) = (u32x2){cvt_pk_bf16(v1[0], v1[1]), cvt_pk_bf16(v1[2], v1[3])};
.LBB0_496:
	s_andn2_b64 vcc, exec, s[18:19]
	s_cbranch_vccnz .LBB0_498
	v_lshl_add_u64 v[20:21], s[8:9], 0, v[20:21]
	s_movk_i32 s12, 0xfc00
	v_lshl_add_u64 v[20:21], s[16:17], 1, v[20:21]
	s_mov_b32 s13, -1
	v_lshl_add_u64 v[10:11], s[0:1], 0, v[22:23]
	v_lshl_add_u64 v[20:21], v[20:21], 0, s[12:13]
	v_cndmask_b32_e64 v11, v21, v11, s[42:43]
	v_cndmask_b32_e64 v10, v20, v10, s[42:43]
	v_mov_b32_e32 v169, v1
	v_lshl_add_u64 v[20:21], v[10:11], 0, v[168:169]
	v_pk_mul_f32 v[12:13], v[8:9], s[74:75] op_sel_hi:[1,0]
	v_pk_mul_f32 v[14:15], v[6:7], s[74:75] op_sel_hi:[1,0]
	v_lshl_add_u64 v[10:11], v[20:21], 0, s[60:61]
	v_pk_mul_f32 v[16:17], v[4:5], s[74:75] op_sel_hi:[1,0]
	v_pk_mul_f32 v[24:25], v[2:3], s[74:75] op_sel_hi:[1,0]
	v_cvt_pk_bf16_f32 v14, v14, v15
	v_cvt_pk_bf16_f32 v15, v12, v13
	v_mov_b64_e32 v[216:217], v[14:15]
	v_cvt_pk_bf16_f32 v12, v24, v25
	v_cvt_pk_bf16_f32 v13, v16, v17

; __device__ __forceinline__ unsigned cvt_pk_bf16(float lo, float hi) { unsigned r; asm volatile("v_cvt_pk_bf16_f32 %0, %1, %2" : "=v"(r) : "v"(lo), "v"(hi)); return r; }
; __device__ __forceinline__ float gelu_tanh_f(float x) { const float y = 1.5957691216057308f * (x + 0.044715f * x * x * x); return x * __builtin_amdgcn_rcpf(1.f + __expf(-y)); }
;     __device__ __forceinline__ void operator()(const f32x4 (&acc)[2][2][4][2], const Unit& u, int wr, int wc, int fr, int fq) const {
;     ...
;                     if (pn <= 1) {
; #pragma unroll
;                         for (int i = 0; i < 4; ++i) { v0[i] = gelu_tanh_f(v0[i]); v1[i] = gelu_tanh_f(v1[i]); }
;                         bf16_t* p = UV + (size_t)r * 512 + pn * 256 + ctb;
;                         *(u32x2*)p = (u32x2){cvt_pk_bf16(v0[0], v0[1]), cvt_pk_bf16(v0[2], v0[3])}; *(u32x2*)(p + 16) = (u32x2){cvt_pk_bf16(v1[0], v1[1]), cvt_pk_bf16(v1[2], v1[3])};
.LBB0_500:
	v_mul_f32_e32 v26, 0x3d372713, v14
	v_mul_f32_e32 v26, v14, v26
	v_fma_f32 v26, v14, v26, v14
	v_mul_f32_e32 v26, 0xbfcc422a, v26
	v_mul_f32_e32 v26, 0x3fb8aa3b, v26
	v_exp_f32_e32 v26, v26
	v_mov_b32_e32 v169, v1
	v_add_f32_e32 v26, 1.0, v26
	v_rcp_f32_e32 v26, v26
	s_nop 0
	v_mul_f32_e32 v14, v14, v26
	v_mul_f32_e32 v26, 0x3d372713, v10
	v_mul_f32_e32 v26, v10, v26
	v_fma_f32 v26, v10, v26, v10
	v_mul_f32_e32 v26, 0xbfcc422a, v26
	v_mul_f32_e32 v26, 0x3fb8aa3b, v26
	v_exp_f32_e32 v26, v26
	s_nop 0
	v_add_f32_e32 v26, 1.0, v26
	v_rcp_f32_e32 v26, v26
	s_nop 0
	v_mul_f32_e32 v28, v10, v26
	v_mul_f32_e32 v10, 0x3d372713, v15
	v_mul_f32_e32 v10, v15, v10
	v_fma_f32 v10, v15, v10, v15
	v_mul_f32_e32 v10, 0xbfcc422a, v10
	v_mul_f32_e32 v10, 0x3fb8aa3b, v10
	v_exp_f32_e32 v10, v10
	v_lshl_add_u64 v[26:27], v[18:19], 0, v[168:169]
	v_add_f32_e32 v10, 1.0, v10
	v_rcp_f32_e32 v10, v10
	s_nop 0
	v_mul_f32_e32 v10, v15, v10
	v_mul_f32_e32 v15, 0x3d372713, v11
	v_mul_f32_e32 v15, v11, v15
	v_fma_f32 v15, v11, v15, v11
	v_mul_f32_e32 v15, 0xbfcc422a, v15
	v_mul_f32_e32 v15, 0x3fb8aa3b, v15
	v_exp_f32_e32 v15, v15
	v_cvt_pk_bf16_f32 v10, v14, v10
	s_nop 0
	v_add_f32_e32 v15, 1.0, v15
	v_rcp_f32_e32 v15, v15
	s_nop 0
	v_mul_f32_e32 v15, v11, v15
	v_mul_f32_e32 v11, 0x3d372713, v16
	v_mul_f32_e32 v11, v16, v11
	v_fma_f32 v11, v16, v11, v16
	v_mul_f32_e32 v11, 0xbfcc422a, v11
	v_mul_f32_e32 v11, 0x3fb8aa3b, v11
	v_exp_f32_e32 v11, v11
	s_nop 0
	v_add_f32_e32 v11, 1.0, v11
	v_rcp_f32_e32 v11, v11
	s_nop 0
	v_mul_f32_e32 v11, v16, v11
	v_mul_f32_e32 v16, 0x3d372713, v12
	v_mul_f32_e32 v16, v12, v16
	v_fma_f32 v16, v12, v16, v12
	v_mul_f32_e32 v16, 0xbfcc422a, v16
	v_mul_f32_e32 v16, 0x3fb8aa3b, v16
	v_exp_f32_e32 v16, v16
	s_nop 0
	v_add_f32_e32 v16, 1.0, v16
	v_rcp_f32_e32 v16, v16
	s_nop 0
	v_mul_f32_e32 v12, v12, v16
	v_mul_f32_e32 v16, 0x3d372713, v17
	v_mul_f32_e32 v16, v17, v16
	v_fma_f32 v16, v17, v16, v17
	v_mul_f32_e32 v16, 0xbfcc422a, v16
	v_mul_f32_e32 v16, 0x3fb8aa3b, v16
	v_exp_f32_e32 v16, v16
	s_nop 0
	v_add_f32_e32 v16, 1.0, v16
	v_rcp_f32_e32 v16, v16
	s_nop 0
	v_mul_f32_e32 v16, v17, v16
	v_mul_f32_e32 v17, 0x3d372713, v13
	v_mul_f32_e32 v17, v13, v17
	v_fma_f32 v17, v13, v17, v13
	v_mul_f32_e32 v17, 0xbfcc422a, v17
	v_mul_f32_e32 v17, 0x3fb8aa3b, v17
	v_exp_f32_e32 v17, v17
	v_cvt_pk_bf16_f32 v11, v11, v16
	v_mov_b64_e32 v[216:217], v[10:11]
	v_cvt_pk_bf16_f32 v28, v28, v15
	v_add_f32_e32 v17, 1.0, v17
	v_rcp_f32_e32 v17, v17
	s_nop 0
	v_mul_f32_e32 v13, v13, v17
	v_cvt_pk_bf16_f32 v29, v12, v13
	s_and_b64 vcc, exec, s[50:51]
	v_mov_b64_e32 v[218:219], v[28:29]
	s_nop 1
	v_permlane16_swap_b32_e32 v216, v218
	v_permlane16_swap_b32_e32 v217, v219
	v_lshl_add_u64 v[220:221], v[26:27], 0, v[222:223]
	flat_store_dwordx4 v[220:221], v[216:219]
	s_cbranch_vccnz .LBB0_485
	s_branch .LBB0_484

; __device__ __forceinline__ unsigned cvt_pk_bf16(float lo, float hi) { unsigned r; asm volatile("v_cvt_pk_bf16_f32 %0, %1, %2" : "=v"(r) : "v"(lo), "v"(hi)); return r; }
; __device__ __forceinline__ float gelu_tanh_f(float x) { const float y = 1.5957691216057308f * (x + 0.044715f * x * x * x); return x * __builtin_amdgcn_rcpf(1.f + __expf(-y)); }
; #define PG8_BAR __builtin_amdgcn_s_barrier()
;     __device__ __forceinline__ void operator()(const f32x4 (&acc)[2][2][4][2], const Unit& u, int wr, int wc, int fr, int fq) const {
;     ...
;                     if (pn <= 1) {
; #pragma unroll
;                         for (int i = 0; i < 4; ++i) { v0[i] = gelu_tanh_f(v0[i]); v1[i] = gelu_tanh_f(v1[i]); }
;                         bf16_t* p = UV + (size_t)r * 512 + pn * 256 + ctb;
;                         *(u32x2*)p = (u32x2){cvt_pk_bf16(v0[0], v0[1]), cvt_pk_bf16(v0[2], v0[3])}; *(u32x2*)(p + 16) = (u32x2){cvt_pk_bf16(v1[0], v1[1]), cvt_pk_bf16(v1[2], v1[3])};
; template <class Epi, class Sched, bool ALIGN_EPI = false, bool SP2 = false>
; __device__ __forceinline__ void gemm_phase(LAS unsigned char* lds, const Gemm g, const Sched& S, const Epi& E, const int tid) {
;     ...
;         if constexpr (!Epi::AFTER_DRAIN) { E(acc, cur, wr, wc, fr, fq); S.done(cur); }
;         if (!has_next) break;
; #pragma unroll
;         for (int a = 0; a < 2; ++a)
; #pragma unroll
;             for (int b = 0; b < 2; ++b)
; #pragma unroll
;                 for (int m = 0; m < 4; ++m)
; #pragma unroll
;                     for (int n = 0; n < 2; ++n) acc[a][b][m][n] = (f32x4){0.f, 0.f, 0.f, 0.f};
;         cur = nxt; cA = nA; cB = nB; ++ui;
;         if constexpr (ALIGN_EPI) { if (wr == 1) PG8_BAR; }
;     }
.LBB0_502:
	v_mul_f32_e32 v0, 0x3d372713, v6
	v_mul_f32_e32 v0, v6, v0
	v_fma_f32 v0, v6, v0, v6
	v_mul_f32_e32 v0, 0xbfcc422a, v0
	v_mul_f32_e32 v0, 0x3fb8aa3b, v0
	v_exp_f32_e32 v0, v0
	v_mov_b32_e32 v169, v1
	v_add_f32_e32 v0, 1.0, v0
	v_rcp_f32_e32 v0, v0
	s_nop 0
	v_mul_f32_e32 v0, v6, v0
	v_mul_f32_e32 v6, 0x3d372713, v2
	v_mul_f32_e32 v6, v2, v6
	v_fma_f32 v6, v2, v6, v2
	v_mul_f32_e32 v6, 0xbfcc422a, v6
	v_mul_f32_e32 v6, 0x3fb8aa3b, v6
	v_exp_f32_e32 v6, v6
	s_nop 0
	v_add_f32_e32 v6, 1.0, v6
	v_rcp_f32_e32 v6, v6
	s_nop 0
	v_mul_f32_e32 v6, v2, v6
	v_mul_f32_e32 v2, 0x3d372713, v7
	v_mul_f32_e32 v2, v7, v2
	v_fma_f32 v2, v7, v2, v7
	v_mul_f32_e32 v2, 0xbfcc422a, v2
	v_mul_f32_e32 v2, 0x3fb8aa3b, v2
	v_exp_f32_e32 v2, v2
	s_nop 0
	v_add_f32_e32 v2, 1.0, v2
	v_rcp_f32_e32 v2, v2
	s_nop 0
	v_mul_f32_e32 v7, v7, v2
	v_mul_f32_e32 v2, 0x3d372713, v3
	v_mul_f32_e32 v2, v3, v2
	v_fma_f32 v2, v3, v2, v3
	v_mul_f32_e32 v2, 0xbfcc422a, v2
	v_mul_f32_e32 v2, 0x3fb8aa3b, v2
	v_exp_f32_e32 v2, v2
	s_nop 0
	v_add_f32_e32 v2, 1.0, v2
	v_rcp_f32_e32 v2, v2
	s_nop 0
	v_mul_f32_e32 v12, v3, v2
	v_mul_f32_e32 v2, 0x3d372713, v8
	v_mul_f32_e32 v2, v8, v2
	v_fma_f32 v2, v8, v2, v8
	v_mul_f32_e32 v2, 0xbfcc422a, v2
	v_mul_f32_e32 v2, 0x3fb8aa3b, v2
	v_exp_f32_e32 v2, v2
	s_nop 0
	v_add_f32_e32 v2, 1.0, v2
	v_rcp_f32_e32 v2, v2
	s_nop 0
	v_mul_f32_e32 v8, v8, v2
	v_mul_f32_e32 v2, 0x3d372713, v4
	v_mul_f32_e32 v2, v4, v2
	v_fma_f32 v2, v4, v2, v4
	v_mul_f32_e32 v2, 0xbfcc422a, v2
	v_mul_f32_e32 v2, 0x3fb8aa3b, v2
	v_exp_f32_e32 v2, v2
	s_nop 0
	v_add_f32_e32 v2, 1.0, v2
	v_rcp_f32_e32 v2, v2
	s_nop 0
	v_mul_f32_e32 v13, v4, v2
	v_mul_f32_e32 v2, 0x3d372713, v9
	v_mul_f32_e32 v2, v9, v2
	v_fma_f32 v2, v9, v2, v9
	v_mul_f32_e32 v2, 0xbfcc422a, v2
	v_mul_f32_e32 v2, 0x3fb8aa3b, v2
	v_exp_f32_e32 v2, v2
	v_cvt_pk_bf16_f32 v4, v0, v7
	s_nop 0
	v_add_f32_e32 v2, 1.0, v2
	v_rcp_f32_e32 v2, v2
	s_nop 0
	v_mul_f32_e32 v9, v9, v2
	v_mul_f32_e32 v2, 0x3d372713, v5
	v_mul_f32_e32 v2, v5, v2
	v_fma_f32 v2, v5, v2, v5
	v_mul_f32_e32 v2, 0xbfcc422a, v2
	v_mul_f32_e32 v2, 0x3fb8aa3b, v2
	v_exp_f32_e32 v2, v2
	s_nop 0
	v_add_f32_e32 v2, 1.0, v2
	v_rcp_f32_e32 v2, v2
	s_nop 0
	v_mul_f32_e32 v14, v5, v2
	v_lshl_add_u64 v[2:3], v[18:19], 0, v[168:169]
	v_lshl_add_u64 v[10:11], v[2:3], 0, s[60:61]
	v_cvt_pk_bf16_f32 v5, v8, v9
	v_mov_b64_e32 v[216:217], v[4:5]
	v_cvt_pk_bf16_f32 v12, v6, v12
	v_cvt_pk_bf16_f32 v13, v13, v14
.LBB0_503:
	v_mov_b64_e32 v[218:219], v[12:13]
	s_nop 1
	v_permlane16_swap_b32_e32 v216, v218
	v_permlane16_swap_b32_e32 v217, v219
	v_lshl_add_u64 v[220:221], v[10:11], 0, v[222:223]
	flat_store_dwordx4 v[220:221], v[216:219]
	v_readlane_b32 s60, v254, 41
	s_andn2_b64 vcc, exec, s[40:41]
	s_mov_b64 s[12:13], -1
	v_readlane_b32 s61, v254, 42
	s_cbranch_vccnz .LBB0_190
	v_readlane_b32 s12, v255, 8
	v_readlane_b32 s13, v255, 9
	s_andn2_b64 vcc, exec, s[12:13]
	s_cbranch_vccnz .LBB0_189
	s_barrier
	s_branch .LBB0_189
